# dead-instruction removal: 528 zero-init v_mov before full-lane row_ror DPP writes (G3a conv epilogue) and 73 no-op lgkmcnt(0) waits in the S2 loop; on top of v73
# speedup vs baseline: 1.0059x; 1.0005x over previous
;     template <int QVV> __device__ __forceinline__ void run(f32x4 (&acc)[2][2][4][2], const Unit& u, int wr, int wc, int fr, int fq) const {
;     ...
;                         for (int m = 0; m < 4; ++m) X[m] = acc[ai][bj][m][n] * rs[ai][m] + sh[n];
;                         if (fr <= 2) *(u32x2*)(tb + lo + (unsigned)(ai * HALF) * rs_ + bj * HALF * 2 + n * 8) = (u32x2){pk2(X[0][0], X[0][1]), pk2(X[0][2], X[0][3])};
;                         if (fr >= 13) *(u32x2*)(tb + lo + (unsigned)(ai * HALF + 48) * rs_ + bj * HALF * 2 + n * 8) = (u32x2){pk2(X[3][0], X[3][1]), pk2(X[3][2], X[3][3])};
; #pragma unroll
;                         for (int m = 0; m < 4; ++m) {
;                             const int mp = m > 0 ? m - 1 : 0, mn = m < 3 ? m + 1 : 3;
;                             f32x4 o;
; #pragma unroll
;                             for (int i = 0; i < 4; ++i) {
;                                 const float xif = X[m][i], xpf = X[mp][i], xnf = X[mn][i];
;                                 const int xi = __float_as_int(xif), xp = __float_as_int(xpf), xn = __float_as_int(xnf);
;                                 const float p1 = __builtin_bit_cast(float, __builtin_amdgcn_update_dpp(__builtin_amdgcn_update_dpp(0, xp, 0x121, 0xf, 0xf, false), xi, 0x111, 0xf, 0xf, false));
;                                 const float p2 = __builtin_bit_cast(float, __builtin_amdgcn_update_dpp(__builtin_amdgcn_update_dpp(0, xp, 0x122, 0xf, 0xf, false), xi, 0x112, 0xf, 0xf, false));
;                                 const float n1 = __builtin_bit_cast(float, __builtin_amdgcn_update_dpp(__builtin_amdgcn_update_dpp(0, xn, 0x12f, 0xf, 0xf, false), xi, 0x101, 0xf, 0xf, false));
;                                 o[i] = bb[i] + w0[i] * p2 + w1[i] * p1 + w2[i] * X[m][i] + w3[i] * n1; }
;                             const int r = r0 + wr * 64 + fr + ai * HALF + m * 16;
;                             const bool edge = (m == 0 && fr < 2) || (m == 3 && fr == 15);
;                             if (!edge) *(u32x2*)(XA + (size_t)r * 1024 + c0 + bj * HALF + 4 * n) = (u32x2){pk2(o[0], o[1]), pk2(o[2], o[3])}; }
.LBB0_473:
	s_or_b64 exec, exec, s[30:31]
	v_pk_fma_f32 v[120:121], v[120:121], v[188:189], v[136:137] op_sel_hi:[1,0,1]
	v_pk_fma_f32 v[118:119], v[118:119], v[188:189], v[134:135] op_sel_hi:[1,0,1]
	v_mov_b32_dpp v128, v166 row_ror:1 row_mask:0xf bank_mask:0xf
	v_mov_b32_dpp v198, v166 row_ror:2 row_mask:0xf bank_mask:0xf
	v_mov_b32_dpp v204, v118 row_ror:15 row_mask:0xf bank_mask:0xf
	v_mov_b32_dpp v129, v167 row_ror:1 row_mask:0xf bank_mask:0xf
	v_mov_b32_dpp v199, v167 row_ror:2 row_mask:0xf bank_mask:0xf
	v_mov_b32_dpp v205, v119 row_ror:15 row_mask:0xf bank_mask:0xf
	v_mov_b32_dpp v200, v126 row_ror:1 row_mask:0xf bank_mask:0xf
	v_mov_b32_dpp v206, v126 row_ror:2 row_mask:0xf bank_mask:0xf
	v_mov_b32_dpp v208, v120 row_ror:15 row_mask:0xf bank_mask:0xf
	v_mov_b32_dpp v201, v127 row_ror:1 row_mask:0xf bank_mask:0xf
	v_mov_b32_dpp v207, v127 row_ror:2 row_mask:0xf bank_mask:0xf
	v_mov_b32_dpp v209, v121 row_ror:15 row_mask:0xf bank_mask:0xf
	v_lshlrev_b64 v[180:181], 11, v[196:197]
	v_mov_b32_dpp v128, v166 row_shr:1 row_mask:0xf bank_mask:0xf
	v_mov_b32_dpp v198, v166 row_shr:2 row_mask:0xf bank_mask:0xf
	v_mov_b32_dpp v204, v166 row_shl:1 row_mask:0xf bank_mask:0xf
	v_mov_b32_dpp v129, v167 row_shr:1 row_mask:0xf bank_mask:0xf
	v_mov_b32_dpp v199, v167 row_shr:2 row_mask:0xf bank_mask:0xf
	v_mov_b32_dpp v205, v167 row_shl:1 row_mask:0xf bank_mask:0xf
	v_mov_b32_dpp v200, v126 row_shr:1 row_mask:0xf bank_mask:0xf
	v_mov_b32_dpp v206, v126 row_shr:2 row_mask:0xf bank_mask:0xf
	v_mov_b32_dpp v208, v126 row_shl:1 row_mask:0xf bank_mask:0xf
	v_mov_b32_dpp v201, v127 row_shr:1 row_mask:0xf bank_mask:0xf
	v_mov_b32_dpp v207, v127 row_shr:2 row_mask:0xf bank_mask:0xf
	v_mov_b32_dpp v209, v127 row_shl:1 row_mask:0xf bank_mask:0xf
	v_lshl_add_u64 v[202:203], s[34:35], 0, v[180:181]
	s_and_saveexec_b64 s[2:3], s[44:45]
	s_xor_b64 s[30:31], exec, s[2:3]
	s_cbranch_execz .LBB0_475
	s_waitcnt vmcnt(0)
	v_pk_fma_f32 v[180:181], v[138:139], v[198:199], v[154:155]
	s_nop 0
	v_pk_fma_f32 v[128:129], v[142:143], v[128:129], v[180:181]
	v_pk_fma_f32 v[180:181], v[140:141], v[206:207], v[156:157]
	v_pk_fma_f32 v[128:129], v[166:167], v[146:147], v[128:129]
	v_pk_fma_f32 v[180:181], v[144:145], v[200:201], v[180:181]
	v_pk_fma_f32 v[128:129], v[150:151], v[204:205], v[128:129]
	v_pk_fma_f32 v[180:181], v[126:127], v[148:149], v[180:181]
	v_cvt_pk_bf16_f32 v128, v128, v129
	v_pk_fma_f32 v[180:181], v[152:153], v[208:209], v[180:181]
	s_nop 0
	v_cvt_pk_bf16_f32 v129, v180, v181
	v_lshl_add_u64 v[180:181], v[158:159], 1, v[202:203]
	global_store_dwordx2 v[180:181], v[128:129], off
.LBB0_475:
	s_andn2_saveexec_b64 s[30:31], s[30:31]
	s_or_b64 exec, exec, s[30:31]
	v_pk_fma_f32 v[180:181], v[116:117], v[186:187], v[136:137] op_sel_hi:[1,0,1]
	v_pk_fma_f32 v[128:129], v[114:115], v[186:187], v[134:135] op_sel_hi:[1,0,1]
	v_mov_b32_dpp v116, v166 row_ror:2 row_mask:0xf bank_mask:0xf
	v_mov_b32_dpp v117, v167 row_ror:2 row_mask:0xf bank_mask:0xf
	v_mov_b32_dpp v114, v166 row_ror:1 row_mask:0xf bank_mask:0xf
	v_mov_b32_dpp v116, v118 row_shr:2 row_mask:0xf bank_mask:0xf
	v_mov_b32_dpp v115, v167 row_ror:1 row_mask:0xf bank_mask:0xf
	v_mov_b32_dpp v117, v119 row_shr:2 row_mask:0xf bank_mask:0xf
	v_mov_b32_dpp v200, v126 row_ror:2 row_mask:0xf bank_mask:0xf
	v_mov_b32_dpp v201, v127 row_ror:2 row_mask:0xf bank_mask:0xf
	v_mov_b32_dpp v114, v118 row_shr:1 row_mask:0xf bank_mask:0xf
	v_mov_b32_dpp v115, v119 row_shr:1 row_mask:0xf bank_mask:0xf
	v_mov_b32_dpp v198, v126 row_ror:1 row_mask:0xf bank_mask:0xf
	v_mov_b32_dpp v200, v120 row_shr:2 row_mask:0xf bank_mask:0xf
	v_mov_b32_dpp v199, v127 row_ror:1 row_mask:0xf bank_mask:0xf
	v_mov_b32_dpp v201, v121 row_shr:2 row_mask:0xf bank_mask:0xf
	s_waitcnt vmcnt(0)
;     template <int QVV> __device__ __forceinline__ void run(f32x4 (&acc)[2][2][4][2], const Unit& u, int wr, int wc, int fr, int fq) const {
;     ...
;                         for (int m = 0; m < 4; ++m) X[m] = acc[ai][bj][m][n] * rs[ai][m] + sh[n];
;                         if (fr <= 2) *(u32x2*)(tb + lo + (unsigned)(ai * HALF) * rs_ + bj * HALF * 2 + n * 8) = (u32x2){pk2(X[0][0], X[0][1]), pk2(X[0][2], X[0][3])};
;                         if (fr >= 13) *(u32x2*)(tb + lo + (unsigned)(ai * HALF + 48) * rs_ + bj * HALF * 2 + n * 8) = (u32x2){pk2(X[3][0], X[3][1]), pk2(X[3][2], X[3][3])};
; #pragma unroll
;                         for (int m = 0; m < 4; ++m) {
;                             const int mp = m > 0 ? m - 1 : 0, mn = m < 3 ? m + 1 : 3;
;                             f32x4 o;
; #pragma unroll
;                             for (int i = 0; i < 4; ++i) {
;                                 const float xif = X[m][i], xpf = X[mp][i], xnf = X[mn][i];
;                                 const int xi = __float_as_int(xif), xp = __float_as_int(xpf), xn = __float_as_int(xnf);
;                                 const float p1 = __builtin_bit_cast(float, __builtin_amdgcn_update_dpp(__builtin_amdgcn_update_dpp(0, xp, 0x121, 0xf, 0xf, false), xi, 0x111, 0xf, 0xf, false));
;                                 const float p2 = __builtin_bit_cast(float, __builtin_amdgcn_update_dpp(__builtin_amdgcn_update_dpp(0, xp, 0x122, 0xf, 0xf, false), xi, 0x112, 0xf, 0xf, false));
;                                 const float n1 = __builtin_bit_cast(float, __builtin_amdgcn_update_dpp(__builtin_amdgcn_update_dpp(0, xn, 0x12f, 0xf, 0xf, false), xi, 0x101, 0xf, 0xf, false));
;                                 o[i] = bb[i] + w0[i] * p2 + w1[i] * p1 + w2[i] * X[m][i] + w3[i] * n1; }
;                             const int r = r0 + wr * 64 + fr + ai * HALF + m * 16;
;                             const bool edge = (m == 0 && fr < 2) || (m == 3 && fr == 15);
;                             if (!edge) *(u32x2*)(XA + (size_t)r * 1024 + c0 + bj * HALF + 4 * n) = (u32x2){pk2(o[0], o[1]), pk2(o[2], o[3])}; }
	v_pk_fma_f32 v[116:117], v[138:139], v[116:117], v[154:155]
	v_mov_b32_dpp v198, v120 row_shr:1 row_mask:0xf bank_mask:0xf
	v_mov_b32_dpp v199, v121 row_shr:1 row_mask:0xf bank_mask:0xf
	v_pk_fma_f32 v[114:115], v[142:143], v[114:115], v[116:117]
	v_pk_fma_f32 v[116:117], v[140:141], v[200:201], v[156:157]
	v_mov_b32_dpp v126, v180 row_ror:15 row_mask:0xf bank_mask:0xf
	v_mov_b32_dpp v127, v181 row_ror:15 row_mask:0xf bank_mask:0xf
	v_pk_fma_f32 v[116:117], v[144:145], v[198:199], v[116:117]
	v_mov_b32_dpp v166, v128 row_ror:15 row_mask:0xf bank_mask:0xf
	v_mov_b32_dpp v167, v129 row_ror:15 row_mask:0xf bank_mask:0xf
	v_mov_b32_dpp v126, v120 row_shl:1 row_mask:0xf bank_mask:0xf
	v_mov_b32_dpp v127, v121 row_shl:1 row_mask:0xf bank_mask:0xf
	v_pk_fma_f32 v[116:117], v[120:121], v[148:149], v[116:117]
	v_mov_b32_dpp v166, v118 row_shl:1 row_mask:0xf bank_mask:0xf
	v_mov_b32_dpp v167, v119 row_shl:1 row_mask:0xf bank_mask:0xf
	v_pk_fma_f32 v[114:115], v[118:119], v[146:147], v[114:115]
	v_pk_fma_f32 v[116:117], v[152:153], v[126:127], v[116:117]
	v_or_b32_e32 v126, 16, v196
	v_pk_fma_f32 v[114:115], v[150:151], v[166:167], v[114:115]
	v_ashrrev_i32_e32 v127, 31, v126
	v_cvt_pk_bf16_f32 v114, v114, v115
	v_cvt_pk_bf16_f32 v115, v116, v117
	v_lshlrev_b64 v[116:117], 11, v[126:127]
	v_lshl_add_u64 v[116:117], s[34:35], 0, v[116:117]
	v_lshlrev_b64 v[126:127], 1, v[158:159]
	v_lshl_add_u64 v[198:199], v[116:117], 0, v[126:127]
	v_mov_b32_dpp v200, v118 row_ror:2 row_mask:0xf bank_mask:0xf
	v_mov_b32_dpp v201, v119 row_ror:2 row_mask:0xf bank_mask:0xf
	global_store_dwordx2 v[198:199], v[114:115], off
	v_mov_b32_dpp v166, v118 row_ror:1 row_mask:0xf bank_mask:0xf
	v_mov_b32_dpp v200, v128 row_shr:2 row_mask:0xf bank_mask:0xf
	v_mov_b32_dpp v167, v119 row_ror:1 row_mask:0xf bank_mask:0xf
	v_mov_b32_dpp v201, v129 row_shr:2 row_mask:0xf bank_mask:0xf
	v_mov_b32_dpp v166, v128 row_shr:1 row_mask:0xf bank_mask:0xf
	v_mov_b32_dpp v114, v122 row_ror:15 row_mask:0xf bank_mask:0xf
	v_mov_b32_dpp v167, v129 row_shr:1 row_mask:0xf bank_mask:0xf
	v_mov_b32_dpp v115, v123 row_ror:15 row_mask:0xf bank_mask:0xf
	v_pk_fma_f32 v[200:201], v[138:139], v[200:201], v[154:155]
	v_mov_b32_e32 v118, v114
	v_mov_b32_e32 v119, v115
	v_mov_b32_dpp v206, v120 row_ror:2 row_mask:0xf bank_mask:0xf
	v_mov_b32_dpp v207, v121 row_ror:2 row_mask:0xf bank_mask:0xf
	v_pk_fma_f32 v[166:167], v[142:143], v[166:167], v[200:201]
	v_mov_b32_dpp v118, v128 row_shl:1 row_mask:0xf bank_mask:0xf
	v_mov_b32_dpp v119, v129 row_shl:1 row_mask:0xf bank_mask:0xf
	v_mov_b32_dpp v204, v120 row_ror:1 row_mask:0xf bank_mask:0xf
	v_mov_b32_dpp v206, v180 row_shr:2 row_mask:0xf bank_mask:0xf
	v_mov_b32_dpp v205, v121 row_ror:1 row_mask:0xf bank_mask:0xf
	v_mov_b32_dpp v207, v181 row_shr:2 row_mask:0xf bank_mask:0xf
	v_pk_fma_f32 v[166:167], v[128:129], v[146:147], v[166:167]
	v_mov_b32_dpp v204, v180 row_shr:1 row_mask:0xf bank_mask:0xf
	v_mov_b32_dpp v116, v124 row_ror:15 row_mask:0xf bank_mask:0xf
	v_mov_b32_dpp v205, v181 row_shr:1 row_mask:0xf bank_mask:0xf
	v_mov_b32_dpp v117, v125 row_ror:15 row_mask:0xf bank_mask:0xf
	v_pk_fma_f32 v[118:119], v[150:151], v[118:119], v[166:167]
	v_pk_fma_f32 v[166:167], v[140:141], v[206:207], v[156:157]
	v_mov_b32_e32 v120, v116
	v_mov_b32_e32 v121, v117
	v_pk_fma_f32 v[166:167], v[144:145], v[204:205], v[166:167]
	v_mov_b32_dpp v120, v180 row_shl:1 row_mask:0xf bank_mask:0xf
	v_mov_b32_dpp v121, v181 row_shl:1 row_mask:0xf bank_mask:0xf
	v_pk_fma_f32 v[166:167], v[180:181], v[148:149], v[166:167]
	v_cvt_pk_bf16_f32 v118, v118, v119
	v_pk_fma_f32 v[120:121], v[152:153], v[120:121], v[166:167]
	v_or_b32_e32 v166, 32, v196
	v_ashrrev_i32_e32 v167, 31, v166
	v_cvt_pk_bf16_f32 v119, v120, v121
	v_lshlrev_b64 v[120:121], 11, v[166:167]
	v_lshl_add_u64 v[120:121], s[34:35], 0, v[120:121]
	v_lshl_add_u64 v[200:201], v[120:121], 0, v[126:127]
	global_store_dwordx2 v[200:201], v[118:119], off
	v_mov_b32_dpp v118, v128 row_ror:1 row_mask:0xf bank_mask:0xf
	v_mov_b32_dpp v120, v128 row_ror:2 row_mask:0xf bank_mask:0xf
	v_mov_b32_dpp v119, v129 row_ror:1 row_mask:0xf bank_mask:0xf
	v_mov_b32_dpp v121, v129 row_ror:2 row_mask:0xf bank_mask:0xf
	v_mov_b32_dpp v126, v180 row_ror:1 row_mask:0xf bank_mask:0xf
	v_mov_b32_dpp v128, v180 row_ror:2 row_mask:0xf bank_mask:0xf
	v_mov_b32_dpp v127, v181 row_ror:1 row_mask:0xf bank_mask:0xf
	v_mov_b32_dpp v129, v181 row_ror:2 row_mask:0xf bank_mask:0xf
	v_mov_b32_dpp v118, v122 row_shr:1 row_mask:0xf bank_mask:0xf
	v_mov_b32_dpp v120, v122 row_shr:2 row_mask:0xf bank_mask:0xf
	v_mov_b32_dpp v114, v122 row_shl:1 row_mask:0xf bank_mask:0xf
	v_mov_b32_dpp v119, v123 row_shr:1 row_mask:0xf bank_mask:0xf
	v_mov_b32_dpp v121, v123 row_shr:2 row_mask:0xf bank_mask:0xf
	v_mov_b32_dpp v115, v123 row_shl:1 row_mask:0xf bank_mask:0xf
	v_mov_b32_dpp v126, v124 row_shr:1 row_mask:0xf bank_mask:0xf
	v_mov_b32_dpp v128, v124 row_shr:2 row_mask:0xf bank_mask:0xf
	v_mov_b32_dpp v116, v124 row_shl:1 row_mask:0xf bank_mask:0xf
	v_mov_b32_dpp v127, v125 row_shr:1 row_mask:0xf bank_mask:0xf
	v_mov_b32_dpp v129, v125 row_shr:2 row_mask:0xf bank_mask:0xf
	v_mov_b32_dpp v117, v125 row_shl:1 row_mask:0xf bank_mask:0xf
	v_or_b32_e32 v166, 48, v196
	s_and_saveexec_b64 s[30:31], s[46:47]
	s_cbranch_execz .LBB0_477
	v_pk_fma_f32 v[120:121], v[138:139], v[120:121], v[154:155]
	v_ashrrev_i32_e32 v167, 31, v166
	v_pk_fma_f32 v[118:119], v[142:143], v[118:119], v[120:121]
	s_nop 0
	v_pk_fma_f32 v[118:119], v[122:123], v[146:147], v[118:119]
	s_nop 0
	v_pk_fma_f32 v[114:115], v[150:151], v[114:115], v[118:119]
	v_pk_fma_f32 v[118:119], v[140:141], v[128:129], v[156:157]
	v_cvt_pk_bf16_f32 v114, v114, v115
	v_pk_fma_f32 v[118:119], v[144:145], v[126:127], v[118:119]
	s_nop 0
	v_pk_fma_f32 v[118:119], v[124:125], v[148:149], v[118:119]
	s_nop 0
	v_pk_fma_f32 v[116:117], v[152:153], v[116:117], v[118:119]
	s_nop 0
	v_cvt_pk_bf16_f32 v115, v116, v117
	v_lshlrev_b64 v[116:117], 11, v[166:167]
	v_lshl_add_u64 v[116:117], s[34:35], 0, v[116:117]
	v_lshl_add_u64 v[116:117], v[158:159], 1, v[116:117]
	global_store_dwordx2 v[116:117], v[114:115], off

;     template <int QVV> __device__ __forceinline__ void run(f32x4 (&acc)[2][2][4][2], const Unit& u, int wr, int wc, int fr, int fq) const {
;     ...
;                         for (int m = 0; m < 4; ++m) X[m] = acc[ai][bj][m][n] * rs[ai][m] + sh[n];
;                         if (fr <= 2) *(u32x2*)(tb + lo + (unsigned)(ai * HALF) * rs_ + bj * HALF * 2 + n * 8) = (u32x2){pk2(X[0][0], X[0][1]), pk2(X[0][2], X[0][3])};
;                         if (fr >= 13) *(u32x2*)(tb + lo + (unsigned)(ai * HALF + 48) * rs_ + bj * HALF * 2 + n * 8) = (u32x2){pk2(X[3][0], X[3][1]), pk2(X[3][2], X[3][3])};
; #pragma unroll
;                         for (int m = 0; m < 4; ++m) {
;                             const int mp = m > 0 ? m - 1 : 0, mn = m < 3 ? m + 1 : 3;
;                             f32x4 o;
; #pragma unroll
;                             for (int i = 0; i < 4; ++i) {
;                                 const float xif = X[m][i], xpf = X[mp][i], xnf = X[mn][i];
;                                 const int xi = __float_as_int(xif), xp = __float_as_int(xpf), xn = __float_as_int(xnf);
;                                 const float p1 = __builtin_bit_cast(float, __builtin_amdgcn_update_dpp(__builtin_amdgcn_update_dpp(0, xp, 0x121, 0xf, 0xf, false), xi, 0x111, 0xf, 0xf, false));
;                                 const float p2 = __builtin_bit_cast(float, __builtin_amdgcn_update_dpp(__builtin_amdgcn_update_dpp(0, xp, 0x122, 0xf, 0xf, false), xi, 0x112, 0xf, 0xf, false));
;                                 const float n1 = __builtin_bit_cast(float, __builtin_amdgcn_update_dpp(__builtin_amdgcn_update_dpp(0, xn, 0x12f, 0xf, 0xf, false), xi, 0x101, 0xf, 0xf, false));
;                                 o[i] = bb[i] + w0[i] * p2 + w1[i] * p1 + w2[i] * X[m][i] + w3[i] * n1; }
;                             const int r = r0 + wr * 64 + fr + ai * HALF + m * 16;
;                             const bool edge = (m == 0 && fr < 2) || (m == 3 && fr == 15);
;                             if (!edge) *(u32x2*)(XA + (size_t)r * 1024 + c0 + bj * HALF + 4 * n) = (u32x2){pk2(o[0], o[1]), pk2(o[2], o[3])}; }
.LBB0_481:
	s_or_b64 exec, exec, s[30:31]
	v_mov_b32_e32 v189, v188
	v_mov_b32_e32 v142, v188
	v_mov_b32_e32 v143, v188
	v_pk_fma_f32 v[104:105], v[104:105], v[142:143], v[132:133]
	v_pk_fma_f32 v[102:103], v[102:103], v[188:189], v[130:131]
	v_mov_b32_dpp v142, v110 row_ror:1 row_mask:0xf bank_mask:0xf
	v_mov_b32_dpp v144, v110 row_ror:2 row_mask:0xf bank_mask:0xf
	v_mov_b32_dpp v148, v102 row_ror:15 row_mask:0xf bank_mask:0xf
	v_mov_b32_dpp v143, v111 row_ror:1 row_mask:0xf bank_mask:0xf
	v_mov_b32_dpp v145, v111 row_ror:2 row_mask:0xf bank_mask:0xf
	v_mov_b32_dpp v149, v103 row_ror:15 row_mask:0xf bank_mask:0xf
	v_mov_b32_dpp v146, v112 row_ror:1 row_mask:0xf bank_mask:0xf
	v_mov_b32_dpp v150, v112 row_ror:2 row_mask:0xf bank_mask:0xf
	v_mov_b32_dpp v152, v104 row_ror:15 row_mask:0xf bank_mask:0xf
	v_mov_b32_dpp v147, v113 row_ror:1 row_mask:0xf bank_mask:0xf
	v_mov_b32_dpp v151, v113 row_ror:2 row_mask:0xf bank_mask:0xf
	v_mov_b32_dpp v153, v105 row_ror:15 row_mask:0xf bank_mask:0xf
	v_mov_b32_dpp v142, v110 row_shr:1 row_mask:0xf bank_mask:0xf
	v_mov_b32_dpp v144, v110 row_shr:2 row_mask:0xf bank_mask:0xf
	v_mov_b32_dpp v148, v110 row_shl:1 row_mask:0xf bank_mask:0xf
	v_mov_b32_dpp v143, v111 row_shr:1 row_mask:0xf bank_mask:0xf
	v_mov_b32_dpp v145, v111 row_shr:2 row_mask:0xf bank_mask:0xf
	v_mov_b32_dpp v149, v111 row_shl:1 row_mask:0xf bank_mask:0xf
	v_mov_b32_dpp v146, v112 row_shr:1 row_mask:0xf bank_mask:0xf
	v_mov_b32_dpp v150, v112 row_shr:2 row_mask:0xf bank_mask:0xf
	v_mov_b32_dpp v152, v112 row_shl:1 row_mask:0xf bank_mask:0xf
	v_mov_b32_dpp v147, v113 row_shr:1 row_mask:0xf bank_mask:0xf
	v_mov_b32_dpp v151, v113 row_shr:2 row_mask:0xf bank_mask:0xf
	v_mov_b32_dpp v153, v113 row_shl:1 row_mask:0xf bank_mask:0xf
	s_and_saveexec_b64 s[2:3], s[44:45]
	s_xor_b64 s[30:31], exec, s[2:3]
	s_cbranch_execz .LBB0_483
	s_waitcnt vmcnt(0)
	v_pk_fma_f32 v[144:145], v[114:115], v[144:145], v[138:139]
	s_nop 0
	v_pk_fma_f32 v[142:143], v[118:119], v[142:143], v[144:145]
	v_pk_fma_f32 v[144:145], v[116:117], v[150:151], v[140:141]
	v_pk_fma_f32 v[142:143], v[110:111], v[122:123], v[142:143]
	v_pk_fma_f32 v[144:145], v[120:121], v[146:147], v[144:145]
	v_pk_fma_f32 v[142:143], v[126:127], v[148:149], v[142:143]
	v_pk_fma_f32 v[144:145], v[112:113], v[124:125], v[144:145]
	v_cvt_pk_bf16_f32 v142, v142, v143
	v_pk_fma_f32 v[144:145], v[128:129], v[152:153], v[144:145]
	s_nop 0
	v_cvt_pk_bf16_f32 v143, v144, v145
	v_lshl_add_u64 v[144:145], v[158:159], 1, v[202:203]
	global_store_dwordx2 v[144:145], v[142:143], off offset:8
;     template <int QVV> __device__ __forceinline__ void run(f32x4 (&acc)[2][2][4][2], const Unit& u, int wr, int wc, int fr, int fq) const {
;     ...
;                         for (int m = 0; m < 4; ++m) X[m] = acc[ai][bj][m][n] * rs[ai][m] + sh[n];
;                         if (fr <= 2) *(u32x2*)(tb + lo + (unsigned)(ai * HALF) * rs_ + bj * HALF * 2 + n * 8) = (u32x2){pk2(X[0][0], X[0][1]), pk2(X[0][2], X[0][3])};
;                         if (fr >= 13) *(u32x2*)(tb + lo + (unsigned)(ai * HALF + 48) * rs_ + bj * HALF * 2 + n * 8) = (u32x2){pk2(X[3][0], X[3][1]), pk2(X[3][2], X[3][3])};
; #pragma unroll
;                         for (int m = 0; m < 4; ++m) {
;                             const int mp = m > 0 ? m - 1 : 0, mn = m < 3 ? m + 1 : 3;
;                             f32x4 o;
; #pragma unroll
;                             for (int i = 0; i < 4; ++i) {
;                                 const float xif = X[m][i], xpf = X[mp][i], xnf = X[mn][i];
;                                 const int xi = __float_as_int(xif), xp = __float_as_int(xpf), xn = __float_as_int(xnf);
;                                 const float p1 = __builtin_bit_cast(float, __builtin_amdgcn_update_dpp(__builtin_amdgcn_update_dpp(0, xp, 0x121, 0xf, 0xf, false), xi, 0x111, 0xf, 0xf, false));
;                                 const float p2 = __builtin_bit_cast(float, __builtin_amdgcn_update_dpp(__builtin_amdgcn_update_dpp(0, xp, 0x122, 0xf, 0xf, false), xi, 0x112, 0xf, 0xf, false));
;                                 const float n1 = __builtin_bit_cast(float, __builtin_amdgcn_update_dpp(__builtin_amdgcn_update_dpp(0, xn, 0x12f, 0xf, 0xf, false), xi, 0x101, 0xf, 0xf, false));
;                                 o[i] = bb[i] + w0[i] * p2 + w1[i] * p1 + w2[i] * X[m][i] + w3[i] * n1; }
;                             const int r = r0 + wr * 64 + fr + ai * HALF + m * 16;
;                             const bool edge = (m == 0 && fr < 2) || (m == 3 && fr == 15);
;                             if (!edge) *(u32x2*)(XA + (size_t)r * 1024 + c0 + bj * HALF + 4 * n) = (u32x2){pk2(o[0], o[1]), pk2(o[2], o[3])}; }
.LBB0_483:
	s_andn2_saveexec_b64 s[30:31], s[30:31]
	s_or_b64 exec, exec, s[30:31]
	v_mov_b32_e32 v142, v186
	v_mov_b32_e32 v143, v186
	v_mov_b32_e32 v187, v186
	v_pk_fma_f32 v[142:143], v[100:101], v[142:143], v[132:133]
	v_pk_fma_f32 v[144:145], v[98:99], v[186:187], v[130:131]
	v_mov_b32_dpp v100, v110 row_ror:2 row_mask:0xf bank_mask:0xf
	v_mov_b32_dpp v101, v111 row_ror:2 row_mask:0xf bank_mask:0xf
	v_mov_b32_dpp v98, v110 row_ror:1 row_mask:0xf bank_mask:0xf
	v_mov_b32_dpp v100, v102 row_shr:2 row_mask:0xf bank_mask:0xf
	v_mov_b32_dpp v99, v111 row_ror:1 row_mask:0xf bank_mask:0xf
	v_mov_b32_dpp v101, v103 row_shr:2 row_mask:0xf bank_mask:0xf
	v_mov_b32_dpp v148, v112 row_ror:2 row_mask:0xf bank_mask:0xf
	v_mov_b32_dpp v149, v113 row_ror:2 row_mask:0xf bank_mask:0xf
	v_mov_b32_dpp v98, v102 row_shr:1 row_mask:0xf bank_mask:0xf
	v_mov_b32_dpp v99, v103 row_shr:1 row_mask:0xf bank_mask:0xf
	v_mov_b32_dpp v146, v112 row_ror:1 row_mask:0xf bank_mask:0xf
	v_mov_b32_dpp v148, v104 row_shr:2 row_mask:0xf bank_mask:0xf
	v_mov_b32_dpp v147, v113 row_ror:1 row_mask:0xf bank_mask:0xf
	v_mov_b32_dpp v149, v105 row_shr:2 row_mask:0xf bank_mask:0xf
	s_waitcnt vmcnt(0)
	v_pk_fma_f32 v[100:101], v[114:115], v[100:101], v[138:139]
	v_mov_b32_dpp v146, v104 row_shr:1 row_mask:0xf bank_mask:0xf
	v_mov_b32_dpp v147, v105 row_shr:1 row_mask:0xf bank_mask:0xf
	v_pk_fma_f32 v[98:99], v[118:119], v[98:99], v[100:101]
	v_pk_fma_f32 v[100:101], v[116:117], v[148:149], v[140:141]
	v_mov_b32_dpp v110, v144 row_ror:15 row_mask:0xf bank_mask:0xf
	v_mov_b32_dpp v111, v145 row_ror:15 row_mask:0xf bank_mask:0xf
	v_mov_b32_dpp v112, v142 row_ror:15 row_mask:0xf bank_mask:0xf
	v_mov_b32_dpp v113, v143 row_ror:15 row_mask:0xf bank_mask:0xf
	v_pk_fma_f32 v[100:101], v[120:121], v[146:147], v[100:101]
	v_mov_b32_dpp v110, v102 row_shl:1 row_mask:0xf bank_mask:0xf
	v_mov_b32_dpp v111, v103 row_shl:1 row_mask:0xf bank_mask:0xf
	v_mov_b32_dpp v112, v104 row_shl:1 row_mask:0xf bank_mask:0xf
	v_mov_b32_dpp v113, v105 row_shl:1 row_mask:0xf bank_mask:0xf
	v_pk_fma_f32 v[98:99], v[102:103], v[122:123], v[98:99]
	v_pk_fma_f32 v[100:101], v[104:105], v[124:125], v[100:101]
	v_pk_fma_f32 v[98:99], v[126:127], v[110:111], v[98:99]
	v_pk_fma_f32 v[100:101], v[128:129], v[112:113], v[100:101]
	v_cvt_pk_bf16_f32 v98, v98, v99
	v_cvt_pk_bf16_f32 v99, v100, v101
	v_mov_b32_dpp v112, v102 row_ror:2 row_mask:0xf bank_mask:0xf
	v_mov_b32_dpp v113, v103 row_ror:2 row_mask:0xf bank_mask:0xf
	global_store_dwordx2 v[198:199], v[98:99], off offset:8
	v_mov_b32_dpp v110, v102 row_ror:1 row_mask:0xf bank_mask:0xf
	v_mov_b32_dpp v112, v144 row_shr:2 row_mask:0xf bank_mask:0xf
	v_mov_b32_dpp v111, v103 row_ror:1 row_mask:0xf bank_mask:0xf
	v_mov_b32_dpp v113, v145 row_shr:2 row_mask:0xf bank_mask:0xf
	v_mov_b32_dpp v110, v144 row_shr:1 row_mask:0xf bank_mask:0xf
	v_mov_b32_dpp v98, v106 row_ror:15 row_mask:0xf bank_mask:0xf
	v_mov_b32_dpp v111, v145 row_shr:1 row_mask:0xf bank_mask:0xf
	v_mov_b32_dpp v99, v107 row_ror:15 row_mask:0xf bank_mask:0xf
	v_pk_fma_f32 v[112:113], v[114:115], v[112:113], v[138:139]
	v_mov_b32_e32 v102, v98
	v_mov_b32_e32 v103, v99
	v_mov_b32_dpp v148, v104 row_ror:2 row_mask:0xf bank_mask:0xf
	v_mov_b32_dpp v149, v105 row_ror:2 row_mask:0xf bank_mask:0xf
	v_pk_fma_f32 v[110:111], v[118:119], v[110:111], v[112:113]
	v_mov_b32_dpp v102, v144 row_shl:1 row_mask:0xf bank_mask:0xf
	v_mov_b32_dpp v103, v145 row_shl:1 row_mask:0xf bank_mask:0xf
	v_mov_b32_dpp v146, v104 row_ror:1 row_mask:0xf bank_mask:0xf
	v_mov_b32_dpp v148, v142 row_shr:2 row_mask:0xf bank_mask:0xf
	v_mov_b32_dpp v147, v105 row_ror:1 row_mask:0xf bank_mask:0xf
	v_mov_b32_dpp v149, v143 row_shr:2 row_mask:0xf bank_mask:0xf
	v_pk_fma_f32 v[110:111], v[144:145], v[122:123], v[110:111]
	v_mov_b32_dpp v146, v142 row_shr:1 row_mask:0xf bank_mask:0xf
	v_mov_b32_dpp v100, v108 row_ror:15 row_mask:0xf bank_mask:0xf
	v_mov_b32_dpp v147, v143 row_shr:1 row_mask:0xf bank_mask:0xf
	v_mov_b32_dpp v101, v109 row_ror:15 row_mask:0xf bank_mask:0xf
	v_pk_fma_f32 v[102:103], v[126:127], v[102:103], v[110:111]
	v_pk_fma_f32 v[110:111], v[116:117], v[148:149], v[140:141]
	v_mov_b32_e32 v104, v100
	v_mov_b32_e32 v105, v101
	v_pk_fma_f32 v[110:111], v[120:121], v[146:147], v[110:111]
	v_mov_b32_dpp v104, v142 row_shl:1 row_mask:0xf bank_mask:0xf
	v_mov_b32_dpp v105, v143 row_shl:1 row_mask:0xf bank_mask:0xf
	v_pk_fma_f32 v[110:111], v[142:143], v[124:125], v[110:111]
	v_cvt_pk_bf16_f32 v102, v102, v103
	v_pk_fma_f32 v[104:105], v[128:129], v[104:105], v[110:111]
	v_cvt_pk_bf16_f32 v103, v104, v105
	global_store_dwordx2 v[200:201], v[102:103], off offset:8
	v_mov_b32_dpp v102, v144 row_ror:1 row_mask:0xf bank_mask:0xf
	v_mov_b32_dpp v104, v144 row_ror:2 row_mask:0xf bank_mask:0xf
	v_mov_b32_dpp v103, v145 row_ror:1 row_mask:0xf bank_mask:0xf
	v_mov_b32_dpp v105, v145 row_ror:2 row_mask:0xf bank_mask:0xf
	v_mov_b32_dpp v110, v142 row_ror:1 row_mask:0xf bank_mask:0xf
	v_mov_b32_dpp v112, v142 row_ror:2 row_mask:0xf bank_mask:0xf
	v_mov_b32_dpp v111, v143 row_ror:1 row_mask:0xf bank_mask:0xf
	v_mov_b32_dpp v113, v143 row_ror:2 row_mask:0xf bank_mask:0xf
	v_mov_b32_dpp v102, v106 row_shr:1 row_mask:0xf bank_mask:0xf
	v_mov_b32_dpp v104, v106 row_shr:2 row_mask:0xf bank_mask:0xf
	v_mov_b32_dpp v98, v106 row_shl:1 row_mask:0xf bank_mask:0xf
	v_mov_b32_dpp v103, v107 row_shr:1 row_mask:0xf bank_mask:0xf
	v_mov_b32_dpp v105, v107 row_shr:2 row_mask:0xf bank_mask:0xf
	v_mov_b32_dpp v99, v107 row_shl:1 row_mask:0xf bank_mask:0xf
	v_mov_b32_dpp v110, v108 row_shr:1 row_mask:0xf bank_mask:0xf
	v_mov_b32_dpp v112, v108 row_shr:2 row_mask:0xf bank_mask:0xf
	v_mov_b32_dpp v100, v108 row_shl:1 row_mask:0xf bank_mask:0xf
	v_mov_b32_dpp v111, v109 row_shr:1 row_mask:0xf bank_mask:0xf
	v_mov_b32_dpp v113, v109 row_shr:2 row_mask:0xf bank_mask:0xf
	v_mov_b32_dpp v101, v109 row_shl:1 row_mask:0xf bank_mask:0xf
	s_and_saveexec_b64 s[30:31], s[46:47]
	s_cbranch_execz .LBB0_485
	v_pk_fma_f32 v[104:105], v[114:115], v[104:105], v[138:139]
	v_ashrrev_i32_e32 v167, 31, v166
	v_pk_fma_f32 v[102:103], v[118:119], v[102:103], v[104:105]
	s_nop 0
	v_pk_fma_f32 v[102:103], v[106:107], v[122:123], v[102:103]
	s_nop 0
	v_pk_fma_f32 v[98:99], v[126:127], v[98:99], v[102:103]
	v_pk_fma_f32 v[102:103], v[116:117], v[112:113], v[140:141]
	v_cvt_pk_bf16_f32 v98, v98, v99
	v_pk_fma_f32 v[102:103], v[120:121], v[110:111], v[102:103]
	s_nop 0
	v_pk_fma_f32 v[102:103], v[108:109], v[124:125], v[102:103]
	s_nop 0
	v_pk_fma_f32 v[100:101], v[128:129], v[100:101], v[102:103]
	s_nop 0
	v_cvt_pk_bf16_f32 v99, v100, v101
	v_lshlrev_b64 v[100:101], 11, v[166:167]
	v_lshl_add_u64 v[100:101], s[34:35], 0, v[100:101]
	v_lshl_add_u64 v[100:101], v[158:159], 1, v[100:101]
	global_store_dwordx2 v[100:101], v[98:99], off offset:8

;     template <int QVV> __device__ __forceinline__ void run(f32x4 (&acc)[2][2][4][2], const Unit& u, int wr, int wc, int fr, int fq) const {
;     ...
;                         for (int m = 0; m < 4; ++m) X[m] = acc[ai][bj][m][n] * rs[ai][m] + sh[n];
;                         if (fr <= 2) *(u32x2*)(tb + lo + (unsigned)(ai * HALF) * rs_ + bj * HALF * 2 + n * 8) = (u32x2){pk2(X[0][0], X[0][1]), pk2(X[0][2], X[0][3])};
;                         if (fr >= 13) *(u32x2*)(tb + lo + (unsigned)(ai * HALF + 48) * rs_ + bj * HALF * 2 + n * 8) = (u32x2){pk2(X[3][0], X[3][1]), pk2(X[3][2], X[3][3])};
; #pragma unroll
;                         for (int m = 0; m < 4; ++m) {
;                             const int mp = m > 0 ? m - 1 : 0, mn = m < 3 ? m + 1 : 3;
;                             f32x4 o;
; #pragma unroll
;                             for (int i = 0; i < 4; ++i) {
;                                 const float xif = X[m][i], xpf = X[mp][i], xnf = X[mn][i];
;                                 const int xi = __float_as_int(xif), xp = __float_as_int(xpf), xn = __float_as_int(xnf);
;                                 const float p1 = __builtin_bit_cast(float, __builtin_amdgcn_update_dpp(__builtin_amdgcn_update_dpp(0, xp, 0x121, 0xf, 0xf, false), xi, 0x111, 0xf, 0xf, false));
;                                 const float p2 = __builtin_bit_cast(float, __builtin_amdgcn_update_dpp(__builtin_amdgcn_update_dpp(0, xp, 0x122, 0xf, 0xf, false), xi, 0x112, 0xf, 0xf, false));
;                                 const float n1 = __builtin_bit_cast(float, __builtin_amdgcn_update_dpp(__builtin_amdgcn_update_dpp(0, xn, 0x12f, 0xf, 0xf, false), xi, 0x101, 0xf, 0xf, false));
;                                 o[i] = bb[i] + w0[i] * p2 + w1[i] * p1 + w2[i] * X[m][i] + w3[i] * n1; }
;                             const int r = r0 + wr * 64 + fr + ai * HALF + m * 16;
;                             const bool edge = (m == 0 && fr < 2) || (m == 3 && fr == 15);
;                             if (!edge) *(u32x2*)(XA + (size_t)r * 1024 + c0 + bj * HALF + 4 * n) = (u32x2){pk2(o[0], o[1]), pk2(o[2], o[3])}; }
.LBB0_489:
	s_or_b64 exec, exec, s[30:31]
	v_pk_fma_f32 v[88:89], v[88:89], v[172:173], v[136:137] op_sel_hi:[1,0,1]
	v_pk_fma_f32 v[86:87], v[86:87], v[172:173], v[134:135] op_sel_hi:[1,0,1]
	v_add_u32_e32 v120, 0x80, v196
	v_mov_b32_dpp v118, v94 row_ror:1 row_mask:0xf bank_mask:0xf
	v_mov_b32_dpp v122, v94 row_ror:2 row_mask:0xf bank_mask:0xf
	v_mov_b32_dpp v126, v86 row_ror:15 row_mask:0xf bank_mask:0xf
	v_mov_b32_dpp v119, v95 row_ror:1 row_mask:0xf bank_mask:0xf
	v_mov_b32_dpp v123, v95 row_ror:2 row_mask:0xf bank_mask:0xf
	v_mov_b32_dpp v127, v87 row_ror:15 row_mask:0xf bank_mask:0xf
	v_mov_b32_dpp v124, v96 row_ror:1 row_mask:0xf bank_mask:0xf
	v_mov_b32_dpp v128, v96 row_ror:2 row_mask:0xf bank_mask:0xf
	v_mov_b32_dpp v138, v88 row_ror:15 row_mask:0xf bank_mask:0xf
	v_mov_b32_dpp v125, v97 row_ror:1 row_mask:0xf bank_mask:0xf
	v_mov_b32_dpp v129, v97 row_ror:2 row_mask:0xf bank_mask:0xf
	v_mov_b32_dpp v139, v89 row_ror:15 row_mask:0xf bank_mask:0xf
	v_mov_b32_dpp v118, v94 row_shr:1 row_mask:0xf bank_mask:0xf
	v_mov_b32_dpp v122, v94 row_shr:2 row_mask:0xf bank_mask:0xf
	v_mov_b32_dpp v126, v94 row_shl:1 row_mask:0xf bank_mask:0xf
	v_mov_b32_dpp v119, v95 row_shr:1 row_mask:0xf bank_mask:0xf
	v_mov_b32_dpp v123, v95 row_shr:2 row_mask:0xf bank_mask:0xf
	v_mov_b32_dpp v127, v95 row_shl:1 row_mask:0xf bank_mask:0xf
	v_mov_b32_dpp v124, v96 row_shr:1 row_mask:0xf bank_mask:0xf
	v_mov_b32_dpp v128, v96 row_shr:2 row_mask:0xf bank_mask:0xf
	v_mov_b32_dpp v138, v96 row_shl:1 row_mask:0xf bank_mask:0xf
	v_mov_b32_dpp v125, v97 row_shr:1 row_mask:0xf bank_mask:0xf
	v_mov_b32_dpp v129, v97 row_shr:2 row_mask:0xf bank_mask:0xf
	v_mov_b32_dpp v139, v97 row_shl:1 row_mask:0xf bank_mask:0xf
	v_ashrrev_i32_e32 v121, 31, v120
	s_and_saveexec_b64 s[2:3], s[44:45]
	s_xor_b64 s[30:31], exec, s[2:3]
	s_cbranch_execz .LBB0_491
	s_waitcnt vmcnt(0)
	v_pk_fma_f32 v[122:123], v[110:111], v[122:123], v[114:115]
	s_nop 0
	v_pk_fma_f32 v[118:119], v[106:107], v[118:119], v[122:123]
	v_pk_fma_f32 v[122:123], v[112:113], v[128:129], v[116:117]
	v_pk_fma_f32 v[118:119], v[94:95], v[98:99], v[118:119]
	v_pk_fma_f32 v[122:123], v[108:109], v[124:125], v[122:123]
	v_pk_fma_f32 v[118:119], v[102:103], v[126:127], v[118:119]
	v_pk_fma_f32 v[122:123], v[96:97], v[100:101], v[122:123]
	v_cvt_pk_bf16_f32 v118, v118, v119
	v_pk_fma_f32 v[122:123], v[104:105], v[138:139], v[122:123]
	s_nop 0
	v_cvt_pk_bf16_f32 v119, v122, v123
	v_lshlrev_b64 v[122:123], 11, v[120:121]
	v_lshl_add_u64 v[122:123], s[34:35], 0, v[122:123]
	v_lshl_add_u64 v[122:123], v[158:159], 1, v[122:123]
	global_store_dwordx2 v[122:123], v[118:119], off
;     template <int QVV> __device__ __forceinline__ void run(f32x4 (&acc)[2][2][4][2], const Unit& u, int wr, int wc, int fr, int fq) const {
;     ...
;                         for (int m = 0; m < 4; ++m) X[m] = acc[ai][bj][m][n] * rs[ai][m] + sh[n];
;                         if (fr <= 2) *(u32x2*)(tb + lo + (unsigned)(ai * HALF) * rs_ + bj * HALF * 2 + n * 8) = (u32x2){pk2(X[0][0], X[0][1]), pk2(X[0][2], X[0][3])};
;                         if (fr >= 13) *(u32x2*)(tb + lo + (unsigned)(ai * HALF + 48) * rs_ + bj * HALF * 2 + n * 8) = (u32x2){pk2(X[3][0], X[3][1]), pk2(X[3][2], X[3][3])};
; #pragma unroll
;                         for (int m = 0; m < 4; ++m) {
;                             const int mp = m > 0 ? m - 1 : 0, mn = m < 3 ? m + 1 : 3;
;                             f32x4 o;
; #pragma unroll
;                             for (int i = 0; i < 4; ++i) {
;                                 const float xif = X[m][i], xpf = X[mp][i], xnf = X[mn][i];
;                                 const int xi = __float_as_int(xif), xp = __float_as_int(xpf), xn = __float_as_int(xnf);
;                                 const float p1 = __builtin_bit_cast(float, __builtin_amdgcn_update_dpp(__builtin_amdgcn_update_dpp(0, xp, 0x121, 0xf, 0xf, false), xi, 0x111, 0xf, 0xf, false));
;                                 const float p2 = __builtin_bit_cast(float, __builtin_amdgcn_update_dpp(__builtin_amdgcn_update_dpp(0, xp, 0x122, 0xf, 0xf, false), xi, 0x112, 0xf, 0xf, false));
;                                 const float n1 = __builtin_bit_cast(float, __builtin_amdgcn_update_dpp(__builtin_amdgcn_update_dpp(0, xn, 0x12f, 0xf, 0xf, false), xi, 0x101, 0xf, 0xf, false));
;                                 o[i] = bb[i] + w0[i] * p2 + w1[i] * p1 + w2[i] * X[m][i] + w3[i] * n1; }
;                             const int r = r0 + wr * 64 + fr + ai * HALF + m * 16;
;                             const bool edge = (m == 0 && fr < 2) || (m == 3 && fr == 15);
;                             if (!edge) *(u32x2*)(XA + (size_t)r * 1024 + c0 + bj * HALF + 4 * n) = (u32x2){pk2(o[0], o[1]), pk2(o[2], o[3])}; }
.LBB0_491:
	s_andn2_saveexec_b64 s[30:31], s[30:31]
	s_or_b64 exec, exec, s[30:31]
	v_pk_fma_f32 v[122:123], v[84:85], v[170:171], v[136:137] op_sel_hi:[1,0,1]
	v_pk_fma_f32 v[124:125], v[82:83], v[170:171], v[134:135] op_sel_hi:[1,0,1]
	v_mov_b32_dpp v84, v94 row_ror:2 row_mask:0xf bank_mask:0xf
	v_mov_b32_dpp v85, v95 row_ror:2 row_mask:0xf bank_mask:0xf
	v_mov_b32_dpp v82, v94 row_ror:1 row_mask:0xf bank_mask:0xf
	v_mov_b32_dpp v84, v86 row_shr:2 row_mask:0xf bank_mask:0xf
	v_mov_b32_dpp v83, v95 row_ror:1 row_mask:0xf bank_mask:0xf
	v_mov_b32_dpp v85, v87 row_shr:2 row_mask:0xf bank_mask:0xf
	v_mov_b32_dpp v126, v96 row_ror:2 row_mask:0xf bank_mask:0xf
	v_mov_b32_dpp v127, v97 row_ror:2 row_mask:0xf bank_mask:0xf
	v_mov_b32_dpp v82, v86 row_shr:1 row_mask:0xf bank_mask:0xf
	v_mov_b32_dpp v83, v87 row_shr:1 row_mask:0xf bank_mask:0xf
	v_mov_b32_dpp v118, v96 row_ror:1 row_mask:0xf bank_mask:0xf
	v_mov_b32_dpp v126, v88 row_shr:2 row_mask:0xf bank_mask:0xf
	v_mov_b32_dpp v119, v97 row_ror:1 row_mask:0xf bank_mask:0xf
	v_mov_b32_dpp v127, v89 row_shr:2 row_mask:0xf bank_mask:0xf
	s_waitcnt vmcnt(0)
	v_pk_fma_f32 v[84:85], v[110:111], v[84:85], v[114:115]
	v_mov_b32_dpp v118, v88 row_shr:1 row_mask:0xf bank_mask:0xf
	v_mov_b32_dpp v119, v89 row_shr:1 row_mask:0xf bank_mask:0xf
	v_pk_fma_f32 v[82:83], v[106:107], v[82:83], v[84:85]
	v_pk_fma_f32 v[84:85], v[112:113], v[126:127], v[116:117]
	v_mov_b32_dpp v94, v124 row_ror:15 row_mask:0xf bank_mask:0xf
	v_mov_b32_dpp v95, v125 row_ror:15 row_mask:0xf bank_mask:0xf
	v_mov_b32_dpp v96, v122 row_ror:15 row_mask:0xf bank_mask:0xf
	v_mov_b32_dpp v97, v123 row_ror:15 row_mask:0xf bank_mask:0xf
	v_pk_fma_f32 v[84:85], v[108:109], v[118:119], v[84:85]
	v_mov_b32_dpp v94, v86 row_shl:1 row_mask:0xf bank_mask:0xf
	v_mov_b32_dpp v95, v87 row_shl:1 row_mask:0xf bank_mask:0xf
	v_mov_b32_dpp v96, v88 row_shl:1 row_mask:0xf bank_mask:0xf
	v_mov_b32_dpp v97, v89 row_shl:1 row_mask:0xf bank_mask:0xf
	v_pk_fma_f32 v[82:83], v[86:87], v[98:99], v[82:83]
	v_pk_fma_f32 v[84:85], v[88:89], v[100:101], v[84:85]
	v_pk_fma_f32 v[82:83], v[102:103], v[94:95], v[82:83]
	v_pk_fma_f32 v[84:85], v[104:105], v[96:97], v[84:85]
	v_lshl_add_u64 v[118:119], v[158:159], 1, v[202:203]
	s_mov_b32 s1, 0x48000
	v_cvt_pk_bf16_f32 v82, v82, v83
	v_cvt_pk_bf16_f32 v83, v84, v85
	v_add_co_u32_e32 v84, vcc, s1, v118
	v_addc_co_u32_e32 v85, vcc, 0, v119, vcc
	v_mov_b32_dpp v96, v86 row_ror:2 row_mask:0xf bank_mask:0xf
	v_mov_b32_dpp v97, v87 row_ror:2 row_mask:0xf bank_mask:0xf
	global_store_dwordx2 v[84:85], v[82:83], off
	v_mov_b32_dpp v94, v86 row_ror:1 row_mask:0xf bank_mask:0xf
	v_mov_b32_dpp v96, v124 row_shr:2 row_mask:0xf bank_mask:0xf
	v_mov_b32_dpp v95, v87 row_ror:1 row_mask:0xf bank_mask:0xf
	v_mov_b32_dpp v97, v125 row_shr:2 row_mask:0xf bank_mask:0xf
	v_mov_b32_dpp v94, v124 row_shr:1 row_mask:0xf bank_mask:0xf
	v_mov_b32_dpp v82, v90 row_ror:15 row_mask:0xf bank_mask:0xf
	v_mov_b32_dpp v95, v125 row_shr:1 row_mask:0xf bank_mask:0xf
	v_mov_b32_dpp v83, v91 row_ror:15 row_mask:0xf bank_mask:0xf
	v_pk_fma_f32 v[96:97], v[110:111], v[96:97], v[114:115]
	v_mov_b32_e32 v86, v82
	v_mov_b32_e32 v87, v83
	v_mov_b32_dpp v128, v88 row_ror:2 row_mask:0xf bank_mask:0xf
	v_mov_b32_dpp v129, v89 row_ror:2 row_mask:0xf bank_mask:0xf
	v_pk_fma_f32 v[94:95], v[106:107], v[94:95], v[96:97]
	v_mov_b32_dpp v86, v124 row_shl:1 row_mask:0xf bank_mask:0xf
	v_mov_b32_dpp v87, v125 row_shl:1 row_mask:0xf bank_mask:0xf
	v_mov_b32_dpp v126, v88 row_ror:1 row_mask:0xf bank_mask:0xf
	v_mov_b32_dpp v128, v122 row_shr:2 row_mask:0xf bank_mask:0xf
	v_mov_b32_dpp v127, v89 row_ror:1 row_mask:0xf bank_mask:0xf
	v_mov_b32_dpp v129, v123 row_shr:2 row_mask:0xf bank_mask:0xf
	v_pk_fma_f32 v[94:95], v[124:125], v[98:99], v[94:95]
	v_mov_b32_dpp v126, v122 row_shr:1 row_mask:0xf bank_mask:0xf
	v_mov_b32_dpp v84, v92 row_ror:15 row_mask:0xf bank_mask:0xf
	v_mov_b32_dpp v127, v123 row_shr:1 row_mask:0xf bank_mask:0xf
	v_mov_b32_dpp v85, v93 row_ror:15 row_mask:0xf bank_mask:0xf
	v_pk_fma_f32 v[86:87], v[102:103], v[86:87], v[94:95]
	v_pk_fma_f32 v[94:95], v[112:113], v[128:129], v[116:117]
	v_mov_b32_e32 v88, v84
	v_mov_b32_e32 v89, v85
	v_pk_fma_f32 v[94:95], v[108:109], v[126:127], v[94:95]
	v_mov_b32_dpp v88, v122 row_shl:1 row_mask:0xf bank_mask:0xf
	v_mov_b32_dpp v89, v123 row_shl:1 row_mask:0xf bank_mask:0xf
	v_pk_fma_f32 v[94:95], v[122:123], v[100:101], v[94:95]
	s_mov_b32 s1, 0x50000
	v_pk_fma_f32 v[88:89], v[104:105], v[88:89], v[94:95]
	v_cvt_pk_bf16_f32 v86, v86, v87
	v_cvt_pk_bf16_f32 v87, v88, v89
	v_add_co_u32_e32 v88, vcc, s1, v118
	s_nop 0
	v_addc_co_u32_e32 v89, vcc, 0, v119, vcc
	global_store_dwordx2 v[88:89], v[86:87], off
	v_mov_b32_dpp v86, v124 row_ror:1 row_mask:0xf bank_mask:0xf
	v_mov_b32_dpp v88, v124 row_ror:2 row_mask:0xf bank_mask:0xf
	v_mov_b32_dpp v87, v125 row_ror:1 row_mask:0xf bank_mask:0xf
	v_mov_b32_dpp v89, v125 row_ror:2 row_mask:0xf bank_mask:0xf
	v_mov_b32_dpp v94, v122 row_ror:1 row_mask:0xf bank_mask:0xf
	v_mov_b32_dpp v96, v122 row_ror:2 row_mask:0xf bank_mask:0xf
	v_mov_b32_dpp v95, v123 row_ror:1 row_mask:0xf bank_mask:0xf
	v_mov_b32_dpp v97, v123 row_ror:2 row_mask:0xf bank_mask:0xf
	v_mov_b32_dpp v86, v90 row_shr:1 row_mask:0xf bank_mask:0xf
	v_mov_b32_dpp v88, v90 row_shr:2 row_mask:0xf bank_mask:0xf
	v_mov_b32_dpp v82, v90 row_shl:1 row_mask:0xf bank_mask:0xf
	v_mov_b32_dpp v87, v91 row_shr:1 row_mask:0xf bank_mask:0xf
	v_mov_b32_dpp v89, v91 row_shr:2 row_mask:0xf bank_mask:0xf
	v_mov_b32_dpp v83, v91 row_shl:1 row_mask:0xf bank_mask:0xf
	v_mov_b32_dpp v94, v92 row_shr:1 row_mask:0xf bank_mask:0xf
	v_mov_b32_dpp v96, v92 row_shr:2 row_mask:0xf bank_mask:0xf
	v_mov_b32_dpp v84, v92 row_shl:1 row_mask:0xf bank_mask:0xf
	v_mov_b32_dpp v95, v93 row_shr:1 row_mask:0xf bank_mask:0xf
	v_mov_b32_dpp v97, v93 row_shr:2 row_mask:0xf bank_mask:0xf
	v_mov_b32_dpp v85, v93 row_shl:1 row_mask:0xf bank_mask:0xf
	s_and_saveexec_b64 s[30:31], s[46:47]
	s_cbranch_execz .LBB0_493
	v_pk_fma_f32 v[88:89], v[110:111], v[88:89], v[114:115]
	s_nop 0
	v_pk_fma_f32 v[86:87], v[106:107], v[86:87], v[88:89]
	s_nop 0
	v_pk_fma_f32 v[86:87], v[90:91], v[98:99], v[86:87]
	s_nop 0
	v_pk_fma_f32 v[82:83], v[102:103], v[82:83], v[86:87]
	v_pk_fma_f32 v[86:87], v[112:113], v[96:97], v[116:117]
	v_cvt_pk_bf16_f32 v82, v82, v83
	v_pk_fma_f32 v[86:87], v[108:109], v[94:95], v[86:87]
	s_nop 0
	v_pk_fma_f32 v[86:87], v[92:93], v[100:101], v[86:87]
	s_nop 0
	v_pk_fma_f32 v[84:85], v[104:105], v[84:85], v[86:87]
	s_nop 0
	v_cvt_pk_bf16_f32 v83, v84, v85
	v_add_co_u32_e32 v84, vcc, 0x58000, v118
	s_nop 1
	v_addc_co_u32_e32 v85, vcc, 0, v119, vcc
	global_store_dwordx2 v[84:85], v[82:83], off

;     template <int QVV> __device__ __forceinline__ void run(f32x4 (&acc)[2][2][4][2], const Unit& u, int wr, int wc, int fr, int fq) const {
;     ...
;                         for (int m = 0; m < 4; ++m) X[m] = acc[ai][bj][m][n] * rs[ai][m] + sh[n];
;                         if (fr <= 2) *(u32x2*)(tb + lo + (unsigned)(ai * HALF) * rs_ + bj * HALF * 2 + n * 8) = (u32x2){pk2(X[0][0], X[0][1]), pk2(X[0][2], X[0][3])};
;                         if (fr >= 13) *(u32x2*)(tb + lo + (unsigned)(ai * HALF + 48) * rs_ + bj * HALF * 2 + n * 8) = (u32x2){pk2(X[3][0], X[3][1]), pk2(X[3][2], X[3][3])};
; #pragma unroll
;                         for (int m = 0; m < 4; ++m) {
;                             const int mp = m > 0 ? m - 1 : 0, mn = m < 3 ? m + 1 : 3;
;                             f32x4 o;
; #pragma unroll
;                             for (int i = 0; i < 4; ++i) {
;                                 const float xif = X[m][i], xpf = X[mp][i], xnf = X[mn][i];
;                                 const int xi = __float_as_int(xif), xp = __float_as_int(xpf), xn = __float_as_int(xnf);
;                                 const float p1 = __builtin_bit_cast(float, __builtin_amdgcn_update_dpp(__builtin_amdgcn_update_dpp(0, xp, 0x121, 0xf, 0xf, false), xi, 0x111, 0xf, 0xf, false));
;                                 const float p2 = __builtin_bit_cast(float, __builtin_amdgcn_update_dpp(__builtin_amdgcn_update_dpp(0, xp, 0x122, 0xf, 0xf, false), xi, 0x112, 0xf, 0xf, false));
;                                 const float n1 = __builtin_bit_cast(float, __builtin_amdgcn_update_dpp(__builtin_amdgcn_update_dpp(0, xn, 0x12f, 0xf, 0xf, false), xi, 0x101, 0xf, 0xf, false));
;                                 o[i] = bb[i] + w0[i] * p2 + w1[i] * p1 + w2[i] * X[m][i] + w3[i] * n1; }
;                             const int r = r0 + wr * 64 + fr + ai * HALF + m * 16;
;                             const bool edge = (m == 0 && fr < 2) || (m == 3 && fr == 15);
;                             if (!edge) *(u32x2*)(XA + (size_t)r * 1024 + c0 + bj * HALF + 4 * n) = (u32x2){pk2(o[0], o[1]), pk2(o[2], o[3])}; }
.LBB0_497:
	s_or_b64 exec, exec, s[30:31]
	v_mov_b32_e32 v173, v172
	v_mov_b32_e32 v102, v172
	v_mov_b32_e32 v103, v172
	v_pk_fma_f32 v[72:73], v[72:73], v[102:103], v[132:133]
	v_pk_fma_f32 v[70:71], v[70:71], v[172:173], v[130:131]
	v_mov_b32_dpp v102, v78 row_ror:1 row_mask:0xf bank_mask:0xf
	v_mov_b32_dpp v104, v78 row_ror:2 row_mask:0xf bank_mask:0xf
	v_mov_b32_dpp v108, v70 row_ror:15 row_mask:0xf bank_mask:0xf
	v_mov_b32_dpp v103, v79 row_ror:1 row_mask:0xf bank_mask:0xf
	v_mov_b32_dpp v105, v79 row_ror:2 row_mask:0xf bank_mask:0xf
	v_mov_b32_dpp v109, v71 row_ror:15 row_mask:0xf bank_mask:0xf
	v_mov_b32_dpp v106, v80 row_ror:1 row_mask:0xf bank_mask:0xf
	v_mov_b32_dpp v110, v80 row_ror:2 row_mask:0xf bank_mask:0xf
	v_mov_b32_dpp v112, v72 row_ror:15 row_mask:0xf bank_mask:0xf
	v_mov_b32_dpp v107, v81 row_ror:1 row_mask:0xf bank_mask:0xf
	v_mov_b32_dpp v111, v81 row_ror:2 row_mask:0xf bank_mask:0xf
	v_mov_b32_dpp v113, v73 row_ror:15 row_mask:0xf bank_mask:0xf
	v_mov_b32_dpp v102, v78 row_shr:1 row_mask:0xf bank_mask:0xf
	v_mov_b32_dpp v104, v78 row_shr:2 row_mask:0xf bank_mask:0xf
	v_mov_b32_dpp v108, v78 row_shl:1 row_mask:0xf bank_mask:0xf
	v_mov_b32_dpp v103, v79 row_shr:1 row_mask:0xf bank_mask:0xf
	v_mov_b32_dpp v105, v79 row_shr:2 row_mask:0xf bank_mask:0xf
	v_mov_b32_dpp v109, v79 row_shl:1 row_mask:0xf bank_mask:0xf
	v_mov_b32_dpp v106, v80 row_shr:1 row_mask:0xf bank_mask:0xf
	v_mov_b32_dpp v110, v80 row_shr:2 row_mask:0xf bank_mask:0xf
	v_mov_b32_dpp v112, v80 row_shl:1 row_mask:0xf bank_mask:0xf
	v_mov_b32_dpp v107, v81 row_shr:1 row_mask:0xf bank_mask:0xf
	v_mov_b32_dpp v111, v81 row_shr:2 row_mask:0xf bank_mask:0xf
	v_mov_b32_dpp v113, v81 row_shl:1 row_mask:0xf bank_mask:0xf
	s_and_saveexec_b64 s[2:3], s[44:45]
	s_xor_b64 s[30:31], exec, s[2:3]
	s_cbranch_execz .LBB0_499
	s_waitcnt vmcnt(0)
	v_pk_fma_f32 v[104:105], v[94:95], v[104:105], v[98:99]
	s_nop 0
	v_pk_fma_f32 v[102:103], v[90:91], v[102:103], v[104:105]
	v_pk_fma_f32 v[104:105], v[96:97], v[110:111], v[100:101]
	v_pk_fma_f32 v[102:103], v[78:79], v[82:83], v[102:103]
	v_pk_fma_f32 v[104:105], v[92:93], v[106:107], v[104:105]
	v_pk_fma_f32 v[102:103], v[86:87], v[108:109], v[102:103]
	v_pk_fma_f32 v[104:105], v[80:81], v[84:85], v[104:105]
	v_cvt_pk_bf16_f32 v102, v102, v103
	v_pk_fma_f32 v[104:105], v[88:89], v[112:113], v[104:105]
	s_nop 0
	v_cvt_pk_bf16_f32 v103, v104, v105
	v_lshlrev_b64 v[104:105], 11, v[120:121]
	v_lshl_add_u64 v[104:105], s[34:35], 0, v[104:105]
	v_lshl_add_u64 v[104:105], v[158:159], 1, v[104:105]
	global_store_dwordx2 v[104:105], v[102:103], off offset:8
;     template <int QVV> __device__ __forceinline__ void run(f32x4 (&acc)[2][2][4][2], const Unit& u, int wr, int wc, int fr, int fq) const {
;     ...
;                         for (int m = 0; m < 4; ++m) X[m] = acc[ai][bj][m][n] * rs[ai][m] + sh[n];
;                         if (fr <= 2) *(u32x2*)(tb + lo + (unsigned)(ai * HALF) * rs_ + bj * HALF * 2 + n * 8) = (u32x2){pk2(X[0][0], X[0][1]), pk2(X[0][2], X[0][3])};
;                         if (fr >= 13) *(u32x2*)(tb + lo + (unsigned)(ai * HALF + 48) * rs_ + bj * HALF * 2 + n * 8) = (u32x2){pk2(X[3][0], X[3][1]), pk2(X[3][2], X[3][3])};
; #pragma unroll
;                         for (int m = 0; m < 4; ++m) {
;                             const int mp = m > 0 ? m - 1 : 0, mn = m < 3 ? m + 1 : 3;
;                             f32x4 o;
; #pragma unroll
;                             for (int i = 0; i < 4; ++i) {
;                                 const float xif = X[m][i], xpf = X[mp][i], xnf = X[mn][i];
;                                 const int xi = __float_as_int(xif), xp = __float_as_int(xpf), xn = __float_as_int(xnf);
;                                 const float p1 = __builtin_bit_cast(float, __builtin_amdgcn_update_dpp(__builtin_amdgcn_update_dpp(0, xp, 0x121, 0xf, 0xf, false), xi, 0x111, 0xf, 0xf, false));
;                                 const float p2 = __builtin_bit_cast(float, __builtin_amdgcn_update_dpp(__builtin_amdgcn_update_dpp(0, xp, 0x122, 0xf, 0xf, false), xi, 0x112, 0xf, 0xf, false));
;                                 const float n1 = __builtin_bit_cast(float, __builtin_amdgcn_update_dpp(__builtin_amdgcn_update_dpp(0, xn, 0x12f, 0xf, 0xf, false), xi, 0x101, 0xf, 0xf, false));
;                                 o[i] = bb[i] + w0[i] * p2 + w1[i] * p1 + w2[i] * X[m][i] + w3[i] * n1; }
;                             const int r = r0 + wr * 64 + fr + ai * HALF + m * 16;
;                             const bool edge = (m == 0 && fr < 2) || (m == 3 && fr == 15);
;                             if (!edge) *(u32x2*)(XA + (size_t)r * 1024 + c0 + bj * HALF + 4 * n) = (u32x2){pk2(o[0], o[1]), pk2(o[2], o[3])}; }
.LBB0_499:
	s_andn2_saveexec_b64 s[30:31], s[30:31]
	s_or_b64 exec, exec, s[30:31]
	v_mov_b32_e32 v106, v170
	v_mov_b32_e32 v107, v170
	v_mov_b32_e32 v171, v170
	v_pk_fma_f32 v[106:107], v[68:69], v[106:107], v[132:133]
	v_pk_fma_f32 v[108:109], v[66:67], v[170:171], v[130:131]
	v_mov_b32_dpp v68, v78 row_ror:2 row_mask:0xf bank_mask:0xf
	v_mov_b32_dpp v69, v79 row_ror:2 row_mask:0xf bank_mask:0xf
	v_mov_b32_dpp v66, v78 row_ror:1 row_mask:0xf bank_mask:0xf
	v_mov_b32_dpp v68, v70 row_shr:2 row_mask:0xf bank_mask:0xf
	v_mov_b32_dpp v67, v79 row_ror:1 row_mask:0xf bank_mask:0xf
	v_mov_b32_dpp v69, v71 row_shr:2 row_mask:0xf bank_mask:0xf
	v_mov_b32_dpp v112, v80 row_ror:2 row_mask:0xf bank_mask:0xf
	v_mov_b32_dpp v113, v81 row_ror:2 row_mask:0xf bank_mask:0xf
	v_mov_b32_dpp v66, v70 row_shr:1 row_mask:0xf bank_mask:0xf
	v_mov_b32_dpp v67, v71 row_shr:1 row_mask:0xf bank_mask:0xf
	v_mov_b32_dpp v110, v80 row_ror:1 row_mask:0xf bank_mask:0xf
	v_mov_b32_dpp v112, v72 row_shr:2 row_mask:0xf bank_mask:0xf
	v_mov_b32_dpp v111, v81 row_ror:1 row_mask:0xf bank_mask:0xf
	v_mov_b32_dpp v113, v73 row_shr:2 row_mask:0xf bank_mask:0xf
	s_waitcnt vmcnt(0)
	v_pk_fma_f32 v[68:69], v[94:95], v[68:69], v[98:99]
	v_mov_b32_dpp v110, v72 row_shr:1 row_mask:0xf bank_mask:0xf
	v_mov_b32_dpp v111, v73 row_shr:1 row_mask:0xf bank_mask:0xf
	v_pk_fma_f32 v[66:67], v[90:91], v[66:67], v[68:69]
	v_pk_fma_f32 v[68:69], v[96:97], v[112:113], v[100:101]
	v_mov_b32_dpp v78, v108 row_ror:15 row_mask:0xf bank_mask:0xf
	v_mov_b32_dpp v79, v109 row_ror:15 row_mask:0xf bank_mask:0xf
	v_mov_b32_dpp v80, v106 row_ror:15 row_mask:0xf bank_mask:0xf
	v_mov_b32_dpp v81, v107 row_ror:15 row_mask:0xf bank_mask:0xf
	v_pk_fma_f32 v[68:69], v[92:93], v[110:111], v[68:69]
	v_mov_b32_dpp v78, v70 row_shl:1 row_mask:0xf bank_mask:0xf
	v_mov_b32_dpp v79, v71 row_shl:1 row_mask:0xf bank_mask:0xf
	v_mov_b32_dpp v80, v72 row_shl:1 row_mask:0xf bank_mask:0xf
	v_mov_b32_dpp v81, v73 row_shl:1 row_mask:0xf bank_mask:0xf
	v_pk_fma_f32 v[66:67], v[70:71], v[82:83], v[66:67]
	v_pk_fma_f32 v[68:69], v[72:73], v[84:85], v[68:69]
	s_mov_b64 s[2:3], 0x48000
	v_pk_fma_f32 v[66:67], v[86:87], v[78:79], v[66:67]
	v_pk_fma_f32 v[68:69], v[88:89], v[80:81], v[68:69]
	v_lshl_add_u64 v[104:105], v[118:119], 0, s[2:3]
	v_cvt_pk_bf16_f32 v66, v66, v67
	v_cvt_pk_bf16_f32 v67, v68, v69
	v_mov_b32_dpp v80, v70 row_ror:2 row_mask:0xf bank_mask:0xf
	v_mov_b32_dpp v81, v71 row_ror:2 row_mask:0xf bank_mask:0xf
	global_store_dwordx2 v[104:105], v[66:67], off offset:8
	v_mov_b32_dpp v78, v70 row_ror:1 row_mask:0xf bank_mask:0xf
	v_mov_b32_dpp v80, v108 row_shr:2 row_mask:0xf bank_mask:0xf
	v_mov_b32_dpp v79, v71 row_ror:1 row_mask:0xf bank_mask:0xf
	v_mov_b32_dpp v81, v109 row_shr:2 row_mask:0xf bank_mask:0xf
	v_mov_b32_dpp v78, v108 row_shr:1 row_mask:0xf bank_mask:0xf
	v_mov_b32_dpp v66, v74 row_ror:15 row_mask:0xf bank_mask:0xf
	v_mov_b32_dpp v79, v109 row_shr:1 row_mask:0xf bank_mask:0xf
	v_mov_b32_dpp v67, v75 row_ror:15 row_mask:0xf bank_mask:0xf
	v_pk_fma_f32 v[80:81], v[94:95], v[80:81], v[98:99]
	v_mov_b32_e32 v70, v66
	v_mov_b32_e32 v71, v67
	v_mov_b32_dpp v112, v72 row_ror:2 row_mask:0xf bank_mask:0xf
	v_mov_b32_dpp v113, v73 row_ror:2 row_mask:0xf bank_mask:0xf
	v_pk_fma_f32 v[78:79], v[90:91], v[78:79], v[80:81]
	v_mov_b32_dpp v70, v108 row_shl:1 row_mask:0xf bank_mask:0xf
	v_mov_b32_dpp v71, v109 row_shl:1 row_mask:0xf bank_mask:0xf
	v_mov_b32_dpp v110, v72 row_ror:1 row_mask:0xf bank_mask:0xf
	v_mov_b32_dpp v112, v106 row_shr:2 row_mask:0xf bank_mask:0xf
	v_mov_b32_dpp v111, v73 row_ror:1 row_mask:0xf bank_mask:0xf
	v_mov_b32_dpp v113, v107 row_shr:2 row_mask:0xf bank_mask:0xf
	v_pk_fma_f32 v[78:79], v[108:109], v[82:83], v[78:79]
	v_mov_b32_dpp v110, v106 row_shr:1 row_mask:0xf bank_mask:0xf
	v_mov_b32_dpp v68, v76 row_ror:15 row_mask:0xf bank_mask:0xf
	v_mov_b32_dpp v111, v107 row_shr:1 row_mask:0xf bank_mask:0xf
	v_mov_b32_dpp v69, v77 row_ror:15 row_mask:0xf bank_mask:0xf
	v_pk_fma_f32 v[70:71], v[86:87], v[70:71], v[78:79]
	v_pk_fma_f32 v[78:79], v[96:97], v[112:113], v[100:101]
	v_mov_b32_e32 v72, v68
	v_mov_b32_e32 v73, v69
	v_pk_fma_f32 v[78:79], v[92:93], v[110:111], v[78:79]
	v_mov_b32_dpp v72, v106 row_shl:1 row_mask:0xf bank_mask:0xf
	v_mov_b32_dpp v73, v107 row_shl:1 row_mask:0xf bank_mask:0xf
	v_pk_fma_f32 v[78:79], v[106:107], v[84:85], v[78:79]
	s_mov_b64 s[2:3], 0x50000
	v_pk_fma_f32 v[72:73], v[88:89], v[72:73], v[78:79]
	v_lshl_add_u64 v[102:103], v[118:119], 0, s[2:3]
	v_cvt_pk_bf16_f32 v70, v70, v71
	v_cvt_pk_bf16_f32 v71, v72, v73
	global_store_dwordx2 v[102:103], v[70:71], off offset:8
	v_mov_b32_dpp v70, v108 row_ror:1 row_mask:0xf bank_mask:0xf
	v_mov_b32_dpp v72, v108 row_ror:2 row_mask:0xf bank_mask:0xf
	v_mov_b32_dpp v71, v109 row_ror:1 row_mask:0xf bank_mask:0xf
	v_mov_b32_dpp v73, v109 row_ror:2 row_mask:0xf bank_mask:0xf
	v_mov_b32_dpp v78, v106 row_ror:1 row_mask:0xf bank_mask:0xf
	v_mov_b32_dpp v80, v106 row_ror:2 row_mask:0xf bank_mask:0xf
	v_mov_b32_dpp v79, v107 row_ror:1 row_mask:0xf bank_mask:0xf
	v_mov_b32_dpp v81, v107 row_ror:2 row_mask:0xf bank_mask:0xf
	v_mov_b32_dpp v70, v74 row_shr:1 row_mask:0xf bank_mask:0xf
	v_mov_b32_dpp v72, v74 row_shr:2 row_mask:0xf bank_mask:0xf
	v_mov_b32_dpp v66, v74 row_shl:1 row_mask:0xf bank_mask:0xf
	v_mov_b32_dpp v71, v75 row_shr:1 row_mask:0xf bank_mask:0xf
	v_mov_b32_dpp v73, v75 row_shr:2 row_mask:0xf bank_mask:0xf
	v_mov_b32_dpp v67, v75 row_shl:1 row_mask:0xf bank_mask:0xf
	v_mov_b32_dpp v78, v76 row_shr:1 row_mask:0xf bank_mask:0xf
	v_mov_b32_dpp v80, v76 row_shr:2 row_mask:0xf bank_mask:0xf
	v_mov_b32_dpp v68, v76 row_shl:1 row_mask:0xf bank_mask:0xf
	v_mov_b32_dpp v79, v77 row_shr:1 row_mask:0xf bank_mask:0xf
	v_mov_b32_dpp v81, v77 row_shr:2 row_mask:0xf bank_mask:0xf
	v_mov_b32_dpp v69, v77 row_shl:1 row_mask:0xf bank_mask:0xf
	s_and_saveexec_b64 s[30:31], s[46:47]
	s_cbranch_execz .LBB0_501
	v_pk_fma_f32 v[72:73], v[94:95], v[72:73], v[98:99]
	s_nop 0
	v_pk_fma_f32 v[70:71], v[90:91], v[70:71], v[72:73]
	s_nop 0
	v_pk_fma_f32 v[70:71], v[74:75], v[82:83], v[70:71]
	s_nop 0
	v_pk_fma_f32 v[66:67], v[86:87], v[66:67], v[70:71]
	v_pk_fma_f32 v[70:71], v[96:97], v[80:81], v[100:101]
	v_cvt_pk_bf16_f32 v66, v66, v67
	v_pk_fma_f32 v[70:71], v[92:93], v[78:79], v[70:71]
	s_nop 0
	v_pk_fma_f32 v[70:71], v[76:77], v[84:85], v[70:71]
	s_nop 0
	v_pk_fma_f32 v[68:69], v[88:89], v[68:69], v[70:71]
	s_nop 0
	v_cvt_pk_bf16_f32 v67, v68, v69
	v_add_co_u32_e32 v68, vcc, 0x58000, v118
	s_nop 1
	v_addc_co_u32_e32 v69, vcc, 0, v119, vcc
	global_store_dwordx2 v[68:69], v[66:67], off offset:8

;     template <int QVV> __device__ __forceinline__ void run(f32x4 (&acc)[2][2][4][2], const Unit& u, int wr, int wc, int fr, int fq) const {
;     ...
;                         for (int m = 0; m < 4; ++m) X[m] = acc[ai][bj][m][n] * rs[ai][m] + sh[n];
;                         if (fr <= 2) *(u32x2*)(tb + lo + (unsigned)(ai * HALF) * rs_ + bj * HALF * 2 + n * 8) = (u32x2){pk2(X[0][0], X[0][1]), pk2(X[0][2], X[0][3])};
;                         if (fr >= 13) *(u32x2*)(tb + lo + (unsigned)(ai * HALF + 48) * rs_ + bj * HALF * 2 + n * 8) = (u32x2){pk2(X[3][0], X[3][1]), pk2(X[3][2], X[3][3])};
; #pragma unroll
;                         for (int m = 0; m < 4; ++m) {
;                             const int mp = m > 0 ? m - 1 : 0, mn = m < 3 ? m + 1 : 3;
;                             f32x4 o;
; #pragma unroll
;                             for (int i = 0; i < 4; ++i) {
;                                 const float xif = X[m][i], xpf = X[mp][i], xnf = X[mn][i];
;                                 const int xi = __float_as_int(xif), xp = __float_as_int(xpf), xn = __float_as_int(xnf);
;                                 const float p1 = __builtin_bit_cast(float, __builtin_amdgcn_update_dpp(__builtin_amdgcn_update_dpp(0, xp, 0x121, 0xf, 0xf, false), xi, 0x111, 0xf, 0xf, false));
;                                 const float p2 = __builtin_bit_cast(float, __builtin_amdgcn_update_dpp(__builtin_amdgcn_update_dpp(0, xp, 0x122, 0xf, 0xf, false), xi, 0x112, 0xf, 0xf, false));
;                                 const float n1 = __builtin_bit_cast(float, __builtin_amdgcn_update_dpp(__builtin_amdgcn_update_dpp(0, xn, 0x12f, 0xf, 0xf, false), xi, 0x101, 0xf, 0xf, false));
;                                 o[i] = bb[i] + w0[i] * p2 + w1[i] * p1 + w2[i] * X[m][i] + w3[i] * n1; }
;                             const int r = r0 + wr * 64 + fr + ai * HALF + m * 16;
;                             const bool edge = (m == 0 && fr < 2) || (m == 3 && fr == 15);
;                             if (!edge) *(u32x2*)(XA + (size_t)r * 1024 + c0 + bj * HALF + 4 * n) = (u32x2){pk2(o[0], o[1]), pk2(o[2], o[3])}; }
.LBB0_505:
	s_or_b64 exec, exec, s[30:31]
	v_mov_b32_e32 v94, v188
	v_mov_b32_e32 v95, v188
	v_pk_fma_f32 v[56:57], v[56:57], v[94:95], v[72:73]
	v_pk_fma_f32 v[54:55], v[54:55], v[188:189], v[70:71]
	v_mov_b32_dpp v94, v62 row_ror:1 row_mask:0xf bank_mask:0xf
	v_mov_b32_dpp v96, v62 row_ror:2 row_mask:0xf bank_mask:0xf
	v_mov_b32_dpp v100, v54 row_ror:15 row_mask:0xf bank_mask:0xf
	v_mov_b32_dpp v95, v63 row_ror:1 row_mask:0xf bank_mask:0xf
	v_mov_b32_dpp v97, v63 row_ror:2 row_mask:0xf bank_mask:0xf
	v_mov_b32_dpp v101, v55 row_ror:15 row_mask:0xf bank_mask:0xf
	v_mov_b32_dpp v98, v64 row_ror:1 row_mask:0xf bank_mask:0xf
	v_mov_b32_dpp v106, v64 row_ror:2 row_mask:0xf bank_mask:0xf
	v_mov_b32_dpp v108, v56 row_ror:15 row_mask:0xf bank_mask:0xf
	v_mov_b32_dpp v99, v65 row_ror:1 row_mask:0xf bank_mask:0xf
	v_mov_b32_dpp v107, v65 row_ror:2 row_mask:0xf bank_mask:0xf
	v_mov_b32_dpp v109, v57 row_ror:15 row_mask:0xf bank_mask:0xf
	v_mov_b32_dpp v94, v62 row_shr:1 row_mask:0xf bank_mask:0xf
	v_mov_b32_dpp v96, v62 row_shr:2 row_mask:0xf bank_mask:0xf
	v_mov_b32_dpp v100, v62 row_shl:1 row_mask:0xf bank_mask:0xf
	v_mov_b32_dpp v95, v63 row_shr:1 row_mask:0xf bank_mask:0xf
	v_mov_b32_dpp v97, v63 row_shr:2 row_mask:0xf bank_mask:0xf
	v_mov_b32_dpp v101, v63 row_shl:1 row_mask:0xf bank_mask:0xf
	v_mov_b32_dpp v98, v64 row_shr:1 row_mask:0xf bank_mask:0xf
	v_mov_b32_dpp v106, v64 row_shr:2 row_mask:0xf bank_mask:0xf
	v_mov_b32_dpp v108, v64 row_shl:1 row_mask:0xf bank_mask:0xf
	v_mov_b32_dpp v99, v65 row_shr:1 row_mask:0xf bank_mask:0xf
	v_mov_b32_dpp v107, v65 row_shr:2 row_mask:0xf bank_mask:0xf
	v_mov_b32_dpp v109, v65 row_shl:1 row_mask:0xf bank_mask:0xf
	s_and_saveexec_b64 s[2:3], s[44:45]
	s_xor_b64 s[30:31], exec, s[2:3]
	s_cbranch_execz .LBB0_507
	s_waitcnt vmcnt(0)
	v_pk_fma_f32 v[96:97], v[74:75], v[96:97], v[90:91]
	s_nop 0
	v_pk_fma_f32 v[94:95], v[78:79], v[94:95], v[96:97]
	v_pk_fma_f32 v[96:97], v[76:77], v[106:107], v[92:93]
	v_pk_fma_f32 v[94:95], v[62:63], v[82:83], v[94:95]
	v_pk_fma_f32 v[96:97], v[80:81], v[98:99], v[96:97]
	v_pk_fma_f32 v[94:95], v[86:87], v[100:101], v[94:95]
	v_pk_fma_f32 v[96:97], v[64:65], v[84:85], v[96:97]
	v_cvt_pk_bf16_f32 v94, v94, v95
	v_pk_fma_f32 v[96:97], v[88:89], v[108:109], v[96:97]
	s_nop 0
	v_cvt_pk_bf16_f32 v95, v96, v97
	global_store_dwordx2 v[118:119], v[94:95], off offset:256
;     template <int QVV> __device__ __forceinline__ void run(f32x4 (&acc)[2][2][4][2], const Unit& u, int wr, int wc, int fr, int fq) const {
;     ...
;                         for (int m = 0; m < 4; ++m) X[m] = acc[ai][bj][m][n] * rs[ai][m] + sh[n];
;                         if (fr <= 2) *(u32x2*)(tb + lo + (unsigned)(ai * HALF) * rs_ + bj * HALF * 2 + n * 8) = (u32x2){pk2(X[0][0], X[0][1]), pk2(X[0][2], X[0][3])};
;                         if (fr >= 13) *(u32x2*)(tb + lo + (unsigned)(ai * HALF + 48) * rs_ + bj * HALF * 2 + n * 8) = (u32x2){pk2(X[3][0], X[3][1]), pk2(X[3][2], X[3][3])};
; #pragma unroll
;                         for (int m = 0; m < 4; ++m) {
;                             const int mp = m > 0 ? m - 1 : 0, mn = m < 3 ? m + 1 : 3;
;                             f32x4 o;
; #pragma unroll
;                             for (int i = 0; i < 4; ++i) {
;                                 const float xif = X[m][i], xpf = X[mp][i], xnf = X[mn][i];
;                                 const int xi = __float_as_int(xif), xp = __float_as_int(xpf), xn = __float_as_int(xnf);
;                                 const float p1 = __builtin_bit_cast(float, __builtin_amdgcn_update_dpp(__builtin_amdgcn_update_dpp(0, xp, 0x121, 0xf, 0xf, false), xi, 0x111, 0xf, 0xf, false));
;                                 const float p2 = __builtin_bit_cast(float, __builtin_amdgcn_update_dpp(__builtin_amdgcn_update_dpp(0, xp, 0x122, 0xf, 0xf, false), xi, 0x112, 0xf, 0xf, false));
;                                 const float n1 = __builtin_bit_cast(float, __builtin_amdgcn_update_dpp(__builtin_amdgcn_update_dpp(0, xn, 0x12f, 0xf, 0xf, false), xi, 0x101, 0xf, 0xf, false));
;                                 o[i] = bb[i] + w0[i] * p2 + w1[i] * p1 + w2[i] * X[m][i] + w3[i] * n1; }
;                             const int r = r0 + wr * 64 + fr + ai * HALF + m * 16;
;                             const bool edge = (m == 0 && fr < 2) || (m == 3 && fr == 15);
;                             if (!edge) *(u32x2*)(XA + (size_t)r * 1024 + c0 + bj * HALF + 4 * n) = (u32x2){pk2(o[0], o[1]), pk2(o[2], o[3])}; }
.LBB0_507:
	s_andn2_saveexec_b64 s[30:31], s[30:31]
	s_or_b64 exec, exec, s[30:31]
	v_mov_b32_e32 v94, v186
	v_mov_b32_e32 v95, v186
	v_pk_fma_f32 v[94:95], v[52:53], v[94:95], v[72:73]
	v_pk_fma_f32 v[96:97], v[50:51], v[186:187], v[70:71]
	v_mov_b32_dpp v52, v62 row_ror:2 row_mask:0xf bank_mask:0xf
	v_mov_b32_dpp v53, v63 row_ror:2 row_mask:0xf bank_mask:0xf
	v_mov_b32_dpp v50, v62 row_ror:1 row_mask:0xf bank_mask:0xf
	v_mov_b32_dpp v52, v54 row_shr:2 row_mask:0xf bank_mask:0xf
	v_mov_b32_dpp v51, v63 row_ror:1 row_mask:0xf bank_mask:0xf
	v_mov_b32_dpp v53, v55 row_shr:2 row_mask:0xf bank_mask:0xf
	v_mov_b32_dpp v100, v64 row_ror:2 row_mask:0xf bank_mask:0xf
	v_mov_b32_dpp v101, v65 row_ror:2 row_mask:0xf bank_mask:0xf
	v_mov_b32_dpp v50, v54 row_shr:1 row_mask:0xf bank_mask:0xf
	v_mov_b32_dpp v51, v55 row_shr:1 row_mask:0xf bank_mask:0xf
	v_mov_b32_dpp v98, v64 row_ror:1 row_mask:0xf bank_mask:0xf
	v_mov_b32_dpp v100, v56 row_shr:2 row_mask:0xf bank_mask:0xf
	v_mov_b32_dpp v99, v65 row_ror:1 row_mask:0xf bank_mask:0xf
	v_mov_b32_dpp v101, v57 row_shr:2 row_mask:0xf bank_mask:0xf
	s_waitcnt vmcnt(0)
	v_pk_fma_f32 v[52:53], v[74:75], v[52:53], v[90:91]
	v_mov_b32_dpp v98, v56 row_shr:1 row_mask:0xf bank_mask:0xf
	v_mov_b32_dpp v99, v57 row_shr:1 row_mask:0xf bank_mask:0xf
	v_pk_fma_f32 v[50:51], v[78:79], v[50:51], v[52:53]
	v_pk_fma_f32 v[52:53], v[76:77], v[100:101], v[92:93]
	v_mov_b32_dpp v62, v96 row_ror:15 row_mask:0xf bank_mask:0xf
	v_mov_b32_dpp v63, v97 row_ror:15 row_mask:0xf bank_mask:0xf
	v_mov_b32_dpp v64, v94 row_ror:15 row_mask:0xf bank_mask:0xf
	v_mov_b32_dpp v65, v95 row_ror:15 row_mask:0xf bank_mask:0xf
	v_pk_fma_f32 v[52:53], v[80:81], v[98:99], v[52:53]
	v_mov_b32_dpp v62, v54 row_shl:1 row_mask:0xf bank_mask:0xf
	v_mov_b32_dpp v63, v55 row_shl:1 row_mask:0xf bank_mask:0xf
	v_mov_b32_dpp v64, v56 row_shl:1 row_mask:0xf bank_mask:0xf
	v_mov_b32_dpp v65, v57 row_shl:1 row_mask:0xf bank_mask:0xf
	v_pk_fma_f32 v[50:51], v[54:55], v[82:83], v[50:51]
	v_pk_fma_f32 v[52:53], v[56:57], v[84:85], v[52:53]
	v_pk_fma_f32 v[50:51], v[86:87], v[62:63], v[50:51]
	v_pk_fma_f32 v[52:53], v[88:89], v[64:65], v[52:53]
	v_cvt_pk_bf16_f32 v50, v50, v51
	v_cvt_pk_bf16_f32 v51, v52, v53
	v_mov_b32_dpp v64, v54 row_ror:2 row_mask:0xf bank_mask:0xf
	v_mov_b32_dpp v65, v55 row_ror:2 row_mask:0xf bank_mask:0xf
	global_store_dwordx2 v[198:199], v[50:51], off offset:256
	v_mov_b32_dpp v62, v54 row_ror:1 row_mask:0xf bank_mask:0xf
	v_mov_b32_dpp v64, v96 row_shr:2 row_mask:0xf bank_mask:0xf
	v_mov_b32_dpp v63, v55 row_ror:1 row_mask:0xf bank_mask:0xf
	v_mov_b32_dpp v65, v97 row_shr:2 row_mask:0xf bank_mask:0xf
	v_mov_b32_dpp v62, v96 row_shr:1 row_mask:0xf bank_mask:0xf
	v_mov_b32_dpp v50, v58 row_ror:15 row_mask:0xf bank_mask:0xf
	v_mov_b32_dpp v63, v97 row_shr:1 row_mask:0xf bank_mask:0xf
	v_mov_b32_dpp v51, v59 row_ror:15 row_mask:0xf bank_mask:0xf
	v_pk_fma_f32 v[64:65], v[74:75], v[64:65], v[90:91]
	v_mov_b32_e32 v54, v50
	v_mov_b32_e32 v55, v51
	v_mov_b32_dpp v100, v56 row_ror:2 row_mask:0xf bank_mask:0xf
	v_mov_b32_dpp v101, v57 row_ror:2 row_mask:0xf bank_mask:0xf
	v_pk_fma_f32 v[62:63], v[78:79], v[62:63], v[64:65]
	v_mov_b32_dpp v54, v96 row_shl:1 row_mask:0xf bank_mask:0xf
	v_mov_b32_dpp v55, v97 row_shl:1 row_mask:0xf bank_mask:0xf
	v_mov_b32_dpp v98, v56 row_ror:1 row_mask:0xf bank_mask:0xf
	v_mov_b32_dpp v100, v94 row_shr:2 row_mask:0xf bank_mask:0xf
	v_mov_b32_dpp v99, v57 row_ror:1 row_mask:0xf bank_mask:0xf
	v_mov_b32_dpp v101, v95 row_shr:2 row_mask:0xf bank_mask:0xf
	v_pk_fma_f32 v[62:63], v[96:97], v[82:83], v[62:63]
	v_mov_b32_dpp v98, v94 row_shr:1 row_mask:0xf bank_mask:0xf
	v_mov_b32_dpp v52, v60 row_ror:15 row_mask:0xf bank_mask:0xf
	v_mov_b32_dpp v99, v95 row_shr:1 row_mask:0xf bank_mask:0xf
	v_mov_b32_dpp v53, v61 row_ror:15 row_mask:0xf bank_mask:0xf
	v_pk_fma_f32 v[54:55], v[86:87], v[54:55], v[62:63]
	v_pk_fma_f32 v[62:63], v[76:77], v[100:101], v[92:93]
	v_mov_b32_e32 v56, v52
	v_mov_b32_e32 v57, v53
	v_pk_fma_f32 v[62:63], v[80:81], v[98:99], v[62:63]
	v_mov_b32_dpp v56, v94 row_shl:1 row_mask:0xf bank_mask:0xf
	v_mov_b32_dpp v57, v95 row_shl:1 row_mask:0xf bank_mask:0xf
	v_pk_fma_f32 v[62:63], v[94:95], v[84:85], v[62:63]
	v_cvt_pk_bf16_f32 v54, v54, v55
	v_pk_fma_f32 v[56:57], v[88:89], v[56:57], v[62:63]
	v_cvt_pk_bf16_f32 v55, v56, v57
	global_store_dwordx2 v[200:201], v[54:55], off offset:256
	v_mov_b32_dpp v54, v96 row_ror:1 row_mask:0xf bank_mask:0xf
	v_mov_b32_dpp v56, v96 row_ror:2 row_mask:0xf bank_mask:0xf
	v_mov_b32_dpp v55, v97 row_ror:1 row_mask:0xf bank_mask:0xf
	v_mov_b32_dpp v57, v97 row_ror:2 row_mask:0xf bank_mask:0xf
	v_mov_b32_dpp v62, v94 row_ror:1 row_mask:0xf bank_mask:0xf
	v_mov_b32_dpp v64, v94 row_ror:2 row_mask:0xf bank_mask:0xf
	v_mov_b32_dpp v63, v95 row_ror:1 row_mask:0xf bank_mask:0xf
	v_mov_b32_dpp v65, v95 row_ror:2 row_mask:0xf bank_mask:0xf
	v_mov_b32_dpp v54, v58 row_shr:1 row_mask:0xf bank_mask:0xf
	v_mov_b32_dpp v56, v58 row_shr:2 row_mask:0xf bank_mask:0xf
	v_mov_b32_dpp v50, v58 row_shl:1 row_mask:0xf bank_mask:0xf
	v_mov_b32_dpp v55, v59 row_shr:1 row_mask:0xf bank_mask:0xf
	v_mov_b32_dpp v57, v59 row_shr:2 row_mask:0xf bank_mask:0xf
	v_mov_b32_dpp v51, v59 row_shl:1 row_mask:0xf bank_mask:0xf
	v_mov_b32_dpp v62, v60 row_shr:1 row_mask:0xf bank_mask:0xf
	v_mov_b32_dpp v64, v60 row_shr:2 row_mask:0xf bank_mask:0xf
	v_mov_b32_dpp v52, v60 row_shl:1 row_mask:0xf bank_mask:0xf
	v_mov_b32_dpp v63, v61 row_shr:1 row_mask:0xf bank_mask:0xf
	v_mov_b32_dpp v65, v61 row_shr:2 row_mask:0xf bank_mask:0xf
	v_mov_b32_dpp v53, v61 row_shl:1 row_mask:0xf bank_mask:0xf
	s_and_saveexec_b64 s[30:31], s[46:47]
	s_cbranch_execz .LBB0_509
	v_pk_fma_f32 v[56:57], v[74:75], v[56:57], v[90:91]
	v_ashrrev_i32_e32 v167, 31, v166
	v_pk_fma_f32 v[54:55], v[78:79], v[54:55], v[56:57]
	s_nop 0
	v_pk_fma_f32 v[54:55], v[58:59], v[82:83], v[54:55]
	s_nop 0
	v_pk_fma_f32 v[50:51], v[86:87], v[50:51], v[54:55]
	v_pk_fma_f32 v[54:55], v[76:77], v[64:65], v[92:93]
	v_cvt_pk_bf16_f32 v50, v50, v51
	v_pk_fma_f32 v[54:55], v[80:81], v[62:63], v[54:55]
	s_nop 0
	v_pk_fma_f32 v[54:55], v[60:61], v[84:85], v[54:55]
	s_nop 0
	v_pk_fma_f32 v[52:53], v[88:89], v[52:53], v[54:55]
	s_nop 0
	v_cvt_pk_bf16_f32 v51, v52, v53
	v_lshlrev_b64 v[52:53], 11, v[166:167]
	v_lshl_add_u64 v[52:53], s[34:35], 0, v[52:53]
	v_lshl_add_u64 v[52:53], v[158:159], 1, v[52:53]
	global_store_dwordx2 v[52:53], v[50:51], off offset:256

;     template <int QVV> __device__ __forceinline__ void run(f32x4 (&acc)[2][2][4][2], const Unit& u, int wr, int wc, int fr, int fq) const {
;     ...
;                         for (int m = 0; m < 4; ++m) X[m] = acc[ai][bj][m][n] * rs[ai][m] + sh[n];
;                         if (fr <= 2) *(u32x2*)(tb + lo + (unsigned)(ai * HALF) * rs_ + bj * HALF * 2 + n * 8) = (u32x2){pk2(X[0][0], X[0][1]), pk2(X[0][2], X[0][3])};
;                         if (fr >= 13) *(u32x2*)(tb + lo + (unsigned)(ai * HALF + 48) * rs_ + bj * HALF * 2 + n * 8) = (u32x2){pk2(X[3][0], X[3][1]), pk2(X[3][2], X[3][3])};
; #pragma unroll
;                         for (int m = 0; m < 4; ++m) {
;                             const int mp = m > 0 ? m - 1 : 0, mn = m < 3 ? m + 1 : 3;
;                             f32x4 o;
; #pragma unroll
;                             for (int i = 0; i < 4; ++i) {
;                                 const float xif = X[m][i], xpf = X[mp][i], xnf = X[mn][i];
;                                 const int xi = __float_as_int(xif), xp = __float_as_int(xpf), xn = __float_as_int(xnf);
;                                 const float p1 = __builtin_bit_cast(float, __builtin_amdgcn_update_dpp(__builtin_amdgcn_update_dpp(0, xp, 0x121, 0xf, 0xf, false), xi, 0x111, 0xf, 0xf, false));
;                                 const float p2 = __builtin_bit_cast(float, __builtin_amdgcn_update_dpp(__builtin_amdgcn_update_dpp(0, xp, 0x122, 0xf, 0xf, false), xi, 0x112, 0xf, 0xf, false));
;                                 const float n1 = __builtin_bit_cast(float, __builtin_amdgcn_update_dpp(__builtin_amdgcn_update_dpp(0, xn, 0x12f, 0xf, 0xf, false), xi, 0x101, 0xf, 0xf, false));
;                                 o[i] = bb[i] + w0[i] * p2 + w1[i] * p1 + w2[i] * X[m][i] + w3[i] * n1; }
;                             const int r = r0 + wr * 64 + fr + ai * HALF + m * 16;
;                             const bool edge = (m == 0 && fr < 2) || (m == 3 && fr == 15);
;                             if (!edge) *(u32x2*)(XA + (size_t)r * 1024 + c0 + bj * HALF + 4 * n) = (u32x2){pk2(o[0], o[1]), pk2(o[2], o[3])}; }
.LBB0_513:
	s_or_b64 exec, exec, s[30:31]
	v_mov_b32_e32 v78, v188
	v_mov_b32_e32 v79, v188
	v_pk_fma_f32 v[40:41], v[40:41], v[78:79], v[68:69]
	v_pk_fma_f32 v[38:39], v[38:39], v[188:189], v[66:67]
	v_mov_b32_dpp v78, v46 row_ror:1 row_mask:0xf bank_mask:0xf
	v_mov_b32_dpp v80, v46 row_ror:2 row_mask:0xf bank_mask:0xf
	v_mov_b32_dpp v84, v38 row_ror:15 row_mask:0xf bank_mask:0xf
	v_mov_b32_dpp v79, v47 row_ror:1 row_mask:0xf bank_mask:0xf
	v_mov_b32_dpp v81, v47 row_ror:2 row_mask:0xf bank_mask:0xf
	v_mov_b32_dpp v85, v39 row_ror:15 row_mask:0xf bank_mask:0xf
	v_mov_b32_dpp v82, v48 row_ror:1 row_mask:0xf bank_mask:0xf
	v_mov_b32_dpp v86, v48 row_ror:2 row_mask:0xf bank_mask:0xf
	v_mov_b32_dpp v88, v40 row_ror:15 row_mask:0xf bank_mask:0xf
	v_mov_b32_dpp v83, v49 row_ror:1 row_mask:0xf bank_mask:0xf
	v_mov_b32_dpp v87, v49 row_ror:2 row_mask:0xf bank_mask:0xf
	v_mov_b32_dpp v89, v41 row_ror:15 row_mask:0xf bank_mask:0xf
	v_mov_b32_dpp v78, v46 row_shr:1 row_mask:0xf bank_mask:0xf
	v_mov_b32_dpp v80, v46 row_shr:2 row_mask:0xf bank_mask:0xf
	v_mov_b32_dpp v84, v46 row_shl:1 row_mask:0xf bank_mask:0xf
	v_mov_b32_dpp v79, v47 row_shr:1 row_mask:0xf bank_mask:0xf
	v_mov_b32_dpp v81, v47 row_shr:2 row_mask:0xf bank_mask:0xf
	v_mov_b32_dpp v85, v47 row_shl:1 row_mask:0xf bank_mask:0xf
	v_mov_b32_dpp v82, v48 row_shr:1 row_mask:0xf bank_mask:0xf
	v_mov_b32_dpp v86, v48 row_shr:2 row_mask:0xf bank_mask:0xf
	v_mov_b32_dpp v88, v48 row_shl:1 row_mask:0xf bank_mask:0xf
	v_mov_b32_dpp v83, v49 row_shr:1 row_mask:0xf bank_mask:0xf
	v_mov_b32_dpp v87, v49 row_shr:2 row_mask:0xf bank_mask:0xf
	v_mov_b32_dpp v89, v49 row_shl:1 row_mask:0xf bank_mask:0xf
	s_and_saveexec_b64 s[2:3], s[44:45]
	s_xor_b64 s[30:31], exec, s[2:3]
	s_cbranch_execz .LBB0_515
	s_waitcnt vmcnt(0)
	v_pk_fma_f32 v[80:81], v[50:51], v[80:81], v[74:75]
	s_nop 0
	v_pk_fma_f32 v[78:79], v[54:55], v[78:79], v[80:81]
	v_pk_fma_f32 v[80:81], v[52:53], v[86:87], v[76:77]
	v_pk_fma_f32 v[78:79], v[46:47], v[58:59], v[78:79]
	v_pk_fma_f32 v[80:81], v[56:57], v[82:83], v[80:81]
	v_pk_fma_f32 v[78:79], v[62:63], v[84:85], v[78:79]
	v_pk_fma_f32 v[80:81], v[48:49], v[60:61], v[80:81]
	v_cvt_pk_bf16_f32 v78, v78, v79
	v_pk_fma_f32 v[80:81], v[64:65], v[88:89], v[80:81]
	s_nop 0
	v_cvt_pk_bf16_f32 v79, v80, v81
	global_store_dwordx2 v[118:119], v[78:79], off offset:264
;     template <int QVV> __device__ __forceinline__ void run(f32x4 (&acc)[2][2][4][2], const Unit& u, int wr, int wc, int fr, int fq) const {
;     ...
;                         for (int m = 0; m < 4; ++m) X[m] = acc[ai][bj][m][n] * rs[ai][m] + sh[n];
;                         if (fr <= 2) *(u32x2*)(tb + lo + (unsigned)(ai * HALF) * rs_ + bj * HALF * 2 + n * 8) = (u32x2){pk2(X[0][0], X[0][1]), pk2(X[0][2], X[0][3])};
;                         if (fr >= 13) *(u32x2*)(tb + lo + (unsigned)(ai * HALF + 48) * rs_ + bj * HALF * 2 + n * 8) = (u32x2){pk2(X[3][0], X[3][1]), pk2(X[3][2], X[3][3])};
; #pragma unroll
;                         for (int m = 0; m < 4; ++m) {
;                             const int mp = m > 0 ? m - 1 : 0, mn = m < 3 ? m + 1 : 3;
;                             f32x4 o;
; #pragma unroll
;                             for (int i = 0; i < 4; ++i) {
;                                 const float xif = X[m][i], xpf = X[mp][i], xnf = X[mn][i];
;                                 const int xi = __float_as_int(xif), xp = __float_as_int(xpf), xn = __float_as_int(xnf);
;                                 const float p1 = __builtin_bit_cast(float, __builtin_amdgcn_update_dpp(__builtin_amdgcn_update_dpp(0, xp, 0x121, 0xf, 0xf, false), xi, 0x111, 0xf, 0xf, false));
;                                 const float p2 = __builtin_bit_cast(float, __builtin_amdgcn_update_dpp(__builtin_amdgcn_update_dpp(0, xp, 0x122, 0xf, 0xf, false), xi, 0x112, 0xf, 0xf, false));
;                                 const float n1 = __builtin_bit_cast(float, __builtin_amdgcn_update_dpp(__builtin_amdgcn_update_dpp(0, xn, 0x12f, 0xf, 0xf, false), xi, 0x101, 0xf, 0xf, false));
;                                 o[i] = bb[i] + w0[i] * p2 + w1[i] * p1 + w2[i] * X[m][i] + w3[i] * n1; }
;                             const int r = r0 + wr * 64 + fr + ai * HALF + m * 16;
;                             const bool edge = (m == 0 && fr < 2) || (m == 3 && fr == 15);
;                             if (!edge) *(u32x2*)(XA + (size_t)r * 1024 + c0 + bj * HALF + 4 * n) = (u32x2){pk2(o[0], o[1]), pk2(o[2], o[3])}; }
.LBB0_515:
	s_andn2_saveexec_b64 s[30:31], s[30:31]
	s_or_b64 exec, exec, s[30:31]
	v_mov_b32_e32 v78, v186
	v_mov_b32_e32 v79, v186
	v_pk_fma_f32 v[78:79], v[36:37], v[78:79], v[68:69]
	v_pk_fma_f32 v[80:81], v[34:35], v[186:187], v[66:67]
	v_mov_b32_dpp v36, v46 row_ror:2 row_mask:0xf bank_mask:0xf
	v_mov_b32_dpp v37, v47 row_ror:2 row_mask:0xf bank_mask:0xf
	v_mov_b32_dpp v34, v46 row_ror:1 row_mask:0xf bank_mask:0xf
	v_mov_b32_dpp v36, v38 row_shr:2 row_mask:0xf bank_mask:0xf
	v_mov_b32_dpp v35, v47 row_ror:1 row_mask:0xf bank_mask:0xf
	v_mov_b32_dpp v37, v39 row_shr:2 row_mask:0xf bank_mask:0xf
	v_mov_b32_dpp v84, v48 row_ror:2 row_mask:0xf bank_mask:0xf
	v_mov_b32_dpp v85, v49 row_ror:2 row_mask:0xf bank_mask:0xf
	v_mov_b32_dpp v34, v38 row_shr:1 row_mask:0xf bank_mask:0xf
	v_mov_b32_dpp v35, v39 row_shr:1 row_mask:0xf bank_mask:0xf
	v_mov_b32_dpp v82, v48 row_ror:1 row_mask:0xf bank_mask:0xf
	v_mov_b32_dpp v84, v40 row_shr:2 row_mask:0xf bank_mask:0xf
	v_mov_b32_dpp v83, v49 row_ror:1 row_mask:0xf bank_mask:0xf
	v_mov_b32_dpp v85, v41 row_shr:2 row_mask:0xf bank_mask:0xf
	s_waitcnt vmcnt(0)
	v_pk_fma_f32 v[36:37], v[50:51], v[36:37], v[74:75]
	v_mov_b32_dpp v82, v40 row_shr:1 row_mask:0xf bank_mask:0xf
	v_mov_b32_dpp v83, v41 row_shr:1 row_mask:0xf bank_mask:0xf
	v_pk_fma_f32 v[34:35], v[54:55], v[34:35], v[36:37]
	v_pk_fma_f32 v[36:37], v[52:53], v[84:85], v[76:77]
	v_mov_b32_dpp v46, v80 row_ror:15 row_mask:0xf bank_mask:0xf
	v_mov_b32_dpp v47, v81 row_ror:15 row_mask:0xf bank_mask:0xf
	v_mov_b32_dpp v48, v78 row_ror:15 row_mask:0xf bank_mask:0xf
	v_mov_b32_dpp v49, v79 row_ror:15 row_mask:0xf bank_mask:0xf
	v_pk_fma_f32 v[36:37], v[56:57], v[82:83], v[36:37]
	v_mov_b32_dpp v46, v38 row_shl:1 row_mask:0xf bank_mask:0xf
	v_mov_b32_dpp v47, v39 row_shl:1 row_mask:0xf bank_mask:0xf
	v_mov_b32_dpp v48, v40 row_shl:1 row_mask:0xf bank_mask:0xf
	v_mov_b32_dpp v49, v41 row_shl:1 row_mask:0xf bank_mask:0xf
	v_pk_fma_f32 v[34:35], v[38:39], v[58:59], v[34:35]
	v_pk_fma_f32 v[36:37], v[40:41], v[60:61], v[36:37]
	v_pk_fma_f32 v[34:35], v[62:63], v[46:47], v[34:35]
	v_pk_fma_f32 v[36:37], v[64:65], v[48:49], v[36:37]
	v_cvt_pk_bf16_f32 v34, v34, v35
	v_cvt_pk_bf16_f32 v35, v36, v37
	v_mov_b32_dpp v48, v38 row_ror:2 row_mask:0xf bank_mask:0xf
	v_mov_b32_dpp v49, v39 row_ror:2 row_mask:0xf bank_mask:0xf
	global_store_dwordx2 v[198:199], v[34:35], off offset:264
	v_mov_b32_dpp v46, v38 row_ror:1 row_mask:0xf bank_mask:0xf
	v_mov_b32_dpp v48, v80 row_shr:2 row_mask:0xf bank_mask:0xf
	v_mov_b32_dpp v47, v39 row_ror:1 row_mask:0xf bank_mask:0xf
	v_mov_b32_dpp v49, v81 row_shr:2 row_mask:0xf bank_mask:0xf
	v_mov_b32_dpp v46, v80 row_shr:1 row_mask:0xf bank_mask:0xf
	v_mov_b32_dpp v34, v42 row_ror:15 row_mask:0xf bank_mask:0xf
	v_mov_b32_dpp v47, v81 row_shr:1 row_mask:0xf bank_mask:0xf
	v_mov_b32_dpp v35, v43 row_ror:15 row_mask:0xf bank_mask:0xf
	v_pk_fma_f32 v[48:49], v[50:51], v[48:49], v[74:75]
	v_mov_b32_e32 v38, v34
	v_mov_b32_e32 v39, v35
	v_mov_b32_dpp v84, v40 row_ror:2 row_mask:0xf bank_mask:0xf
	v_mov_b32_dpp v85, v41 row_ror:2 row_mask:0xf bank_mask:0xf
	v_pk_fma_f32 v[46:47], v[54:55], v[46:47], v[48:49]
	v_mov_b32_dpp v38, v80 row_shl:1 row_mask:0xf bank_mask:0xf
	v_mov_b32_dpp v39, v81 row_shl:1 row_mask:0xf bank_mask:0xf
	v_mov_b32_dpp v82, v40 row_ror:1 row_mask:0xf bank_mask:0xf
	v_mov_b32_dpp v84, v78 row_shr:2 row_mask:0xf bank_mask:0xf
	v_mov_b32_dpp v83, v41 row_ror:1 row_mask:0xf bank_mask:0xf
	v_mov_b32_dpp v85, v79 row_shr:2 row_mask:0xf bank_mask:0xf
	v_pk_fma_f32 v[46:47], v[80:81], v[58:59], v[46:47]
	v_mov_b32_dpp v82, v78 row_shr:1 row_mask:0xf bank_mask:0xf
	v_mov_b32_dpp v36, v44 row_ror:15 row_mask:0xf bank_mask:0xf
	v_mov_b32_dpp v83, v79 row_shr:1 row_mask:0xf bank_mask:0xf
	v_mov_b32_dpp v37, v45 row_ror:15 row_mask:0xf bank_mask:0xf
	v_pk_fma_f32 v[38:39], v[62:63], v[38:39], v[46:47]
	v_pk_fma_f32 v[46:47], v[52:53], v[84:85], v[76:77]
	v_mov_b32_e32 v40, v36
	v_mov_b32_e32 v41, v37
	v_pk_fma_f32 v[46:47], v[56:57], v[82:83], v[46:47]
	v_mov_b32_dpp v40, v78 row_shl:1 row_mask:0xf bank_mask:0xf
	v_mov_b32_dpp v41, v79 row_shl:1 row_mask:0xf bank_mask:0xf
	v_pk_fma_f32 v[46:47], v[78:79], v[60:61], v[46:47]
	v_cvt_pk_bf16_f32 v38, v38, v39
	v_pk_fma_f32 v[40:41], v[64:65], v[40:41], v[46:47]
	v_cvt_pk_bf16_f32 v39, v40, v41
	global_store_dwordx2 v[200:201], v[38:39], off offset:264
	v_mov_b32_dpp v38, v80 row_ror:1 row_mask:0xf bank_mask:0xf
	v_mov_b32_dpp v40, v80 row_ror:2 row_mask:0xf bank_mask:0xf
	v_mov_b32_dpp v39, v81 row_ror:1 row_mask:0xf bank_mask:0xf
	v_mov_b32_dpp v41, v81 row_ror:2 row_mask:0xf bank_mask:0xf
	v_mov_b32_dpp v46, v78 row_ror:1 row_mask:0xf bank_mask:0xf
	v_mov_b32_dpp v48, v78 row_ror:2 row_mask:0xf bank_mask:0xf
	v_mov_b32_dpp v47, v79 row_ror:1 row_mask:0xf bank_mask:0xf
	v_mov_b32_dpp v49, v79 row_ror:2 row_mask:0xf bank_mask:0xf
	v_mov_b32_dpp v38, v42 row_shr:1 row_mask:0xf bank_mask:0xf
	v_mov_b32_dpp v40, v42 row_shr:2 row_mask:0xf bank_mask:0xf
	v_mov_b32_dpp v34, v42 row_shl:1 row_mask:0xf bank_mask:0xf
	v_mov_b32_dpp v39, v43 row_shr:1 row_mask:0xf bank_mask:0xf
	v_mov_b32_dpp v41, v43 row_shr:2 row_mask:0xf bank_mask:0xf
	v_mov_b32_dpp v35, v43 row_shl:1 row_mask:0xf bank_mask:0xf
	v_mov_b32_dpp v46, v44 row_shr:1 row_mask:0xf bank_mask:0xf
	v_mov_b32_dpp v48, v44 row_shr:2 row_mask:0xf bank_mask:0xf
	v_mov_b32_dpp v36, v44 row_shl:1 row_mask:0xf bank_mask:0xf
	v_mov_b32_dpp v47, v45 row_shr:1 row_mask:0xf bank_mask:0xf
	v_mov_b32_dpp v49, v45 row_shr:2 row_mask:0xf bank_mask:0xf
	v_mov_b32_dpp v37, v45 row_shl:1 row_mask:0xf bank_mask:0xf
	s_and_saveexec_b64 s[30:31], s[46:47]
	s_cbranch_execz .LBB0_517
	v_pk_fma_f32 v[40:41], v[50:51], v[40:41], v[74:75]
	v_ashrrev_i32_e32 v167, 31, v166
	v_pk_fma_f32 v[38:39], v[54:55], v[38:39], v[40:41]
	s_nop 0
	v_pk_fma_f32 v[38:39], v[42:43], v[58:59], v[38:39]
	s_nop 0
	v_pk_fma_f32 v[34:35], v[62:63], v[34:35], v[38:39]
	v_pk_fma_f32 v[38:39], v[52:53], v[48:49], v[76:77]
	v_cvt_pk_bf16_f32 v34, v34, v35
	v_pk_fma_f32 v[38:39], v[56:57], v[46:47], v[38:39]
	s_nop 0
	v_pk_fma_f32 v[38:39], v[44:45], v[60:61], v[38:39]
	s_nop 0
	v_pk_fma_f32 v[36:37], v[64:65], v[36:37], v[38:39]
	s_nop 0
	v_cvt_pk_bf16_f32 v35, v36, v37
	v_lshlrev_b64 v[36:37], 11, v[166:167]
	v_lshl_add_u64 v[36:37], s[34:35], 0, v[36:37]
	v_lshl_add_u64 v[36:37], v[158:159], 1, v[36:37]
	global_store_dwordx2 v[36:37], v[34:35], off offset:264

;     template <int QVV> __device__ __forceinline__ void run(f32x4 (&acc)[2][2][4][2], const Unit& u, int wr, int wc, int fr, int fq) const {
;     ...
;                         for (int m = 0; m < 4; ++m) X[m] = acc[ai][bj][m][n] * rs[ai][m] + sh[n];
;                         if (fr <= 2) *(u32x2*)(tb + lo + (unsigned)(ai * HALF) * rs_ + bj * HALF * 2 + n * 8) = (u32x2){pk2(X[0][0], X[0][1]), pk2(X[0][2], X[0][3])};
;                         if (fr >= 13) *(u32x2*)(tb + lo + (unsigned)(ai * HALF + 48) * rs_ + bj * HALF * 2 + n * 8) = (u32x2){pk2(X[3][0], X[3][1]), pk2(X[3][2], X[3][3])};
; #pragma unroll
;                         for (int m = 0; m < 4; ++m) {
;                             const int mp = m > 0 ? m - 1 : 0, mn = m < 3 ? m + 1 : 3;
;                             f32x4 o;
; #pragma unroll
;                             for (int i = 0; i < 4; ++i) {
;                                 const float xif = X[m][i], xpf = X[mp][i], xnf = X[mn][i];
;                                 const int xi = __float_as_int(xif), xp = __float_as_int(xpf), xn = __float_as_int(xnf);
;                                 const float p1 = __builtin_bit_cast(float, __builtin_amdgcn_update_dpp(__builtin_amdgcn_update_dpp(0, xp, 0x121, 0xf, 0xf, false), xi, 0x111, 0xf, 0xf, false));
;                                 const float p2 = __builtin_bit_cast(float, __builtin_amdgcn_update_dpp(__builtin_amdgcn_update_dpp(0, xp, 0x122, 0xf, 0xf, false), xi, 0x112, 0xf, 0xf, false));
;                                 const float n1 = __builtin_bit_cast(float, __builtin_amdgcn_update_dpp(__builtin_amdgcn_update_dpp(0, xn, 0x12f, 0xf, 0xf, false), xi, 0x101, 0xf, 0xf, false));
;                                 o[i] = bb[i] + w0[i] * p2 + w1[i] * p1 + w2[i] * X[m][i] + w3[i] * n1; }
;                             const int r = r0 + wr * 64 + fr + ai * HALF + m * 16;
;                             const bool edge = (m == 0 && fr < 2) || (m == 3 && fr == 15);
;                             if (!edge) *(u32x2*)(XA + (size_t)r * 1024 + c0 + bj * HALF + 4 * n) = (u32x2){pk2(o[0], o[1]), pk2(o[2], o[3])}; }
.LBB0_521:
	s_or_b64 exec, exec, s[30:31]
	v_mov_b32_e32 v54, v172
	v_mov_b32_e32 v55, v172
	v_pk_fma_f32 v[24:25], v[24:25], v[54:55], v[72:73]
	v_pk_fma_f32 v[22:23], v[22:23], v[172:173], v[70:71]
	v_mov_b32_dpp v54, v30 row_ror:1 row_mask:0xf bank_mask:0xf
	v_mov_b32_dpp v56, v30 row_ror:2 row_mask:0xf bank_mask:0xf
	v_mov_b32_dpp v60, v22 row_ror:15 row_mask:0xf bank_mask:0xf
	v_mov_b32_dpp v55, v31 row_ror:1 row_mask:0xf bank_mask:0xf
	v_mov_b32_dpp v57, v31 row_ror:2 row_mask:0xf bank_mask:0xf
	v_mov_b32_dpp v61, v23 row_ror:15 row_mask:0xf bank_mask:0xf
	v_mov_b32_dpp v58, v32 row_ror:1 row_mask:0xf bank_mask:0xf
	v_mov_b32_dpp v62, v32 row_ror:2 row_mask:0xf bank_mask:0xf
	v_mov_b32_dpp v64, v24 row_ror:15 row_mask:0xf bank_mask:0xf
	v_mov_b32_dpp v59, v33 row_ror:1 row_mask:0xf bank_mask:0xf
	v_mov_b32_dpp v63, v33 row_ror:2 row_mask:0xf bank_mask:0xf
	v_mov_b32_dpp v65, v25 row_ror:15 row_mask:0xf bank_mask:0xf
	v_mov_b32_dpp v54, v30 row_shr:1 row_mask:0xf bank_mask:0xf
	v_mov_b32_dpp v56, v30 row_shr:2 row_mask:0xf bank_mask:0xf
	v_mov_b32_dpp v60, v30 row_shl:1 row_mask:0xf bank_mask:0xf
	v_mov_b32_dpp v55, v31 row_shr:1 row_mask:0xf bank_mask:0xf
	v_mov_b32_dpp v57, v31 row_shr:2 row_mask:0xf bank_mask:0xf
	v_mov_b32_dpp v61, v31 row_shl:1 row_mask:0xf bank_mask:0xf
	v_mov_b32_dpp v58, v32 row_shr:1 row_mask:0xf bank_mask:0xf
	v_mov_b32_dpp v62, v32 row_shr:2 row_mask:0xf bank_mask:0xf
	v_mov_b32_dpp v64, v32 row_shl:1 row_mask:0xf bank_mask:0xf
	v_mov_b32_dpp v59, v33 row_shr:1 row_mask:0xf bank_mask:0xf
	v_mov_b32_dpp v63, v33 row_shr:2 row_mask:0xf bank_mask:0xf
	v_mov_b32_dpp v65, v33 row_shl:1 row_mask:0xf bank_mask:0xf
	s_and_saveexec_b64 s[2:3], s[44:45]
	s_xor_b64 s[30:31], exec, s[2:3]
	s_cbranch_execz .LBB0_523
	s_waitcnt vmcnt(0)
	v_pk_fma_f32 v[56:57], v[46:47], v[56:57], v[50:51]
	s_nop 0
	v_pk_fma_f32 v[54:55], v[42:43], v[54:55], v[56:57]
	v_pk_fma_f32 v[56:57], v[48:49], v[62:63], v[52:53]
	v_pk_fma_f32 v[54:55], v[30:31], v[34:35], v[54:55]
	v_pk_fma_f32 v[56:57], v[44:45], v[58:59], v[56:57]
	v_pk_fma_f32 v[54:55], v[38:39], v[60:61], v[54:55]
	v_pk_fma_f32 v[56:57], v[32:33], v[36:37], v[56:57]
	v_cvt_pk_bf16_f32 v54, v54, v55
	v_pk_fma_f32 v[56:57], v[40:41], v[64:65], v[56:57]
	s_nop 0
	v_cvt_pk_bf16_f32 v55, v56, v57
	v_lshlrev_b64 v[56:57], 11, v[120:121]
	v_lshl_add_u64 v[56:57], s[34:35], 0, v[56:57]
	v_lshl_add_u64 v[56:57], v[158:159], 1, v[56:57]
	global_store_dwordx2 v[56:57], v[54:55], off offset:256
;     template <int QVV> __device__ __forceinline__ void run(f32x4 (&acc)[2][2][4][2], const Unit& u, int wr, int wc, int fr, int fq) const {
;     ...
;                         for (int m = 0; m < 4; ++m) X[m] = acc[ai][bj][m][n] * rs[ai][m] + sh[n];
;                         if (fr <= 2) *(u32x2*)(tb + lo + (unsigned)(ai * HALF) * rs_ + bj * HALF * 2 + n * 8) = (u32x2){pk2(X[0][0], X[0][1]), pk2(X[0][2], X[0][3])};
;                         if (fr >= 13) *(u32x2*)(tb + lo + (unsigned)(ai * HALF + 48) * rs_ + bj * HALF * 2 + n * 8) = (u32x2){pk2(X[3][0], X[3][1]), pk2(X[3][2], X[3][3])};
; #pragma unroll
;                         for (int m = 0; m < 4; ++m) {
;                             const int mp = m > 0 ? m - 1 : 0, mn = m < 3 ? m + 1 : 3;
;                             f32x4 o;
; #pragma unroll
;                             for (int i = 0; i < 4; ++i) {
;                                 const float xif = X[m][i], xpf = X[mp][i], xnf = X[mn][i];
;                                 const int xi = __float_as_int(xif), xp = __float_as_int(xpf), xn = __float_as_int(xnf);
;                                 const float p1 = __builtin_bit_cast(float, __builtin_amdgcn_update_dpp(__builtin_amdgcn_update_dpp(0, xp, 0x121, 0xf, 0xf, false), xi, 0x111, 0xf, 0xf, false));
;                                 const float p2 = __builtin_bit_cast(float, __builtin_amdgcn_update_dpp(__builtin_amdgcn_update_dpp(0, xp, 0x122, 0xf, 0xf, false), xi, 0x112, 0xf, 0xf, false));
;                                 const float n1 = __builtin_bit_cast(float, __builtin_amdgcn_update_dpp(__builtin_amdgcn_update_dpp(0, xn, 0x12f, 0xf, 0xf, false), xi, 0x101, 0xf, 0xf, false));
;                                 o[i] = bb[i] + w0[i] * p2 + w1[i] * p1 + w2[i] * X[m][i] + w3[i] * n1; }
;                             const int r = r0 + wr * 64 + fr + ai * HALF + m * 16;
;                             const bool edge = (m == 0 && fr < 2) || (m == 3 && fr == 15);
;                             if (!edge) *(u32x2*)(XA + (size_t)r * 1024 + c0 + bj * HALF + 4 * n) = (u32x2){pk2(o[0], o[1]), pk2(o[2], o[3])}; }
.LBB0_523:
	s_andn2_saveexec_b64 s[30:31], s[30:31]
	s_or_b64 exec, exec, s[30:31]
	v_mov_b32_e32 v54, v170
	v_mov_b32_e32 v55, v170
	v_pk_fma_f32 v[54:55], v[20:21], v[54:55], v[72:73]
	v_pk_fma_f32 v[56:57], v[18:19], v[170:171], v[70:71]
	v_mov_b32_dpp v20, v30 row_ror:2 row_mask:0xf bank_mask:0xf
	v_mov_b32_dpp v21, v31 row_ror:2 row_mask:0xf bank_mask:0xf
	v_mov_b32_dpp v18, v30 row_ror:1 row_mask:0xf bank_mask:0xf
	v_mov_b32_dpp v20, v22 row_shr:2 row_mask:0xf bank_mask:0xf
	v_mov_b32_dpp v19, v31 row_ror:1 row_mask:0xf bank_mask:0xf
	v_mov_b32_dpp v21, v23 row_shr:2 row_mask:0xf bank_mask:0xf
	v_mov_b32_dpp v60, v32 row_ror:2 row_mask:0xf bank_mask:0xf
	v_mov_b32_dpp v61, v33 row_ror:2 row_mask:0xf bank_mask:0xf
	v_mov_b32_dpp v18, v22 row_shr:1 row_mask:0xf bank_mask:0xf
	v_mov_b32_dpp v19, v23 row_shr:1 row_mask:0xf bank_mask:0xf
	v_mov_b32_dpp v58, v32 row_ror:1 row_mask:0xf bank_mask:0xf
	v_mov_b32_dpp v60, v24 row_shr:2 row_mask:0xf bank_mask:0xf
	v_mov_b32_dpp v59, v33 row_ror:1 row_mask:0xf bank_mask:0xf
	v_mov_b32_dpp v61, v25 row_shr:2 row_mask:0xf bank_mask:0xf
	s_waitcnt vmcnt(0)
	v_pk_fma_f32 v[20:21], v[46:47], v[20:21], v[50:51]
	v_mov_b32_dpp v58, v24 row_shr:1 row_mask:0xf bank_mask:0xf
	v_mov_b32_dpp v59, v25 row_shr:1 row_mask:0xf bank_mask:0xf
	v_pk_fma_f32 v[18:19], v[42:43], v[18:19], v[20:21]
	v_pk_fma_f32 v[20:21], v[48:49], v[60:61], v[52:53]
	v_mov_b32_dpp v30, v56 row_ror:15 row_mask:0xf bank_mask:0xf
	v_mov_b32_dpp v31, v57 row_ror:15 row_mask:0xf bank_mask:0xf
	v_mov_b32_dpp v32, v54 row_ror:15 row_mask:0xf bank_mask:0xf
	v_mov_b32_dpp v33, v55 row_ror:15 row_mask:0xf bank_mask:0xf
	v_pk_fma_f32 v[20:21], v[44:45], v[58:59], v[20:21]
	v_mov_b32_dpp v30, v22 row_shl:1 row_mask:0xf bank_mask:0xf
	v_mov_b32_dpp v31, v23 row_shl:1 row_mask:0xf bank_mask:0xf
	v_mov_b32_dpp v32, v24 row_shl:1 row_mask:0xf bank_mask:0xf
	v_mov_b32_dpp v33, v25 row_shl:1 row_mask:0xf bank_mask:0xf
	v_pk_fma_f32 v[18:19], v[22:23], v[34:35], v[18:19]
	v_pk_fma_f32 v[20:21], v[24:25], v[36:37], v[20:21]
	v_pk_fma_f32 v[18:19], v[38:39], v[30:31], v[18:19]
	v_pk_fma_f32 v[20:21], v[40:41], v[32:33], v[20:21]
	v_cvt_pk_bf16_f32 v18, v18, v19
	v_cvt_pk_bf16_f32 v19, v20, v21
	v_mov_b32_dpp v32, v22 row_ror:2 row_mask:0xf bank_mask:0xf
	v_mov_b32_dpp v33, v23 row_ror:2 row_mask:0xf bank_mask:0xf
	global_store_dwordx2 v[104:105], v[18:19], off offset:256
	v_mov_b32_dpp v30, v22 row_ror:1 row_mask:0xf bank_mask:0xf
	v_mov_b32_dpp v32, v56 row_shr:2 row_mask:0xf bank_mask:0xf
	v_mov_b32_dpp v31, v23 row_ror:1 row_mask:0xf bank_mask:0xf
	v_mov_b32_dpp v33, v57 row_shr:2 row_mask:0xf bank_mask:0xf
	v_mov_b32_dpp v30, v56 row_shr:1 row_mask:0xf bank_mask:0xf
	v_mov_b32_dpp v18, v26 row_ror:15 row_mask:0xf bank_mask:0xf
	v_mov_b32_dpp v31, v57 row_shr:1 row_mask:0xf bank_mask:0xf
	v_mov_b32_dpp v19, v27 row_ror:15 row_mask:0xf bank_mask:0xf
	v_pk_fma_f32 v[32:33], v[46:47], v[32:33], v[50:51]
	v_mov_b32_e32 v22, v18
	v_mov_b32_e32 v23, v19
	v_mov_b32_dpp v60, v24 row_ror:2 row_mask:0xf bank_mask:0xf
	v_mov_b32_dpp v61, v25 row_ror:2 row_mask:0xf bank_mask:0xf
	v_pk_fma_f32 v[30:31], v[42:43], v[30:31], v[32:33]
	v_mov_b32_dpp v22, v56 row_shl:1 row_mask:0xf bank_mask:0xf
	v_mov_b32_dpp v23, v57 row_shl:1 row_mask:0xf bank_mask:0xf
	v_mov_b32_dpp v58, v24 row_ror:1 row_mask:0xf bank_mask:0xf
	v_mov_b32_dpp v60, v54 row_shr:2 row_mask:0xf bank_mask:0xf
	v_mov_b32_dpp v59, v25 row_ror:1 row_mask:0xf bank_mask:0xf
	v_mov_b32_dpp v61, v55 row_shr:2 row_mask:0xf bank_mask:0xf
	v_pk_fma_f32 v[30:31], v[56:57], v[34:35], v[30:31]
	v_mov_b32_dpp v58, v54 row_shr:1 row_mask:0xf bank_mask:0xf
	v_mov_b32_dpp v20, v28 row_ror:15 row_mask:0xf bank_mask:0xf
	v_mov_b32_dpp v59, v55 row_shr:1 row_mask:0xf bank_mask:0xf
	v_mov_b32_dpp v21, v29 row_ror:15 row_mask:0xf bank_mask:0xf
	v_pk_fma_f32 v[22:23], v[38:39], v[22:23], v[30:31]
	v_pk_fma_f32 v[30:31], v[48:49], v[60:61], v[52:53]
	v_mov_b32_e32 v24, v20
	v_mov_b32_e32 v25, v21
	v_pk_fma_f32 v[30:31], v[44:45], v[58:59], v[30:31]
	v_mov_b32_dpp v24, v54 row_shl:1 row_mask:0xf bank_mask:0xf
	v_mov_b32_dpp v25, v55 row_shl:1 row_mask:0xf bank_mask:0xf
	v_pk_fma_f32 v[30:31], v[54:55], v[36:37], v[30:31]
	v_cvt_pk_bf16_f32 v22, v22, v23
	v_pk_fma_f32 v[24:25], v[40:41], v[24:25], v[30:31]
	v_cvt_pk_bf16_f32 v23, v24, v25
	global_store_dwordx2 v[102:103], v[22:23], off offset:256
	v_mov_b32_dpp v22, v56 row_ror:1 row_mask:0xf bank_mask:0xf
	v_mov_b32_dpp v24, v56 row_ror:2 row_mask:0xf bank_mask:0xf
	v_mov_b32_dpp v23, v57 row_ror:1 row_mask:0xf bank_mask:0xf
	v_mov_b32_dpp v25, v57 row_ror:2 row_mask:0xf bank_mask:0xf
	v_mov_b32_dpp v30, v54 row_ror:1 row_mask:0xf bank_mask:0xf
	v_mov_b32_dpp v32, v54 row_ror:2 row_mask:0xf bank_mask:0xf
	v_mov_b32_dpp v31, v55 row_ror:1 row_mask:0xf bank_mask:0xf
	v_mov_b32_dpp v33, v55 row_ror:2 row_mask:0xf bank_mask:0xf
	v_mov_b32_dpp v22, v26 row_shr:1 row_mask:0xf bank_mask:0xf
	v_mov_b32_dpp v24, v26 row_shr:2 row_mask:0xf bank_mask:0xf
	v_mov_b32_dpp v18, v26 row_shl:1 row_mask:0xf bank_mask:0xf
	v_mov_b32_dpp v23, v27 row_shr:1 row_mask:0xf bank_mask:0xf
	v_mov_b32_dpp v25, v27 row_shr:2 row_mask:0xf bank_mask:0xf
	v_mov_b32_dpp v19, v27 row_shl:1 row_mask:0xf bank_mask:0xf
	v_mov_b32_dpp v30, v28 row_shr:1 row_mask:0xf bank_mask:0xf
	v_mov_b32_dpp v32, v28 row_shr:2 row_mask:0xf bank_mask:0xf
	v_mov_b32_dpp v20, v28 row_shl:1 row_mask:0xf bank_mask:0xf
	v_mov_b32_dpp v31, v29 row_shr:1 row_mask:0xf bank_mask:0xf
	v_mov_b32_dpp v33, v29 row_shr:2 row_mask:0xf bank_mask:0xf
	v_mov_b32_dpp v21, v29 row_shl:1 row_mask:0xf bank_mask:0xf
	s_and_saveexec_b64 s[30:31], s[46:47]
	s_cbranch_execz .LBB0_525
	v_pk_fma_f32 v[24:25], v[46:47], v[24:25], v[50:51]
	s_nop 0
	v_pk_fma_f32 v[22:23], v[42:43], v[22:23], v[24:25]
	s_nop 0
	v_pk_fma_f32 v[22:23], v[26:27], v[34:35], v[22:23]
	s_nop 0
	v_pk_fma_f32 v[18:19], v[38:39], v[18:19], v[22:23]
	v_pk_fma_f32 v[22:23], v[48:49], v[32:33], v[52:53]
	v_cvt_pk_bf16_f32 v18, v18, v19
	v_pk_fma_f32 v[22:23], v[44:45], v[30:31], v[22:23]
	s_nop 0
	v_pk_fma_f32 v[22:23], v[28:29], v[36:37], v[22:23]
	s_nop 0
	v_pk_fma_f32 v[20:21], v[40:41], v[20:21], v[22:23]
	s_nop 0
	v_cvt_pk_bf16_f32 v19, v20, v21
	v_add_co_u32_e32 v20, vcc, 0x58000, v118
	s_nop 1
	v_addc_co_u32_e32 v21, vcc, 0, v119, vcc
	global_store_dwordx2 v[20:21], v[18:19], off offset:256

;     template <int QVV> __device__ __forceinline__ void run(f32x4 (&acc)[2][2][4][2], const Unit& u, int wr, int wc, int fr, int fq) const {
;     ...
;                         for (int m = 0; m < 4; ++m) X[m] = acc[ai][bj][m][n] * rs[ai][m] + sh[n];
;                         if (fr <= 2) *(u32x2*)(tb + lo + (unsigned)(ai * HALF) * rs_ + bj * HALF * 2 + n * 8) = (u32x2){pk2(X[0][0], X[0][1]), pk2(X[0][2], X[0][3])};
;                         if (fr >= 13) *(u32x2*)(tb + lo + (unsigned)(ai * HALF + 48) * rs_ + bj * HALF * 2 + n * 8) = (u32x2){pk2(X[3][0], X[3][1]), pk2(X[3][2], X[3][3])};
; #pragma unroll
;                         for (int m = 0; m < 4; ++m) {
;                             const int mp = m > 0 ? m - 1 : 0, mn = m < 3 ? m + 1 : 3;
;                             f32x4 o;
; #pragma unroll
;                             for (int i = 0; i < 4; ++i) {
;                                 const float xif = X[m][i], xpf = X[mp][i], xnf = X[mn][i];
;                                 const int xi = __float_as_int(xif), xp = __float_as_int(xpf), xn = __float_as_int(xnf);
;                                 const float p1 = __builtin_bit_cast(float, __builtin_amdgcn_update_dpp(__builtin_amdgcn_update_dpp(0, xp, 0x121, 0xf, 0xf, false), xi, 0x111, 0xf, 0xf, false));
;                                 const float p2 = __builtin_bit_cast(float, __builtin_amdgcn_update_dpp(__builtin_amdgcn_update_dpp(0, xp, 0x122, 0xf, 0xf, false), xi, 0x112, 0xf, 0xf, false));
;                                 const float n1 = __builtin_bit_cast(float, __builtin_amdgcn_update_dpp(__builtin_amdgcn_update_dpp(0, xn, 0x12f, 0xf, 0xf, false), xi, 0x101, 0xf, 0xf, false));
;                                 o[i] = bb[i] + w0[i] * p2 + w1[i] * p1 + w2[i] * X[m][i] + w3[i] * n1; }
;                             const int r = r0 + wr * 64 + fr + ai * HALF + m * 16;
;                             const bool edge = (m == 0 && fr < 2) || (m == 3 && fr == 15);
;                             if (!edge) *(u32x2*)(XA + (size_t)r * 1024 + c0 + bj * HALF + 4 * n) = (u32x2){pk2(o[0], o[1]), pk2(o[2], o[3])}; }
.LBB0_529:
	s_or_b64 exec, exec, s[30:31]
	v_mov_b32_e32 v38, v172
	v_mov_b32_e32 v39, v172
	v_pk_fma_f32 v[12:13], v[12:13], v[38:39], v[68:69]
	v_pk_fma_f32 v[10:11], v[10:11], v[172:173], v[66:67]
	v_mov_b32_dpp v38, v14 row_ror:1 row_mask:0xf bank_mask:0xf
	v_mov_b32_dpp v40, v14 row_ror:2 row_mask:0xf bank_mask:0xf
	v_mov_b32_dpp v44, v10 row_ror:15 row_mask:0xf bank_mask:0xf
	v_mov_b32_dpp v39, v15 row_ror:1 row_mask:0xf bank_mask:0xf
	v_mov_b32_dpp v41, v15 row_ror:2 row_mask:0xf bank_mask:0xf
	v_mov_b32_dpp v45, v11 row_ror:15 row_mask:0xf bank_mask:0xf
	v_mov_b32_dpp v42, v16 row_ror:1 row_mask:0xf bank_mask:0xf
	v_mov_b32_dpp v46, v16 row_ror:2 row_mask:0xf bank_mask:0xf
	v_mov_b32_dpp v48, v12 row_ror:15 row_mask:0xf bank_mask:0xf
	v_mov_b32_dpp v43, v17 row_ror:1 row_mask:0xf bank_mask:0xf
	v_mov_b32_dpp v47, v17 row_ror:2 row_mask:0xf bank_mask:0xf
	v_mov_b32_dpp v49, v13 row_ror:15 row_mask:0xf bank_mask:0xf
	v_mov_b32_dpp v38, v14 row_shr:1 row_mask:0xf bank_mask:0xf
	v_mov_b32_dpp v40, v14 row_shr:2 row_mask:0xf bank_mask:0xf
	v_mov_b32_dpp v44, v14 row_shl:1 row_mask:0xf bank_mask:0xf
	v_mov_b32_dpp v39, v15 row_shr:1 row_mask:0xf bank_mask:0xf
	v_mov_b32_dpp v41, v15 row_shr:2 row_mask:0xf bank_mask:0xf
	v_mov_b32_dpp v45, v15 row_shl:1 row_mask:0xf bank_mask:0xf
	v_mov_b32_dpp v42, v16 row_shr:1 row_mask:0xf bank_mask:0xf
	v_mov_b32_dpp v46, v16 row_shr:2 row_mask:0xf bank_mask:0xf
	v_mov_b32_dpp v48, v16 row_shl:1 row_mask:0xf bank_mask:0xf
	v_mov_b32_dpp v43, v17 row_shr:1 row_mask:0xf bank_mask:0xf
	v_mov_b32_dpp v47, v17 row_shr:2 row_mask:0xf bank_mask:0xf
	v_mov_b32_dpp v49, v17 row_shl:1 row_mask:0xf bank_mask:0xf
	s_and_saveexec_b64 s[2:3], s[44:45]
	s_xor_b64 s[30:31], exec, s[2:3]
	s_cbranch_execz .LBB0_531
	s_waitcnt vmcnt(0)
	v_pk_fma_f32 v[40:41], v[30:31], v[40:41], v[34:35]
	s_nop 0
	v_pk_fma_f32 v[38:39], v[26:27], v[38:39], v[40:41]
	v_pk_fma_f32 v[40:41], v[32:33], v[46:47], v[36:37]
	v_pk_fma_f32 v[38:39], v[14:15], v[18:19], v[38:39]
	v_pk_fma_f32 v[40:41], v[28:29], v[42:43], v[40:41]
	v_pk_fma_f32 v[38:39], v[22:23], v[44:45], v[38:39]
	v_pk_fma_f32 v[40:41], v[16:17], v[20:21], v[40:41]
	v_cvt_pk_bf16_f32 v38, v38, v39
	v_pk_fma_f32 v[40:41], v[24:25], v[48:49], v[40:41]
	s_nop 0
	v_cvt_pk_bf16_f32 v39, v40, v41
	v_lshlrev_b64 v[40:41], 11, v[120:121]
	v_lshl_add_u64 v[40:41], s[34:35], 0, v[40:41]
	v_lshl_add_u64 v[40:41], v[158:159], 1, v[40:41]
	global_store_dwordx2 v[40:41], v[38:39], off offset:264
;     template <int QVV> __device__ __forceinline__ void run(f32x4 (&acc)[2][2][4][2], const Unit& u, int wr, int wc, int fr, int fq) const {
;     ...
;                         for (int m = 0; m < 4; ++m) X[m] = acc[ai][bj][m][n] * rs[ai][m] + sh[n];
;                         if (fr <= 2) *(u32x2*)(tb + lo + (unsigned)(ai * HALF) * rs_ + bj * HALF * 2 + n * 8) = (u32x2){pk2(X[0][0], X[0][1]), pk2(X[0][2], X[0][3])};
;                         if (fr >= 13) *(u32x2*)(tb + lo + (unsigned)(ai * HALF + 48) * rs_ + bj * HALF * 2 + n * 8) = (u32x2){pk2(X[3][0], X[3][1]), pk2(X[3][2], X[3][3])};
; #pragma unroll
;                         for (int m = 0; m < 4; ++m) {
;                             const int mp = m > 0 ? m - 1 : 0, mn = m < 3 ? m + 1 : 3;
;                             f32x4 o;
; #pragma unroll
;                             for (int i = 0; i < 4; ++i) {
;                                 const float xif = X[m][i], xpf = X[mp][i], xnf = X[mn][i];
;                                 const int xi = __float_as_int(xif), xp = __float_as_int(xpf), xn = __float_as_int(xnf);
;                                 const float p1 = __builtin_bit_cast(float, __builtin_amdgcn_update_dpp(__builtin_amdgcn_update_dpp(0, xp, 0x121, 0xf, 0xf, false), xi, 0x111, 0xf, 0xf, false));
;                                 const float p2 = __builtin_bit_cast(float, __builtin_amdgcn_update_dpp(__builtin_amdgcn_update_dpp(0, xp, 0x122, 0xf, 0xf, false), xi, 0x112, 0xf, 0xf, false));
;                                 const float n1 = __builtin_bit_cast(float, __builtin_amdgcn_update_dpp(__builtin_amdgcn_update_dpp(0, xn, 0x12f, 0xf, 0xf, false), xi, 0x101, 0xf, 0xf, false));
;                                 o[i] = bb[i] + w0[i] * p2 + w1[i] * p1 + w2[i] * X[m][i] + w3[i] * n1; }
;                             const int r = r0 + wr * 64 + fr + ai * HALF + m * 16;
;                             const bool edge = (m == 0 && fr < 2) || (m == 3 && fr == 15);
;                             if (!edge) *(u32x2*)(XA + (size_t)r * 1024 + c0 + bj * HALF + 4 * n) = (u32x2){pk2(o[0], o[1]), pk2(o[2], o[3])}; }
.LBB0_531:
	s_andn2_saveexec_b64 s[30:31], s[30:31]
	s_or_b64 exec, exec, s[30:31]
	v_mov_b32_e32 v38, v170
	v_mov_b32_e32 v39, v170
	v_pk_fma_f32 v[38:39], v[4:5], v[38:39], v[68:69]
	v_pk_fma_f32 v[40:41], v[2:3], v[170:171], v[66:67]
	v_mov_b32_dpp v4, v14 row_ror:2 row_mask:0xf bank_mask:0xf
	v_mov_b32_dpp v5, v15 row_ror:2 row_mask:0xf bank_mask:0xf
	v_mov_b32_dpp v2, v14 row_ror:1 row_mask:0xf bank_mask:0xf
	v_mov_b32_dpp v4, v10 row_shr:2 row_mask:0xf bank_mask:0xf
	v_mov_b32_dpp v3, v15 row_ror:1 row_mask:0xf bank_mask:0xf
	v_mov_b32_dpp v5, v11 row_shr:2 row_mask:0xf bank_mask:0xf
	v_mov_b32_dpp v44, v16 row_ror:2 row_mask:0xf bank_mask:0xf
	v_mov_b32_dpp v45, v17 row_ror:2 row_mask:0xf bank_mask:0xf
	v_mov_b32_dpp v2, v10 row_shr:1 row_mask:0xf bank_mask:0xf
	v_mov_b32_dpp v3, v11 row_shr:1 row_mask:0xf bank_mask:0xf
	v_mov_b32_dpp v42, v16 row_ror:1 row_mask:0xf bank_mask:0xf
	v_mov_b32_dpp v44, v12 row_shr:2 row_mask:0xf bank_mask:0xf
	v_mov_b32_dpp v43, v17 row_ror:1 row_mask:0xf bank_mask:0xf
	v_mov_b32_dpp v45, v13 row_shr:2 row_mask:0xf bank_mask:0xf
	s_waitcnt vmcnt(0)
	v_pk_fma_f32 v[4:5], v[30:31], v[4:5], v[34:35]
	v_mov_b32_dpp v42, v12 row_shr:1 row_mask:0xf bank_mask:0xf
	v_mov_b32_dpp v43, v13 row_shr:1 row_mask:0xf bank_mask:0xf
	v_pk_fma_f32 v[2:3], v[26:27], v[2:3], v[4:5]
	v_pk_fma_f32 v[4:5], v[32:33], v[44:45], v[36:37]
	v_mov_b32_dpp v14, v40 row_ror:15 row_mask:0xf bank_mask:0xf
	v_mov_b32_dpp v15, v41 row_ror:15 row_mask:0xf bank_mask:0xf
	v_mov_b32_dpp v16, v38 row_ror:15 row_mask:0xf bank_mask:0xf
	v_mov_b32_dpp v17, v39 row_ror:15 row_mask:0xf bank_mask:0xf
	v_pk_fma_f32 v[4:5], v[28:29], v[42:43], v[4:5]
	v_mov_b32_dpp v14, v10 row_shl:1 row_mask:0xf bank_mask:0xf
	v_mov_b32_dpp v15, v11 row_shl:1 row_mask:0xf bank_mask:0xf
	v_mov_b32_dpp v16, v12 row_shl:1 row_mask:0xf bank_mask:0xf
	v_mov_b32_dpp v17, v13 row_shl:1 row_mask:0xf bank_mask:0xf
	v_pk_fma_f32 v[2:3], v[10:11], v[18:19], v[2:3]
	v_pk_fma_f32 v[4:5], v[12:13], v[20:21], v[4:5]
	v_pk_fma_f32 v[2:3], v[22:23], v[14:15], v[2:3]
	v_pk_fma_f32 v[4:5], v[24:25], v[16:17], v[4:5]
	v_cvt_pk_bf16_f32 v2, v2, v3
	v_cvt_pk_bf16_f32 v3, v4, v5
	v_mov_b32_dpp v16, v10 row_ror:2 row_mask:0xf bank_mask:0xf
	v_mov_b32_dpp v17, v11 row_ror:2 row_mask:0xf bank_mask:0xf
	global_store_dwordx2 v[104:105], v[2:3], off offset:264
	v_mov_b32_dpp v14, v10 row_ror:1 row_mask:0xf bank_mask:0xf
	v_mov_b32_dpp v16, v40 row_shr:2 row_mask:0xf bank_mask:0xf
	v_mov_b32_dpp v15, v11 row_ror:1 row_mask:0xf bank_mask:0xf
	v_mov_b32_dpp v17, v41 row_shr:2 row_mask:0xf bank_mask:0xf
	v_mov_b32_dpp v14, v40 row_shr:1 row_mask:0xf bank_mask:0xf
	v_mov_b32_dpp v2, v6 row_ror:15 row_mask:0xf bank_mask:0xf
	v_mov_b32_dpp v15, v41 row_shr:1 row_mask:0xf bank_mask:0xf
	v_mov_b32_dpp v3, v7 row_ror:15 row_mask:0xf bank_mask:0xf
	v_pk_fma_f32 v[16:17], v[30:31], v[16:17], v[34:35]
	v_mov_b32_e32 v10, v2
	v_mov_b32_e32 v11, v3
	v_mov_b32_dpp v44, v12 row_ror:2 row_mask:0xf bank_mask:0xf
	v_mov_b32_dpp v45, v13 row_ror:2 row_mask:0xf bank_mask:0xf
	v_pk_fma_f32 v[14:15], v[26:27], v[14:15], v[16:17]
	v_mov_b32_dpp v10, v40 row_shl:1 row_mask:0xf bank_mask:0xf
	v_mov_b32_dpp v11, v41 row_shl:1 row_mask:0xf bank_mask:0xf
	v_mov_b32_dpp v42, v12 row_ror:1 row_mask:0xf bank_mask:0xf
	v_mov_b32_dpp v44, v38 row_shr:2 row_mask:0xf bank_mask:0xf
	v_mov_b32_dpp v43, v13 row_ror:1 row_mask:0xf bank_mask:0xf
	v_mov_b32_dpp v45, v39 row_shr:2 row_mask:0xf bank_mask:0xf
	v_pk_fma_f32 v[14:15], v[40:41], v[18:19], v[14:15]
	v_mov_b32_dpp v42, v38 row_shr:1 row_mask:0xf bank_mask:0xf
	v_mov_b32_dpp v4, v8 row_ror:15 row_mask:0xf bank_mask:0xf
	v_mov_b32_dpp v43, v39 row_shr:1 row_mask:0xf bank_mask:0xf
	v_mov_b32_dpp v5, v9 row_ror:15 row_mask:0xf bank_mask:0xf
	v_pk_fma_f32 v[10:11], v[22:23], v[10:11], v[14:15]
	v_pk_fma_f32 v[14:15], v[32:33], v[44:45], v[36:37]
	v_mov_b32_e32 v12, v4
	v_mov_b32_e32 v13, v5
	v_pk_fma_f32 v[14:15], v[28:29], v[42:43], v[14:15]
	v_mov_b32_dpp v12, v38 row_shl:1 row_mask:0xf bank_mask:0xf
	v_mov_b32_dpp v13, v39 row_shl:1 row_mask:0xf bank_mask:0xf
	v_pk_fma_f32 v[14:15], v[38:39], v[20:21], v[14:15]
	v_cvt_pk_bf16_f32 v10, v10, v11
	v_pk_fma_f32 v[12:13], v[24:25], v[12:13], v[14:15]
	v_cvt_pk_bf16_f32 v11, v12, v13
	global_store_dwordx2 v[102:103], v[10:11], off offset:264
	v_mov_b32_dpp v10, v40 row_ror:1 row_mask:0xf bank_mask:0xf
	v_mov_b32_dpp v12, v40 row_ror:2 row_mask:0xf bank_mask:0xf
	v_mov_b32_dpp v11, v41 row_ror:1 row_mask:0xf bank_mask:0xf
	v_mov_b32_dpp v13, v41 row_ror:2 row_mask:0xf bank_mask:0xf
	v_mov_b32_dpp v14, v38 row_ror:1 row_mask:0xf bank_mask:0xf
	v_mov_b32_dpp v16, v38 row_ror:2 row_mask:0xf bank_mask:0xf
	v_mov_b32_dpp v15, v39 row_ror:1 row_mask:0xf bank_mask:0xf
	v_mov_b32_dpp v17, v39 row_ror:2 row_mask:0xf bank_mask:0xf
	v_mov_b32_dpp v10, v6 row_shr:1 row_mask:0xf bank_mask:0xf
	v_mov_b32_dpp v12, v6 row_shr:2 row_mask:0xf bank_mask:0xf
	v_mov_b32_dpp v2, v6 row_shl:1 row_mask:0xf bank_mask:0xf
	v_mov_b32_dpp v11, v7 row_shr:1 row_mask:0xf bank_mask:0xf
	v_mov_b32_dpp v13, v7 row_shr:2 row_mask:0xf bank_mask:0xf
	v_mov_b32_dpp v3, v7 row_shl:1 row_mask:0xf bank_mask:0xf
	v_mov_b32_dpp v14, v8 row_shr:1 row_mask:0xf bank_mask:0xf
	v_mov_b32_dpp v16, v8 row_shr:2 row_mask:0xf bank_mask:0xf
	v_mov_b32_dpp v4, v8 row_shl:1 row_mask:0xf bank_mask:0xf
	v_mov_b32_dpp v15, v9 row_shr:1 row_mask:0xf bank_mask:0xf
	v_mov_b32_dpp v17, v9 row_shr:2 row_mask:0xf bank_mask:0xf
	v_mov_b32_dpp v5, v9 row_shl:1 row_mask:0xf bank_mask:0xf
	s_and_saveexec_b64 s[30:31], s[46:47]
	s_cbranch_execz .LBB0_533
	v_pk_fma_f32 v[12:13], v[30:31], v[12:13], v[34:35]
	s_nop 0
	v_pk_fma_f32 v[10:11], v[26:27], v[10:11], v[12:13]
	s_nop 0
	v_pk_fma_f32 v[6:7], v[6:7], v[18:19], v[10:11]
	s_nop 0
	v_pk_fma_f32 v[2:3], v[22:23], v[2:3], v[6:7]
	v_pk_fma_f32 v[6:7], v[32:33], v[16:17], v[36:37]
	v_cvt_pk_bf16_f32 v2, v2, v3
	v_pk_fma_f32 v[6:7], v[28:29], v[14:15], v[6:7]
	s_nop 0
	v_pk_fma_f32 v[6:7], v[8:9], v[20:21], v[6:7]
	s_nop 0
	v_pk_fma_f32 v[4:5], v[24:25], v[4:5], v[6:7]
	s_nop 0
	v_cvt_pk_bf16_f32 v3, v4, v5
	v_add_co_u32_e32 v4, vcc, 0x58000, v118
	s_nop 1
	v_addc_co_u32_e32 v5, vcc, 0, v119, vcc
	global_store_dwordx2 v[4:5], v[2:3], off offset:264

;     template <int QVV> __device__ __forceinline__ void run(f32x4 (&acc)[2][2][4][2], const Unit& u, int wr, int wc, int fr, int fq) const {
;     ...
;                         for (int m = 0; m < 4; ++m) X[m] = acc[ai][bj][m][n] * rs[ai][m] + sh[n];
;                         if (fr <= 2) *(u32x2*)(tb + lo + (unsigned)(ai * HALF) * rs_ + bj * HALF * 2 + n * 8) = (u32x2){pk2(X[0][0], X[0][1]), pk2(X[0][2], X[0][3])};
;                         if (fr >= 13) *(u32x2*)(tb + lo + (unsigned)(ai * HALF + 48) * rs_ + bj * HALF * 2 + n * 8) = (u32x2){pk2(X[3][0], X[3][1]), pk2(X[3][2], X[3][3])};
; #pragma unroll
;                         for (int m = 0; m < 4; ++m) {
;                             const int mp = m > 0 ? m - 1 : 0, mn = m < 3 ? m + 1 : 3;
;                             f32x4 o;
; #pragma unroll
;                             for (int i = 0; i < 4; ++i) {
;                                 const float xif = X[m][i], xpf = X[mp][i], xnf = X[mn][i];
;                                 const int xi = __float_as_int(xif), xp = __float_as_int(xpf), xn = __float_as_int(xnf);
;                                 const float p1 = __builtin_bit_cast(float, __builtin_amdgcn_update_dpp(__builtin_amdgcn_update_dpp(0, xp, 0x121, 0xf, 0xf, false), xi, 0x111, 0xf, 0xf, false));
;                                 const float p2 = __builtin_bit_cast(float, __builtin_amdgcn_update_dpp(__builtin_amdgcn_update_dpp(0, xp, 0x122, 0xf, 0xf, false), xi, 0x112, 0xf, 0xf, false));
;                                 const float n1 = __builtin_bit_cast(float, __builtin_amdgcn_update_dpp(__builtin_amdgcn_update_dpp(0, xn, 0x12f, 0xf, 0xf, false), xi, 0x101, 0xf, 0xf, false));
;                                 o[i] = bb[i] + w0[i] * p2 + w1[i] * p1 + w2[i] * X[m][i] + w3[i] * n1; }
;                             const int r = r0 + wr * 64 + fr + ai * HALF + m * 16;
;                             const bool edge = (m == 0 && fr < 2) || (m == 3 && fr == 15);
;                             if (!edge) *(u32x2*)(XA + (size_t)r * 1024 + c0 + bj * HALF + 4 * n) = (u32x2){pk2(o[0], o[1]), pk2(o[2], o[3])}; }
.LBB0_570:
	s_or_b64 exec, exec, s[30:31]
	v_pk_fma_f32 v[56:57], v[56:57], v[106:107], v[92:93] op_sel_hi:[1,0,1]
	v_pk_fma_f32 v[54:55], v[54:55], v[106:107], v[90:91] op_sel_hi:[1,0,1]
	v_mov_b32_dpp v64, v116 row_ror:1 row_mask:0xf bank_mask:0xf
	v_mov_b32_dpp v118, v116 row_ror:2 row_mask:0xf bank_mask:0xf
	v_mov_b32_dpp v122, v54 row_ror:15 row_mask:0xf bank_mask:0xf
	v_mov_b32_dpp v65, v117 row_ror:1 row_mask:0xf bank_mask:0xf
	v_mov_b32_dpp v119, v117 row_ror:2 row_mask:0xf bank_mask:0xf
	v_mov_b32_dpp v123, v55 row_ror:15 row_mask:0xf bank_mask:0xf
	v_mov_b32_dpp v120, v62 row_ror:1 row_mask:0xf bank_mask:0xf
	v_mov_b32_dpp v124, v62 row_ror:2 row_mask:0xf bank_mask:0xf
	v_mov_b32_dpp v126, v56 row_ror:15 row_mask:0xf bank_mask:0xf
	v_mov_b32_dpp v121, v63 row_ror:1 row_mask:0xf bank_mask:0xf
	v_mov_b32_dpp v125, v63 row_ror:2 row_mask:0xf bank_mask:0xf
	v_mov_b32_dpp v127, v57 row_ror:15 row_mask:0xf bank_mask:0xf
	v_lshlrev_b64 v[96:97], 11, v[114:115]
	v_cmp_lt_u32_e64 s[40:41], 1, v105
	v_mov_b32_dpp v64, v116 row_shr:1 row_mask:0xf bank_mask:0xf
	v_mov_b32_dpp v118, v116 row_shr:2 row_mask:0xf bank_mask:0xf
	v_mov_b32_dpp v122, v116 row_shl:1 row_mask:0xf bank_mask:0xf
	v_mov_b32_dpp v65, v117 row_shr:1 row_mask:0xf bank_mask:0xf
	v_mov_b32_dpp v119, v117 row_shr:2 row_mask:0xf bank_mask:0xf
	v_mov_b32_dpp v123, v117 row_shl:1 row_mask:0xf bank_mask:0xf
	v_mov_b32_dpp v120, v62 row_shr:1 row_mask:0xf bank_mask:0xf
	v_mov_b32_dpp v124, v62 row_shr:2 row_mask:0xf bank_mask:0xf
	v_mov_b32_dpp v126, v62 row_shl:1 row_mask:0xf bank_mask:0xf
	v_mov_b32_dpp v121, v63 row_shr:1 row_mask:0xf bank_mask:0xf
	v_mov_b32_dpp v125, v63 row_shr:2 row_mask:0xf bank_mask:0xf
	v_mov_b32_dpp v127, v63 row_shl:1 row_mask:0xf bank_mask:0xf
	v_lshl_add_u64 v[96:97], s[34:35], 0, v[96:97]
	s_and_saveexec_b64 s[2:3], s[40:41]
	s_xor_b64 s[30:31], exec, s[2:3]
	s_cbranch_execz .LBB0_572
	s_waitcnt vmcnt(0)
	v_pk_fma_f32 v[118:119], v[70:71], v[118:119], v[86:87]
	s_nop 0
	v_pk_fma_f32 v[64:65], v[74:75], v[64:65], v[118:119]
	v_pk_fma_f32 v[118:119], v[72:73], v[124:125], v[88:89]
	v_pk_fma_f32 v[64:65], v[116:117], v[78:79], v[64:65]
	v_pk_fma_f32 v[118:119], v[76:77], v[120:121], v[118:119]
	v_pk_fma_f32 v[64:65], v[82:83], v[122:123], v[64:65]
	v_pk_fma_f32 v[118:119], v[62:63], v[80:81], v[118:119]
	v_cvt_pk_bf16_f32 v64, v64, v65
	v_pk_fma_f32 v[118:119], v[84:85], v[126:127], v[118:119]
	s_nop 0
	v_cvt_pk_bf16_f32 v65, v118, v119
	v_lshl_add_u64 v[118:119], v[94:95], 1, v[96:97]
	global_store_dwordx2 v[118:119], v[64:65], off
;     template <int QVV> __device__ __forceinline__ void run(f32x4 (&acc)[2][2][4][2], const Unit& u, int wr, int wc, int fr, int fq) const {
;     ...
;                         const f32x4 w0 = *(const f32x4*)(cwp + 4 * n), w1 = *(const f32x4*)(cwp + 1024 + 4 * n), w2 = *(const f32x4*)(cwp + 2048 + 4 * n), w3 = *(const f32x4*)(cwp + 3072 + 4 * n), bb = *(const f32x4*)(cbp + 4 * n);
;                         f32x4 X[4];
; #pragma unroll
;                         for (int m = 0; m < 4; ++m) X[m] = acc[ai][bj][m][n] * rs[ai][m] + sh[n];
;                         if (fr <= 2) *(u32x2*)(tb + lo + (unsigned)(ai * HALF) * rs_ + bj * HALF * 2 + n * 8) = (u32x2){pk2(X[0][0], X[0][1]), pk2(X[0][2], X[0][3])};
;                         if (fr >= 13) *(u32x2*)(tb + lo + (unsigned)(ai * HALF + 48) * rs_ + bj * HALF * 2 + n * 8) = (u32x2){pk2(X[3][0], X[3][1]), pk2(X[3][2], X[3][3])};
; #pragma unroll
;                         for (int m = 0; m < 4; ++m) {
;                             const int mp = m > 0 ? m - 1 : 0, mn = m < 3 ? m + 1 : 3;
;                             f32x4 o;
; #pragma unroll
;                             for (int i = 0; i < 4; ++i) {
;                                 const float xif = X[m][i], xpf = X[mp][i], xnf = X[mn][i];
;                                 const int xi = __float_as_int(xif), xp = __float_as_int(xpf), xn = __float_as_int(xnf);
;                                 const float p1 = __builtin_bit_cast(float, __builtin_amdgcn_update_dpp(__builtin_amdgcn_update_dpp(0, xp, 0x121, 0xf, 0xf, false), xi, 0x111, 0xf, 0xf, false));
;                                 const float p2 = __builtin_bit_cast(float, __builtin_amdgcn_update_dpp(__builtin_amdgcn_update_dpp(0, xp, 0x122, 0xf, 0xf, false), xi, 0x112, 0xf, 0xf, false));
;                                 const float n1 = __builtin_bit_cast(float, __builtin_amdgcn_update_dpp(__builtin_amdgcn_update_dpp(0, xn, 0x12f, 0xf, 0xf, false), xi, 0x101, 0xf, 0xf, false));
;                                 o[i] = bb[i] + w0[i] * p2 + w1[i] * p1 + w2[i] * X[m][i] + w3[i] * n1; }
;                             const int r = r0 + wr * 64 + fr + ai * HALF + m * 16;
;                             const bool edge = (m == 0 && fr < 2) || (m == 3 && fr == 15);
;                             if (!edge) *(u32x2*)(XA + (size_t)r * 1024 + c0 + bj * HALF + 4 * n) = (u32x2){pk2(o[0], o[1]), pk2(o[2], o[3])}; }
.LBB0_572:
	s_andn2_saveexec_b64 s[30:31], s[30:31]
	s_or_b64 exec, exec, s[30:31]
	v_pk_fma_f32 v[118:119], v[52:53], v[104:105], v[92:93] op_sel_hi:[1,0,1]
	v_pk_fma_f32 v[64:65], v[50:51], v[104:105], v[90:91] op_sel_hi:[1,0,1]
	v_mov_b32_dpp v50, v116 row_ror:1 row_mask:0xf bank_mask:0xf
	v_mov_b32_dpp v52, v116 row_ror:2 row_mask:0xf bank_mask:0xf
	v_mov_b32_dpp v51, v117 row_ror:1 row_mask:0xf bank_mask:0xf
	v_mov_b32_dpp v53, v117 row_ror:2 row_mask:0xf bank_mask:0xf
	v_mov_b32_dpp v52, v54 row_shr:2 row_mask:0xf bank_mask:0xf
	v_mov_b32_dpp v53, v55 row_shr:2 row_mask:0xf bank_mask:0xf
	v_mov_b32_dpp v116, v62 row_ror:2 row_mask:0xf bank_mask:0xf
	v_mov_b32_dpp v117, v63 row_ror:2 row_mask:0xf bank_mask:0xf
	v_mov_b32_dpp v50, v54 row_shr:1 row_mask:0xf bank_mask:0xf
	v_mov_b32_dpp v51, v55 row_shr:1 row_mask:0xf bank_mask:0xf
	v_mov_b32_dpp v92, v62 row_ror:1 row_mask:0xf bank_mask:0xf
	v_mov_b32_dpp v116, v56 row_shr:2 row_mask:0xf bank_mask:0xf
	v_mov_b32_dpp v93, v63 row_ror:1 row_mask:0xf bank_mask:0xf
	v_mov_b32_dpp v117, v57 row_shr:2 row_mask:0xf bank_mask:0xf
	s_waitcnt vmcnt(0)
	v_pk_fma_f32 v[52:53], v[70:71], v[52:53], v[86:87]
	v_mov_b32_dpp v92, v56 row_shr:1 row_mask:0xf bank_mask:0xf
	v_mov_b32_dpp v93, v57 row_shr:1 row_mask:0xf bank_mask:0xf
	v_pk_fma_f32 v[50:51], v[74:75], v[50:51], v[52:53]
	v_pk_fma_f32 v[52:53], v[72:73], v[116:117], v[88:89]
	v_mov_b32_dpp v62, v118 row_ror:15 row_mask:0xf bank_mask:0xf
	v_mov_b32_dpp v63, v119 row_ror:15 row_mask:0xf bank_mask:0xf
	v_pk_fma_f32 v[52:53], v[76:77], v[92:93], v[52:53]
	v_mov_b32_dpp v90, v64 row_ror:15 row_mask:0xf bank_mask:0xf
	v_mov_b32_dpp v91, v65 row_ror:15 row_mask:0xf bank_mask:0xf
	v_mov_b32_dpp v62, v56 row_shl:1 row_mask:0xf bank_mask:0xf
	v_mov_b32_dpp v63, v57 row_shl:1 row_mask:0xf bank_mask:0xf
	v_pk_fma_f32 v[52:53], v[56:57], v[80:81], v[52:53]
	v_mov_b32_dpp v90, v54 row_shl:1 row_mask:0xf bank_mask:0xf
	v_mov_b32_dpp v91, v55 row_shl:1 row_mask:0xf bank_mask:0xf
	v_pk_fma_f32 v[50:51], v[54:55], v[78:79], v[50:51]
	v_pk_fma_f32 v[52:53], v[84:85], v[62:63], v[52:53]
	v_or_b32_e32 v62, 16, v114
	v_pk_fma_f32 v[50:51], v[82:83], v[90:91], v[50:51]
	v_ashrrev_i32_e32 v63, 31, v62
	v_cvt_pk_bf16_f32 v50, v50, v51
	v_cvt_pk_bf16_f32 v51, v52, v53
	v_lshlrev_b64 v[52:53], 11, v[62:63]
	v_lshl_add_u64 v[52:53], s[34:35], 0, v[52:53]
	v_lshlrev_b64 v[62:63], 1, v[94:95]
	v_lshl_add_u64 v[92:93], v[52:53], 0, v[62:63]
	v_mov_b32_dpp v116, v54 row_ror:2 row_mask:0xf bank_mask:0xf
	v_mov_b32_dpp v117, v55 row_ror:2 row_mask:0xf bank_mask:0xf
	global_store_dwordx2 v[92:93], v[50:51], off
	v_mov_b32_dpp v90, v54 row_ror:1 row_mask:0xf bank_mask:0xf
	v_mov_b32_dpp v116, v64 row_shr:2 row_mask:0xf bank_mask:0xf
	v_mov_b32_dpp v91, v55 row_ror:1 row_mask:0xf bank_mask:0xf
	v_mov_b32_dpp v117, v65 row_shr:2 row_mask:0xf bank_mask:0xf
	v_mov_b32_dpp v90, v64 row_shr:1 row_mask:0xf bank_mask:0xf
	v_mov_b32_dpp v50, v58 row_ror:15 row_mask:0xf bank_mask:0xf
	v_mov_b32_dpp v91, v65 row_shr:1 row_mask:0xf bank_mask:0xf
	v_mov_b32_dpp v51, v59 row_ror:15 row_mask:0xf bank_mask:0xf
	v_pk_fma_f32 v[116:117], v[70:71], v[116:117], v[86:87]
	v_mov_b32_e32 v54, v50
	v_mov_b32_e32 v55, v51
	v_mov_b32_dpp v122, v56 row_ror:2 row_mask:0xf bank_mask:0xf
	v_mov_b32_dpp v123, v57 row_ror:2 row_mask:0xf bank_mask:0xf
	v_pk_fma_f32 v[90:91], v[74:75], v[90:91], v[116:117]
	v_mov_b32_dpp v54, v64 row_shl:1 row_mask:0xf bank_mask:0xf
	v_mov_b32_dpp v55, v65 row_shl:1 row_mask:0xf bank_mask:0xf
	v_mov_b32_dpp v120, v56 row_ror:1 row_mask:0xf bank_mask:0xf
	v_mov_b32_dpp v122, v118 row_shr:2 row_mask:0xf bank_mask:0xf
	v_mov_b32_dpp v121, v57 row_ror:1 row_mask:0xf bank_mask:0xf
	v_mov_b32_dpp v123, v119 row_shr:2 row_mask:0xf bank_mask:0xf
	v_pk_fma_f32 v[90:91], v[64:65], v[78:79], v[90:91]
	v_mov_b32_dpp v120, v118 row_shr:1 row_mask:0xf bank_mask:0xf
	v_mov_b32_dpp v52, v60 row_ror:15 row_mask:0xf bank_mask:0xf
	v_mov_b32_dpp v121, v119 row_shr:1 row_mask:0xf bank_mask:0xf
	v_mov_b32_dpp v53, v61 row_ror:15 row_mask:0xf bank_mask:0xf
	v_pk_fma_f32 v[54:55], v[82:83], v[54:55], v[90:91]
	v_pk_fma_f32 v[90:91], v[72:73], v[122:123], v[88:89]
	v_mov_b32_e32 v56, v52
	v_mov_b32_e32 v57, v53
	v_pk_fma_f32 v[90:91], v[76:77], v[120:121], v[90:91]
	v_mov_b32_dpp v56, v118 row_shl:1 row_mask:0xf bank_mask:0xf
	v_mov_b32_dpp v57, v119 row_shl:1 row_mask:0xf bank_mask:0xf
	v_pk_fma_f32 v[90:91], v[118:119], v[80:81], v[90:91]
	v_cvt_pk_bf16_f32 v54, v54, v55
	v_pk_fma_f32 v[56:57], v[84:85], v[56:57], v[90:91]
	v_or_b32_e32 v90, 32, v114
	v_ashrrev_i32_e32 v91, 31, v90
	v_cvt_pk_bf16_f32 v55, v56, v57
	v_lshlrev_b64 v[56:57], 11, v[90:91]
	v_lshl_add_u64 v[56:57], s[34:35], 0, v[56:57]
	v_lshl_add_u64 v[116:117], v[56:57], 0, v[62:63]
	global_store_dwordx2 v[116:117], v[54:55], off
	v_mov_b32_dpp v54, v64 row_ror:1 row_mask:0xf bank_mask:0xf
	v_mov_b32_dpp v56, v64 row_ror:2 row_mask:0xf bank_mask:0xf
	v_mov_b32_dpp v55, v65 row_ror:1 row_mask:0xf bank_mask:0xf
	v_mov_b32_dpp v57, v65 row_ror:2 row_mask:0xf bank_mask:0xf
	v_mov_b32_dpp v62, v118 row_ror:1 row_mask:0xf bank_mask:0xf
	v_mov_b32_dpp v64, v118 row_ror:2 row_mask:0xf bank_mask:0xf
	v_mov_b32_dpp v63, v119 row_ror:1 row_mask:0xf bank_mask:0xf
	v_mov_b32_dpp v65, v119 row_ror:2 row_mask:0xf bank_mask:0xf
	v_cmp_ne_u32_e64 s[38:39], 15, v105
	v_mov_b32_dpp v54, v58 row_shr:1 row_mask:0xf bank_mask:0xf
	v_mov_b32_dpp v56, v58 row_shr:2 row_mask:0xf bank_mask:0xf
	v_mov_b32_dpp v50, v58 row_shl:1 row_mask:0xf bank_mask:0xf
	v_mov_b32_dpp v55, v59 row_shr:1 row_mask:0xf bank_mask:0xf
	v_mov_b32_dpp v57, v59 row_shr:2 row_mask:0xf bank_mask:0xf
	v_mov_b32_dpp v51, v59 row_shl:1 row_mask:0xf bank_mask:0xf
	v_mov_b32_dpp v62, v60 row_shr:1 row_mask:0xf bank_mask:0xf
	v_mov_b32_dpp v64, v60 row_shr:2 row_mask:0xf bank_mask:0xf
	v_mov_b32_dpp v52, v60 row_shl:1 row_mask:0xf bank_mask:0xf
	v_mov_b32_dpp v63, v61 row_shr:1 row_mask:0xf bank_mask:0xf
	v_mov_b32_dpp v65, v61 row_shr:2 row_mask:0xf bank_mask:0xf
	v_mov_b32_dpp v53, v61 row_shl:1 row_mask:0xf bank_mask:0xf
	v_or_b32_e32 v90, 48, v114
	s_and_saveexec_b64 s[30:31], s[38:39]
	s_cbranch_execz .LBB0_574
	v_pk_fma_f32 v[56:57], v[70:71], v[56:57], v[86:87]
	v_ashrrev_i32_e32 v91, 31, v90
	v_pk_fma_f32 v[54:55], v[74:75], v[54:55], v[56:57]
	s_nop 0
	v_pk_fma_f32 v[54:55], v[58:59], v[78:79], v[54:55]
	s_nop 0
	v_pk_fma_f32 v[50:51], v[82:83], v[50:51], v[54:55]
	v_pk_fma_f32 v[54:55], v[72:73], v[64:65], v[88:89]
	v_cvt_pk_bf16_f32 v50, v50, v51
	v_pk_fma_f32 v[54:55], v[76:77], v[62:63], v[54:55]
	s_nop 0
	v_pk_fma_f32 v[54:55], v[60:61], v[80:81], v[54:55]
	s_nop 0
	v_pk_fma_f32 v[52:53], v[84:85], v[52:53], v[54:55]
	s_nop 0
	v_cvt_pk_bf16_f32 v51, v52, v53
	v_lshlrev_b64 v[52:53], 11, v[90:91]
	v_lshl_add_u64 v[52:53], s[34:35], 0, v[52:53]
	v_lshl_add_u64 v[52:53], v[94:95], 1, v[52:53]
	global_store_dwordx2 v[52:53], v[50:51], off

;     template <int QVV> __device__ __forceinline__ void run(f32x4 (&acc)[2][2][4][2], const Unit& u, int wr, int wc, int fr, int fq) const {
;     ...
;                         for (int m = 0; m < 4; ++m) X[m] = acc[ai][bj][m][n] * rs[ai][m] + sh[n];
;                         if (fr <= 2) *(u32x2*)(tb + lo + (unsigned)(ai * HALF) * rs_ + bj * HALF * 2 + n * 8) = (u32x2){pk2(X[0][0], X[0][1]), pk2(X[0][2], X[0][3])};
;                         if (fr >= 13) *(u32x2*)(tb + lo + (unsigned)(ai * HALF + 48) * rs_ + bj * HALF * 2 + n * 8) = (u32x2){pk2(X[3][0], X[3][1]), pk2(X[3][2], X[3][3])};
; #pragma unroll
;                         for (int m = 0; m < 4; ++m) {
;                             const int mp = m > 0 ? m - 1 : 0, mn = m < 3 ? m + 1 : 3;
;                             f32x4 o;
; #pragma unroll
;                             for (int i = 0; i < 4; ++i) {
;                                 const float xif = X[m][i], xpf = X[mp][i], xnf = X[mn][i];
;                                 const int xi = __float_as_int(xif), xp = __float_as_int(xpf), xn = __float_as_int(xnf);
;                                 const float p1 = __builtin_bit_cast(float, __builtin_amdgcn_update_dpp(__builtin_amdgcn_update_dpp(0, xp, 0x121, 0xf, 0xf, false), xi, 0x111, 0xf, 0xf, false));
;                                 const float p2 = __builtin_bit_cast(float, __builtin_amdgcn_update_dpp(__builtin_amdgcn_update_dpp(0, xp, 0x122, 0xf, 0xf, false), xi, 0x112, 0xf, 0xf, false));
;                                 const float n1 = __builtin_bit_cast(float, __builtin_amdgcn_update_dpp(__builtin_amdgcn_update_dpp(0, xn, 0x12f, 0xf, 0xf, false), xi, 0x101, 0xf, 0xf, false));
;                                 o[i] = bb[i] + w0[i] * p2 + w1[i] * p1 + w2[i] * X[m][i] + w3[i] * n1; }
.LBB0_578:
	s_or_b64 exec, exec, s[30:31]
	v_mov_b32_e32 v107, v106
	v_mov_b32_e32 v74, v106
	v_mov_b32_e32 v75, v106
	v_pk_fma_f32 v[40:41], v[40:41], v[74:75], v[68:69]
	v_pk_fma_f32 v[38:39], v[38:39], v[106:107], v[66:67]
	v_mov_b32_dpp v74, v46 row_ror:1 row_mask:0xf bank_mask:0xf
	v_mov_b32_dpp v76, v46 row_ror:2 row_mask:0xf bank_mask:0xf
	v_mov_b32_dpp v80, v38 row_ror:15 row_mask:0xf bank_mask:0xf
	v_mov_b32_dpp v75, v47 row_ror:1 row_mask:0xf bank_mask:0xf
	v_mov_b32_dpp v77, v47 row_ror:2 row_mask:0xf bank_mask:0xf
	v_mov_b32_dpp v81, v39 row_ror:15 row_mask:0xf bank_mask:0xf
	v_mov_b32_dpp v78, v48 row_ror:1 row_mask:0xf bank_mask:0xf
	v_mov_b32_dpp v82, v48 row_ror:2 row_mask:0xf bank_mask:0xf
	v_mov_b32_dpp v84, v40 row_ror:15 row_mask:0xf bank_mask:0xf
	v_mov_b32_dpp v79, v49 row_ror:1 row_mask:0xf bank_mask:0xf
	v_mov_b32_dpp v83, v49 row_ror:2 row_mask:0xf bank_mask:0xf
	v_mov_b32_dpp v85, v41 row_ror:15 row_mask:0xf bank_mask:0xf
	v_mov_b32_dpp v74, v46 row_shr:1 row_mask:0xf bank_mask:0xf
	v_mov_b32_dpp v76, v46 row_shr:2 row_mask:0xf bank_mask:0xf
	v_mov_b32_dpp v80, v46 row_shl:1 row_mask:0xf bank_mask:0xf
	v_mov_b32_dpp v75, v47 row_shr:1 row_mask:0xf bank_mask:0xf
	v_mov_b32_dpp v77, v47 row_shr:2 row_mask:0xf bank_mask:0xf
	v_mov_b32_dpp v81, v47 row_shl:1 row_mask:0xf bank_mask:0xf
	v_mov_b32_dpp v78, v48 row_shr:1 row_mask:0xf bank_mask:0xf
	v_mov_b32_dpp v82, v48 row_shr:2 row_mask:0xf bank_mask:0xf
	v_mov_b32_dpp v84, v48 row_shl:1 row_mask:0xf bank_mask:0xf
	v_mov_b32_dpp v79, v49 row_shr:1 row_mask:0xf bank_mask:0xf
	v_mov_b32_dpp v83, v49 row_shr:2 row_mask:0xf bank_mask:0xf
	v_mov_b32_dpp v85, v49 row_shl:1 row_mask:0xf bank_mask:0xf
	s_and_saveexec_b64 s[2:3], s[40:41]
	s_xor_b64 s[30:31], exec, s[2:3]
	s_cbranch_execz .LBB0_580
	s_waitcnt vmcnt(0)
	v_pk_fma_f32 v[76:77], v[50:51], v[76:77], v[70:71]
	s_nop 0
	v_pk_fma_f32 v[74:75], v[54:55], v[74:75], v[76:77]
	v_pk_fma_f32 v[76:77], v[52:53], v[82:83], v[72:73]
	v_pk_fma_f32 v[74:75], v[46:47], v[58:59], v[74:75]
	v_pk_fma_f32 v[76:77], v[56:57], v[78:79], v[76:77]
	v_pk_fma_f32 v[74:75], v[62:63], v[80:81], v[74:75]
	v_pk_fma_f32 v[76:77], v[48:49], v[60:61], v[76:77]
	v_cvt_pk_bf16_f32 v74, v74, v75
	v_pk_fma_f32 v[76:77], v[64:65], v[84:85], v[76:77]
	s_nop 0
	v_cvt_pk_bf16_f32 v75, v76, v77
	v_lshl_add_u64 v[76:77], v[94:95], 1, v[96:97]
	global_store_dwordx2 v[76:77], v[74:75], off offset:8
;     template <int QVV> __device__ __forceinline__ void run(f32x4 (&acc)[2][2][4][2], const Unit& u, int wr, int wc, int fr, int fq) const {
;     ...
;                         const f32x4 w0 = *(const f32x4*)(cwp + 4 * n), w1 = *(const f32x4*)(cwp + 1024 + 4 * n), w2 = *(const f32x4*)(cwp + 2048 + 4 * n), w3 = *(const f32x4*)(cwp + 3072 + 4 * n), bb = *(const f32x4*)(cbp + 4 * n);
;                         f32x4 X[4];
; #pragma unroll
;                         for (int m = 0; m < 4; ++m) X[m] = acc[ai][bj][m][n] * rs[ai][m] + sh[n];
;                         if (fr <= 2) *(u32x2*)(tb + lo + (unsigned)(ai * HALF) * rs_ + bj * HALF * 2 + n * 8) = (u32x2){pk2(X[0][0], X[0][1]), pk2(X[0][2], X[0][3])};
;                         if (fr >= 13) *(u32x2*)(tb + lo + (unsigned)(ai * HALF + 48) * rs_ + bj * HALF * 2 + n * 8) = (u32x2){pk2(X[3][0], X[3][1]), pk2(X[3][2], X[3][3])};
; #pragma unroll
;                         for (int m = 0; m < 4; ++m) {
;                             const int mp = m > 0 ? m - 1 : 0, mn = m < 3 ? m + 1 : 3;
;                             f32x4 o;
; #pragma unroll
;                             for (int i = 0; i < 4; ++i) {
;                                 const float xif = X[m][i], xpf = X[mp][i], xnf = X[mn][i];
;                                 const int xi = __float_as_int(xif), xp = __float_as_int(xpf), xn = __float_as_int(xnf);
;                                 const float p1 = __builtin_bit_cast(float, __builtin_amdgcn_update_dpp(__builtin_amdgcn_update_dpp(0, xp, 0x121, 0xf, 0xf, false), xi, 0x111, 0xf, 0xf, false));
;                                 const float p2 = __builtin_bit_cast(float, __builtin_amdgcn_update_dpp(__builtin_amdgcn_update_dpp(0, xp, 0x122, 0xf, 0xf, false), xi, 0x112, 0xf, 0xf, false));
;                                 const float n1 = __builtin_bit_cast(float, __builtin_amdgcn_update_dpp(__builtin_amdgcn_update_dpp(0, xn, 0x12f, 0xf, 0xf, false), xi, 0x101, 0xf, 0xf, false));
;                                 o[i] = bb[i] + w0[i] * p2 + w1[i] * p1 + w2[i] * X[m][i] + w3[i] * n1; }
;                             const int r = r0 + wr * 64 + fr + ai * HALF + m * 16;
;                             const bool edge = (m == 0 && fr < 2) || (m == 3 && fr == 15);
;                             if (!edge) *(u32x2*)(XA + (size_t)r * 1024 + c0 + bj * HALF + 4 * n) = (u32x2){pk2(o[0], o[1]), pk2(o[2], o[3])}; }
.LBB0_580:
	s_andn2_saveexec_b64 s[30:31], s[30:31]
	s_or_b64 exec, exec, s[30:31]
	v_mov_b32_e32 v74, v104
	v_mov_b32_e32 v75, v104
	v_mov_b32_e32 v105, v104
	v_pk_fma_f32 v[68:69], v[36:37], v[74:75], v[68:69]
	v_pk_fma_f32 v[66:67], v[34:35], v[104:105], v[66:67]
	v_mov_b32_dpp v36, v46 row_ror:2 row_mask:0xf bank_mask:0xf
	v_mov_b32_dpp v37, v47 row_ror:2 row_mask:0xf bank_mask:0xf
	v_mov_b32_dpp v34, v46 row_ror:1 row_mask:0xf bank_mask:0xf
	v_mov_b32_dpp v36, v38 row_shr:2 row_mask:0xf bank_mask:0xf
	v_mov_b32_dpp v35, v47 row_ror:1 row_mask:0xf bank_mask:0xf
	v_mov_b32_dpp v37, v39 row_shr:2 row_mask:0xf bank_mask:0xf
	v_mov_b32_dpp v76, v48 row_ror:2 row_mask:0xf bank_mask:0xf
	v_mov_b32_dpp v77, v49 row_ror:2 row_mask:0xf bank_mask:0xf
	v_mov_b32_dpp v34, v38 row_shr:1 row_mask:0xf bank_mask:0xf
	v_mov_b32_dpp v35, v39 row_shr:1 row_mask:0xf bank_mask:0xf
	v_mov_b32_dpp v74, v48 row_ror:1 row_mask:0xf bank_mask:0xf
	v_mov_b32_dpp v76, v40 row_shr:2 row_mask:0xf bank_mask:0xf
	v_mov_b32_dpp v75, v49 row_ror:1 row_mask:0xf bank_mask:0xf
	v_mov_b32_dpp v77, v41 row_shr:2 row_mask:0xf bank_mask:0xf
	s_waitcnt vmcnt(0)
	v_pk_fma_f32 v[36:37], v[50:51], v[36:37], v[70:71]
	v_mov_b32_dpp v74, v40 row_shr:1 row_mask:0xf bank_mask:0xf
	v_mov_b32_dpp v75, v41 row_shr:1 row_mask:0xf bank_mask:0xf
	v_pk_fma_f32 v[34:35], v[54:55], v[34:35], v[36:37]
	v_pk_fma_f32 v[36:37], v[52:53], v[76:77], v[72:73]
	v_mov_b32_dpp v46, v66 row_ror:15 row_mask:0xf bank_mask:0xf
	v_mov_b32_dpp v47, v67 row_ror:15 row_mask:0xf bank_mask:0xf
	v_mov_b32_dpp v48, v68 row_ror:15 row_mask:0xf bank_mask:0xf
	v_mov_b32_dpp v49, v69 row_ror:15 row_mask:0xf bank_mask:0xf
	v_pk_fma_f32 v[36:37], v[56:57], v[74:75], v[36:37]
	v_mov_b32_dpp v46, v38 row_shl:1 row_mask:0xf bank_mask:0xf
	v_mov_b32_dpp v47, v39 row_shl:1 row_mask:0xf bank_mask:0xf
	v_mov_b32_dpp v48, v40 row_shl:1 row_mask:0xf bank_mask:0xf
	v_mov_b32_dpp v49, v41 row_shl:1 row_mask:0xf bank_mask:0xf
	v_pk_fma_f32 v[34:35], v[38:39], v[58:59], v[34:35]
	v_pk_fma_f32 v[36:37], v[40:41], v[60:61], v[36:37]
	v_pk_fma_f32 v[34:35], v[62:63], v[46:47], v[34:35]
	v_pk_fma_f32 v[36:37], v[64:65], v[48:49], v[36:37]
	v_cvt_pk_bf16_f32 v34, v34, v35
	v_cvt_pk_bf16_f32 v35, v36, v37
	v_mov_b32_dpp v48, v38 row_ror:2 row_mask:0xf bank_mask:0xf
	v_mov_b32_dpp v49, v39 row_ror:2 row_mask:0xf bank_mask:0xf
	global_store_dwordx2 v[92:93], v[34:35], off offset:8
	v_mov_b32_dpp v46, v38 row_ror:1 row_mask:0xf bank_mask:0xf
	v_mov_b32_dpp v48, v66 row_shr:2 row_mask:0xf bank_mask:0xf
	v_mov_b32_dpp v47, v39 row_ror:1 row_mask:0xf bank_mask:0xf
	v_mov_b32_dpp v49, v67 row_shr:2 row_mask:0xf bank_mask:0xf
	v_mov_b32_dpp v46, v66 row_shr:1 row_mask:0xf bank_mask:0xf
	v_mov_b32_dpp v34, v42 row_ror:15 row_mask:0xf bank_mask:0xf
	v_mov_b32_dpp v47, v67 row_shr:1 row_mask:0xf bank_mask:0xf
	v_mov_b32_dpp v35, v43 row_ror:15 row_mask:0xf bank_mask:0xf
	v_pk_fma_f32 v[48:49], v[50:51], v[48:49], v[70:71]
	v_mov_b32_e32 v38, v34
	v_mov_b32_e32 v39, v35
	v_mov_b32_dpp v76, v40 row_ror:2 row_mask:0xf bank_mask:0xf
	v_mov_b32_dpp v77, v41 row_ror:2 row_mask:0xf bank_mask:0xf
	v_pk_fma_f32 v[46:47], v[54:55], v[46:47], v[48:49]
	v_mov_b32_dpp v38, v66 row_shl:1 row_mask:0xf bank_mask:0xf
	v_mov_b32_dpp v39, v67 row_shl:1 row_mask:0xf bank_mask:0xf
	v_mov_b32_dpp v74, v40 row_ror:1 row_mask:0xf bank_mask:0xf
	v_mov_b32_dpp v76, v68 row_shr:2 row_mask:0xf bank_mask:0xf
	v_mov_b32_dpp v75, v41 row_ror:1 row_mask:0xf bank_mask:0xf
	v_mov_b32_dpp v77, v69 row_shr:2 row_mask:0xf bank_mask:0xf
	v_pk_fma_f32 v[46:47], v[66:67], v[58:59], v[46:47]
	v_mov_b32_dpp v74, v68 row_shr:1 row_mask:0xf bank_mask:0xf
	v_mov_b32_dpp v36, v44 row_ror:15 row_mask:0xf bank_mask:0xf
	v_mov_b32_dpp v75, v69 row_shr:1 row_mask:0xf bank_mask:0xf
	v_mov_b32_dpp v37, v45 row_ror:15 row_mask:0xf bank_mask:0xf
	v_pk_fma_f32 v[38:39], v[62:63], v[38:39], v[46:47]
	v_pk_fma_f32 v[46:47], v[52:53], v[76:77], v[72:73]
	v_mov_b32_e32 v40, v36
	v_mov_b32_e32 v41, v37
	v_pk_fma_f32 v[46:47], v[56:57], v[74:75], v[46:47]
	v_mov_b32_dpp v40, v68 row_shl:1 row_mask:0xf bank_mask:0xf
	v_mov_b32_dpp v41, v69 row_shl:1 row_mask:0xf bank_mask:0xf
	v_pk_fma_f32 v[46:47], v[68:69], v[60:61], v[46:47]
	v_cvt_pk_bf16_f32 v38, v38, v39
	v_pk_fma_f32 v[40:41], v[64:65], v[40:41], v[46:47]
	v_cvt_pk_bf16_f32 v39, v40, v41
	global_store_dwordx2 v[116:117], v[38:39], off offset:8
	v_mov_b32_dpp v38, v66 row_ror:1 row_mask:0xf bank_mask:0xf
	v_mov_b32_dpp v40, v66 row_ror:2 row_mask:0xf bank_mask:0xf
	v_mov_b32_dpp v39, v67 row_ror:1 row_mask:0xf bank_mask:0xf
	v_mov_b32_dpp v41, v67 row_ror:2 row_mask:0xf bank_mask:0xf
	v_mov_b32_dpp v46, v68 row_ror:1 row_mask:0xf bank_mask:0xf
	v_mov_b32_dpp v48, v68 row_ror:2 row_mask:0xf bank_mask:0xf
	v_mov_b32_dpp v47, v69 row_ror:1 row_mask:0xf bank_mask:0xf
	v_mov_b32_dpp v49, v69 row_ror:2 row_mask:0xf bank_mask:0xf
	v_mov_b32_dpp v38, v42 row_shr:1 row_mask:0xf bank_mask:0xf
	v_mov_b32_dpp v40, v42 row_shr:2 row_mask:0xf bank_mask:0xf
	v_mov_b32_dpp v34, v42 row_shl:1 row_mask:0xf bank_mask:0xf
	v_mov_b32_dpp v39, v43 row_shr:1 row_mask:0xf bank_mask:0xf
	v_mov_b32_dpp v41, v43 row_shr:2 row_mask:0xf bank_mask:0xf
	v_mov_b32_dpp v35, v43 row_shl:1 row_mask:0xf bank_mask:0xf
	v_mov_b32_dpp v46, v44 row_shr:1 row_mask:0xf bank_mask:0xf
	v_mov_b32_dpp v48, v44 row_shr:2 row_mask:0xf bank_mask:0xf
	v_mov_b32_dpp v36, v44 row_shl:1 row_mask:0xf bank_mask:0xf
	v_mov_b32_dpp v47, v45 row_shr:1 row_mask:0xf bank_mask:0xf
	v_mov_b32_dpp v49, v45 row_shr:2 row_mask:0xf bank_mask:0xf
	v_mov_b32_dpp v37, v45 row_shl:1 row_mask:0xf bank_mask:0xf
	s_and_saveexec_b64 s[30:31], s[38:39]
	s_cbranch_execz .LBB0_582
	v_pk_fma_f32 v[40:41], v[50:51], v[40:41], v[70:71]
	v_ashrrev_i32_e32 v91, 31, v90
	v_pk_fma_f32 v[38:39], v[54:55], v[38:39], v[40:41]
	s_nop 0
	v_pk_fma_f32 v[38:39], v[42:43], v[58:59], v[38:39]
	s_nop 0
	v_pk_fma_f32 v[34:35], v[62:63], v[34:35], v[38:39]
	v_pk_fma_f32 v[38:39], v[52:53], v[48:49], v[72:73]
	v_cvt_pk_bf16_f32 v34, v34, v35
	v_pk_fma_f32 v[38:39], v[56:57], v[46:47], v[38:39]
	s_nop 0
	v_pk_fma_f32 v[38:39], v[44:45], v[60:61], v[38:39]
	s_nop 0
	v_pk_fma_f32 v[36:37], v[64:65], v[36:37], v[38:39]
	s_nop 0
	v_cvt_pk_bf16_f32 v35, v36, v37
	v_lshlrev_b64 v[36:37], 11, v[90:91]
	v_lshl_add_u64 v[36:37], s[34:35], 0, v[36:37]
	v_lshl_add_u64 v[36:37], v[94:95], 1, v[36:37]
	global_store_dwordx2 v[36:37], v[34:35], off offset:8

;     template <int QVV> __device__ __forceinline__ void run(f32x4 (&acc)[2][2][4][2], const Unit& u, int wr, int wc, int fr, int fq) const {
;     ...
;                         for (int m = 0; m < 4; ++m) X[m] = acc[ai][bj][m][n] * rs[ai][m] + sh[n];
;                         if (fr <= 2) *(u32x2*)(tb + lo + (unsigned)(ai * HALF) * rs_ + bj * HALF * 2 + n * 8) = (u32x2){pk2(X[0][0], X[0][1]), pk2(X[0][2], X[0][3])};
;                         if (fr >= 13) *(u32x2*)(tb + lo + (unsigned)(ai * HALF + 48) * rs_ + bj * HALF * 2 + n * 8) = (u32x2){pk2(X[3][0], X[3][1]), pk2(X[3][2], X[3][3])};
; #pragma unroll
;                         for (int m = 0; m < 4; ++m) {
;                             const int mp = m > 0 ? m - 1 : 0, mn = m < 3 ? m + 1 : 3;
;                             f32x4 o;
; #pragma unroll
;                             for (int i = 0; i < 4; ++i) {
;                                 const float xif = X[m][i], xpf = X[mp][i], xnf = X[mn][i];
;                                 const int xi = __float_as_int(xif), xp = __float_as_int(xpf), xn = __float_as_int(xnf);
;                                 const float p1 = __builtin_bit_cast(float, __builtin_amdgcn_update_dpp(__builtin_amdgcn_update_dpp(0, xp, 0x121, 0xf, 0xf, false), xi, 0x111, 0xf, 0xf, false));
;                                 const float p2 = __builtin_bit_cast(float, __builtin_amdgcn_update_dpp(__builtin_amdgcn_update_dpp(0, xp, 0x122, 0xf, 0xf, false), xi, 0x112, 0xf, 0xf, false));
;                                 const float n1 = __builtin_bit_cast(float, __builtin_amdgcn_update_dpp(__builtin_amdgcn_update_dpp(0, xn, 0x12f, 0xf, 0xf, false), xi, 0x101, 0xf, 0xf, false));
;                                 o[i] = bb[i] + w0[i] * p2 + w1[i] * p1 + w2[i] * X[m][i] + w3[i] * n1; }
.LBB0_586:
	s_or_b64 exec, exec, s[30:31]
	v_mov_b32_e32 v62, v106
	v_mov_b32_e32 v63, v106
	v_pk_fma_f32 v[24:25], v[24:25], v[62:63], v[60:61]
	v_pk_fma_f32 v[22:23], v[22:23], v[106:107], v[58:59]
	v_mov_b32_dpp v62, v30 row_ror:1 row_mask:0xf bank_mask:0xf
	v_mov_b32_dpp v64, v30 row_ror:2 row_mask:0xf bank_mask:0xf
	v_mov_b32_dpp v68, v22 row_ror:15 row_mask:0xf bank_mask:0xf
	v_mov_b32_dpp v63, v31 row_ror:1 row_mask:0xf bank_mask:0xf
	v_mov_b32_dpp v65, v31 row_ror:2 row_mask:0xf bank_mask:0xf
	v_mov_b32_dpp v69, v23 row_ror:15 row_mask:0xf bank_mask:0xf
	v_mov_b32_dpp v66, v32 row_ror:1 row_mask:0xf bank_mask:0xf
	v_mov_b32_dpp v70, v32 row_ror:2 row_mask:0xf bank_mask:0xf
	v_mov_b32_dpp v72, v24 row_ror:15 row_mask:0xf bank_mask:0xf
	v_mov_b32_dpp v67, v33 row_ror:1 row_mask:0xf bank_mask:0xf
	v_mov_b32_dpp v71, v33 row_ror:2 row_mask:0xf bank_mask:0xf
	v_mov_b32_dpp v73, v25 row_ror:15 row_mask:0xf bank_mask:0xf
	v_mov_b32_dpp v62, v30 row_shr:1 row_mask:0xf bank_mask:0xf
	v_mov_b32_dpp v64, v30 row_shr:2 row_mask:0xf bank_mask:0xf
	v_mov_b32_dpp v68, v30 row_shl:1 row_mask:0xf bank_mask:0xf
	v_mov_b32_dpp v63, v31 row_shr:1 row_mask:0xf bank_mask:0xf
	v_mov_b32_dpp v65, v31 row_shr:2 row_mask:0xf bank_mask:0xf
	v_mov_b32_dpp v69, v31 row_shl:1 row_mask:0xf bank_mask:0xf
	v_mov_b32_dpp v66, v32 row_shr:1 row_mask:0xf bank_mask:0xf
	v_mov_b32_dpp v70, v32 row_shr:2 row_mask:0xf bank_mask:0xf
	v_mov_b32_dpp v72, v32 row_shl:1 row_mask:0xf bank_mask:0xf
	v_mov_b32_dpp v67, v33 row_shr:1 row_mask:0xf bank_mask:0xf
	v_mov_b32_dpp v71, v33 row_shr:2 row_mask:0xf bank_mask:0xf
	v_mov_b32_dpp v73, v33 row_shl:1 row_mask:0xf bank_mask:0xf
	s_and_saveexec_b64 s[2:3], s[40:41]
	s_xor_b64 s[30:31], exec, s[2:3]
	s_cbranch_execz .LBB0_588
	s_waitcnt vmcnt(0)
	v_pk_fma_f32 v[64:65], v[38:39], v[64:65], v[54:55]
	s_nop 0
	v_pk_fma_f32 v[62:63], v[42:43], v[62:63], v[64:65]
	v_pk_fma_f32 v[64:65], v[40:41], v[70:71], v[56:57]
	v_pk_fma_f32 v[62:63], v[30:31], v[46:47], v[62:63]
	v_pk_fma_f32 v[64:65], v[44:45], v[66:67], v[64:65]
	v_pk_fma_f32 v[62:63], v[50:51], v[68:69], v[62:63]
	v_pk_fma_f32 v[64:65], v[32:33], v[48:49], v[64:65]
	v_cvt_pk_bf16_f32 v62, v62, v63
	v_pk_fma_f32 v[64:65], v[52:53], v[72:73], v[64:65]
	s_nop 0
	v_cvt_pk_bf16_f32 v63, v64, v65
	v_lshl_add_u64 v[64:65], v[94:95], 1, v[96:97]
	global_store_dwordx2 v[64:65], v[62:63], off offset:256
;     template <int QVV> __device__ __forceinline__ void run(f32x4 (&acc)[2][2][4][2], const Unit& u, int wr, int wc, int fr, int fq) const {
;     ...
;                         const f32x4 w0 = *(const f32x4*)(cwp + 4 * n), w1 = *(const f32x4*)(cwp + 1024 + 4 * n), w2 = *(const f32x4*)(cwp + 2048 + 4 * n), w3 = *(const f32x4*)(cwp + 3072 + 4 * n), bb = *(const f32x4*)(cbp + 4 * n);
;                         f32x4 X[4];
; #pragma unroll
;                         for (int m = 0; m < 4; ++m) X[m] = acc[ai][bj][m][n] * rs[ai][m] + sh[n];
;                         if (fr <= 2) *(u32x2*)(tb + lo + (unsigned)(ai * HALF) * rs_ + bj * HALF * 2 + n * 8) = (u32x2){pk2(X[0][0], X[0][1]), pk2(X[0][2], X[0][3])};
;                         if (fr >= 13) *(u32x2*)(tb + lo + (unsigned)(ai * HALF + 48) * rs_ + bj * HALF * 2 + n * 8) = (u32x2){pk2(X[3][0], X[3][1]), pk2(X[3][2], X[3][3])};
; #pragma unroll
;                         for (int m = 0; m < 4; ++m) {
;                             const int mp = m > 0 ? m - 1 : 0, mn = m < 3 ? m + 1 : 3;
;                             f32x4 o;
; #pragma unroll
;                             for (int i = 0; i < 4; ++i) {
;                                 const float xif = X[m][i], xpf = X[mp][i], xnf = X[mn][i];
;                                 const int xi = __float_as_int(xif), xp = __float_as_int(xpf), xn = __float_as_int(xnf);
;                                 const float p1 = __builtin_bit_cast(float, __builtin_amdgcn_update_dpp(__builtin_amdgcn_update_dpp(0, xp, 0x121, 0xf, 0xf, false), xi, 0x111, 0xf, 0xf, false));
;                                 const float p2 = __builtin_bit_cast(float, __builtin_amdgcn_update_dpp(__builtin_amdgcn_update_dpp(0, xp, 0x122, 0xf, 0xf, false), xi, 0x112, 0xf, 0xf, false));
;                                 const float n1 = __builtin_bit_cast(float, __builtin_amdgcn_update_dpp(__builtin_amdgcn_update_dpp(0, xn, 0x12f, 0xf, 0xf, false), xi, 0x101, 0xf, 0xf, false));
;                                 o[i] = bb[i] + w0[i] * p2 + w1[i] * p1 + w2[i] * X[m][i] + w3[i] * n1; }
;                             const int r = r0 + wr * 64 + fr + ai * HALF + m * 16;
;                             const bool edge = (m == 0 && fr < 2) || (m == 3 && fr == 15);
;                             if (!edge) *(u32x2*)(XA + (size_t)r * 1024 + c0 + bj * HALF + 4 * n) = (u32x2){pk2(o[0], o[1]), pk2(o[2], o[3])}; }
.LBB0_588:
	s_andn2_saveexec_b64 s[30:31], s[30:31]
	s_or_b64 exec, exec, s[30:31]
	v_mov_b32_e32 v62, v104
	v_mov_b32_e32 v63, v104
	v_pk_fma_f32 v[60:61], v[20:21], v[62:63], v[60:61]
	v_pk_fma_f32 v[58:59], v[18:19], v[104:105], v[58:59]
	v_mov_b32_dpp v20, v30 row_ror:2 row_mask:0xf bank_mask:0xf
	v_mov_b32_dpp v21, v31 row_ror:2 row_mask:0xf bank_mask:0xf
	v_mov_b32_dpp v18, v30 row_ror:1 row_mask:0xf bank_mask:0xf
	v_mov_b32_dpp v20, v22 row_shr:2 row_mask:0xf bank_mask:0xf
	v_mov_b32_dpp v19, v31 row_ror:1 row_mask:0xf bank_mask:0xf
	v_mov_b32_dpp v21, v23 row_shr:2 row_mask:0xf bank_mask:0xf
	v_mov_b32_dpp v64, v32 row_ror:2 row_mask:0xf bank_mask:0xf
	v_mov_b32_dpp v65, v33 row_ror:2 row_mask:0xf bank_mask:0xf
	v_mov_b32_dpp v18, v22 row_shr:1 row_mask:0xf bank_mask:0xf
	v_mov_b32_dpp v19, v23 row_shr:1 row_mask:0xf bank_mask:0xf
	v_mov_b32_dpp v62, v32 row_ror:1 row_mask:0xf bank_mask:0xf
	v_mov_b32_dpp v64, v24 row_shr:2 row_mask:0xf bank_mask:0xf
	v_mov_b32_dpp v63, v33 row_ror:1 row_mask:0xf bank_mask:0xf
	v_mov_b32_dpp v65, v25 row_shr:2 row_mask:0xf bank_mask:0xf
	s_waitcnt vmcnt(0)
	v_pk_fma_f32 v[20:21], v[38:39], v[20:21], v[54:55]
	v_mov_b32_dpp v62, v24 row_shr:1 row_mask:0xf bank_mask:0xf
	v_mov_b32_dpp v63, v25 row_shr:1 row_mask:0xf bank_mask:0xf
	v_pk_fma_f32 v[18:19], v[42:43], v[18:19], v[20:21]
	v_pk_fma_f32 v[20:21], v[40:41], v[64:65], v[56:57]
	v_mov_b32_dpp v30, v58 row_ror:15 row_mask:0xf bank_mask:0xf
	v_mov_b32_dpp v31, v59 row_ror:15 row_mask:0xf bank_mask:0xf
	v_mov_b32_dpp v32, v60 row_ror:15 row_mask:0xf bank_mask:0xf
	v_mov_b32_dpp v33, v61 row_ror:15 row_mask:0xf bank_mask:0xf
	v_pk_fma_f32 v[20:21], v[44:45], v[62:63], v[20:21]
	v_mov_b32_dpp v30, v22 row_shl:1 row_mask:0xf bank_mask:0xf
	v_mov_b32_dpp v31, v23 row_shl:1 row_mask:0xf bank_mask:0xf
	v_mov_b32_dpp v32, v24 row_shl:1 row_mask:0xf bank_mask:0xf
	v_mov_b32_dpp v33, v25 row_shl:1 row_mask:0xf bank_mask:0xf
	v_pk_fma_f32 v[18:19], v[22:23], v[46:47], v[18:19]
	v_pk_fma_f32 v[20:21], v[24:25], v[48:49], v[20:21]
	v_pk_fma_f32 v[18:19], v[50:51], v[30:31], v[18:19]
	v_pk_fma_f32 v[20:21], v[52:53], v[32:33], v[20:21]
	v_cvt_pk_bf16_f32 v18, v18, v19
	v_cvt_pk_bf16_f32 v19, v20, v21
	v_mov_b32_dpp v32, v22 row_ror:2 row_mask:0xf bank_mask:0xf
	v_mov_b32_dpp v33, v23 row_ror:2 row_mask:0xf bank_mask:0xf
	global_store_dwordx2 v[92:93], v[18:19], off offset:256
	v_mov_b32_dpp v30, v22 row_ror:1 row_mask:0xf bank_mask:0xf
	v_mov_b32_dpp v32, v58 row_shr:2 row_mask:0xf bank_mask:0xf
	v_mov_b32_dpp v31, v23 row_ror:1 row_mask:0xf bank_mask:0xf
	v_mov_b32_dpp v33, v59 row_shr:2 row_mask:0xf bank_mask:0xf
	v_mov_b32_dpp v30, v58 row_shr:1 row_mask:0xf bank_mask:0xf
	v_mov_b32_dpp v18, v26 row_ror:15 row_mask:0xf bank_mask:0xf
	v_mov_b32_dpp v31, v59 row_shr:1 row_mask:0xf bank_mask:0xf
	v_mov_b32_dpp v19, v27 row_ror:15 row_mask:0xf bank_mask:0xf
	v_pk_fma_f32 v[32:33], v[38:39], v[32:33], v[54:55]
	v_mov_b32_e32 v22, v18
	v_mov_b32_e32 v23, v19
	v_mov_b32_dpp v64, v24 row_ror:2 row_mask:0xf bank_mask:0xf
	v_mov_b32_dpp v65, v25 row_ror:2 row_mask:0xf bank_mask:0xf
	v_pk_fma_f32 v[30:31], v[42:43], v[30:31], v[32:33]
	v_mov_b32_dpp v22, v58 row_shl:1 row_mask:0xf bank_mask:0xf
	v_mov_b32_dpp v23, v59 row_shl:1 row_mask:0xf bank_mask:0xf
	v_mov_b32_dpp v62, v24 row_ror:1 row_mask:0xf bank_mask:0xf
	v_mov_b32_dpp v64, v60 row_shr:2 row_mask:0xf bank_mask:0xf
	v_mov_b32_dpp v63, v25 row_ror:1 row_mask:0xf bank_mask:0xf
	v_mov_b32_dpp v65, v61 row_shr:2 row_mask:0xf bank_mask:0xf
	v_pk_fma_f32 v[30:31], v[58:59], v[46:47], v[30:31]
	v_mov_b32_dpp v62, v60 row_shr:1 row_mask:0xf bank_mask:0xf
	v_mov_b32_dpp v20, v28 row_ror:15 row_mask:0xf bank_mask:0xf
	v_mov_b32_dpp v63, v61 row_shr:1 row_mask:0xf bank_mask:0xf
	v_mov_b32_dpp v21, v29 row_ror:15 row_mask:0xf bank_mask:0xf
	v_pk_fma_f32 v[22:23], v[50:51], v[22:23], v[30:31]
	v_pk_fma_f32 v[30:31], v[40:41], v[64:65], v[56:57]
	v_mov_b32_e32 v24, v20
	v_mov_b32_e32 v25, v21
	v_pk_fma_f32 v[30:31], v[44:45], v[62:63], v[30:31]
	v_mov_b32_dpp v24, v60 row_shl:1 row_mask:0xf bank_mask:0xf
	v_mov_b32_dpp v25, v61 row_shl:1 row_mask:0xf bank_mask:0xf
	v_pk_fma_f32 v[30:31], v[60:61], v[48:49], v[30:31]
	v_cvt_pk_bf16_f32 v22, v22, v23
	v_pk_fma_f32 v[24:25], v[52:53], v[24:25], v[30:31]
	v_cvt_pk_bf16_f32 v23, v24, v25
	global_store_dwordx2 v[116:117], v[22:23], off offset:256
	v_mov_b32_dpp v22, v58 row_ror:1 row_mask:0xf bank_mask:0xf
	v_mov_b32_dpp v24, v58 row_ror:2 row_mask:0xf bank_mask:0xf
	v_mov_b32_dpp v23, v59 row_ror:1 row_mask:0xf bank_mask:0xf
	v_mov_b32_dpp v25, v59 row_ror:2 row_mask:0xf bank_mask:0xf
	v_mov_b32_dpp v30, v60 row_ror:1 row_mask:0xf bank_mask:0xf
	v_mov_b32_dpp v32, v60 row_ror:2 row_mask:0xf bank_mask:0xf
	v_mov_b32_dpp v31, v61 row_ror:1 row_mask:0xf bank_mask:0xf
	v_mov_b32_dpp v33, v61 row_ror:2 row_mask:0xf bank_mask:0xf
	v_mov_b32_dpp v22, v26 row_shr:1 row_mask:0xf bank_mask:0xf
	v_mov_b32_dpp v24, v26 row_shr:2 row_mask:0xf bank_mask:0xf
	v_mov_b32_dpp v18, v26 row_shl:1 row_mask:0xf bank_mask:0xf
	v_mov_b32_dpp v23, v27 row_shr:1 row_mask:0xf bank_mask:0xf
	v_mov_b32_dpp v25, v27 row_shr:2 row_mask:0xf bank_mask:0xf
	v_mov_b32_dpp v19, v27 row_shl:1 row_mask:0xf bank_mask:0xf
	v_mov_b32_dpp v30, v28 row_shr:1 row_mask:0xf bank_mask:0xf
	v_mov_b32_dpp v32, v28 row_shr:2 row_mask:0xf bank_mask:0xf
	v_mov_b32_dpp v20, v28 row_shl:1 row_mask:0xf bank_mask:0xf
	v_mov_b32_dpp v31, v29 row_shr:1 row_mask:0xf bank_mask:0xf
	v_mov_b32_dpp v33, v29 row_shr:2 row_mask:0xf bank_mask:0xf
	v_mov_b32_dpp v21, v29 row_shl:1 row_mask:0xf bank_mask:0xf
	s_and_saveexec_b64 s[30:31], s[38:39]
	s_cbranch_execz .LBB0_590
	v_pk_fma_f32 v[24:25], v[38:39], v[24:25], v[54:55]
	v_ashrrev_i32_e32 v91, 31, v90
	v_pk_fma_f32 v[22:23], v[42:43], v[22:23], v[24:25]
	s_nop 0
	v_pk_fma_f32 v[22:23], v[26:27], v[46:47], v[22:23]
	s_nop 0
	v_pk_fma_f32 v[18:19], v[50:51], v[18:19], v[22:23]
	v_pk_fma_f32 v[22:23], v[40:41], v[32:33], v[56:57]
	v_cvt_pk_bf16_f32 v18, v18, v19
	v_pk_fma_f32 v[22:23], v[44:45], v[30:31], v[22:23]
	s_nop 0
	v_pk_fma_f32 v[22:23], v[28:29], v[48:49], v[22:23]
	s_nop 0
	v_pk_fma_f32 v[20:21], v[52:53], v[20:21], v[22:23]
	s_nop 0
	v_cvt_pk_bf16_f32 v19, v20, v21
	v_lshlrev_b64 v[20:21], 11, v[90:91]
	v_lshl_add_u64 v[20:21], s[34:35], 0, v[20:21]
	v_lshl_add_u64 v[20:21], v[94:95], 1, v[20:21]
	global_store_dwordx2 v[20:21], v[18:19], off offset:256

;     template <int QVV> __device__ __forceinline__ void run(f32x4 (&acc)[2][2][4][2], const Unit& u, int wr, int wc, int fr, int fq) const {
;     ...
;                         for (int m = 0; m < 4; ++m) X[m] = acc[ai][bj][m][n] * rs[ai][m] + sh[n];
;                         if (fr <= 2) *(u32x2*)(tb + lo + (unsigned)(ai * HALF) * rs_ + bj * HALF * 2 + n * 8) = (u32x2){pk2(X[0][0], X[0][1]), pk2(X[0][2], X[0][3])};
;                         if (fr >= 13) *(u32x2*)(tb + lo + (unsigned)(ai * HALF + 48) * rs_ + bj * HALF * 2 + n * 8) = (u32x2){pk2(X[3][0], X[3][1]), pk2(X[3][2], X[3][3])};
; #pragma unroll
;                         for (int m = 0; m < 4; ++m) {
;                             const int mp = m > 0 ? m - 1 : 0, mn = m < 3 ? m + 1 : 3;
;                             f32x4 o;
; #pragma unroll
;                             for (int i = 0; i < 4; ++i) {
;                                 const float xif = X[m][i], xpf = X[mp][i], xnf = X[mn][i];
;                                 const int xi = __float_as_int(xif), xp = __float_as_int(xpf), xn = __float_as_int(xnf);
;                                 const float p1 = __builtin_bit_cast(float, __builtin_amdgcn_update_dpp(__builtin_amdgcn_update_dpp(0, xp, 0x121, 0xf, 0xf, false), xi, 0x111, 0xf, 0xf, false));
;                                 const float p2 = __builtin_bit_cast(float, __builtin_amdgcn_update_dpp(__builtin_amdgcn_update_dpp(0, xp, 0x122, 0xf, 0xf, false), xi, 0x112, 0xf, 0xf, false));
;                                 const float n1 = __builtin_bit_cast(float, __builtin_amdgcn_update_dpp(__builtin_amdgcn_update_dpp(0, xn, 0x12f, 0xf, 0xf, false), xi, 0x101, 0xf, 0xf, false));
;                                 o[i] = bb[i] + w0[i] * p2 + w1[i] * p1 + w2[i] * X[m][i] + w3[i] * n1; }
.LBB0_594:
	s_or_b64 exec, exec, s[30:31]
	v_mov_b32_e32 v42, v106
	v_mov_b32_e32 v43, v106
	v_pk_fma_f32 v[12:13], v[12:13], v[42:43], v[36:37]
	v_pk_fma_f32 v[10:11], v[10:11], v[106:107], v[34:35]
	v_mov_b32_dpp v42, v14 row_ror:1 row_mask:0xf bank_mask:0xf
	v_mov_b32_dpp v44, v14 row_ror:2 row_mask:0xf bank_mask:0xf
	v_mov_b32_dpp v48, v10 row_ror:15 row_mask:0xf bank_mask:0xf
	v_mov_b32_dpp v43, v15 row_ror:1 row_mask:0xf bank_mask:0xf
	v_mov_b32_dpp v45, v15 row_ror:2 row_mask:0xf bank_mask:0xf
	v_mov_b32_dpp v49, v11 row_ror:15 row_mask:0xf bank_mask:0xf
	v_mov_b32_dpp v46, v16 row_ror:1 row_mask:0xf bank_mask:0xf
	v_mov_b32_dpp v50, v16 row_ror:2 row_mask:0xf bank_mask:0xf
	v_mov_b32_dpp v52, v12 row_ror:15 row_mask:0xf bank_mask:0xf
	v_mov_b32_dpp v47, v17 row_ror:1 row_mask:0xf bank_mask:0xf
	v_mov_b32_dpp v51, v17 row_ror:2 row_mask:0xf bank_mask:0xf
	v_mov_b32_dpp v53, v13 row_ror:15 row_mask:0xf bank_mask:0xf
	v_mov_b32_dpp v42, v14 row_shr:1 row_mask:0xf bank_mask:0xf
	v_mov_b32_dpp v44, v14 row_shr:2 row_mask:0xf bank_mask:0xf
	v_mov_b32_dpp v48, v14 row_shl:1 row_mask:0xf bank_mask:0xf
	v_mov_b32_dpp v43, v15 row_shr:1 row_mask:0xf bank_mask:0xf
	v_mov_b32_dpp v45, v15 row_shr:2 row_mask:0xf bank_mask:0xf
	v_mov_b32_dpp v49, v15 row_shl:1 row_mask:0xf bank_mask:0xf
	v_mov_b32_dpp v46, v16 row_shr:1 row_mask:0xf bank_mask:0xf
	v_mov_b32_dpp v50, v16 row_shr:2 row_mask:0xf bank_mask:0xf
	v_mov_b32_dpp v52, v16 row_shl:1 row_mask:0xf bank_mask:0xf
	v_mov_b32_dpp v47, v17 row_shr:1 row_mask:0xf bank_mask:0xf
	v_mov_b32_dpp v51, v17 row_shr:2 row_mask:0xf bank_mask:0xf
	v_mov_b32_dpp v53, v17 row_shl:1 row_mask:0xf bank_mask:0xf
	s_and_saveexec_b64 s[2:3], s[40:41]
	s_xor_b64 s[30:31], exec, s[2:3]
	s_cbranch_execz .LBB0_596
	s_waitcnt vmcnt(0)
	v_pk_fma_f32 v[44:45], v[18:19], v[44:45], v[38:39]
	s_nop 0
	v_pk_fma_f32 v[42:43], v[22:23], v[42:43], v[44:45]
	v_pk_fma_f32 v[44:45], v[20:21], v[50:51], v[40:41]
	v_pk_fma_f32 v[42:43], v[14:15], v[26:27], v[42:43]
	v_pk_fma_f32 v[44:45], v[24:25], v[46:47], v[44:45]
	v_pk_fma_f32 v[42:43], v[30:31], v[48:49], v[42:43]
	v_pk_fma_f32 v[44:45], v[16:17], v[28:29], v[44:45]
	v_cvt_pk_bf16_f32 v42, v42, v43
	v_pk_fma_f32 v[44:45], v[32:33], v[52:53], v[44:45]
	s_nop 0
	v_cvt_pk_bf16_f32 v43, v44, v45
	v_lshl_add_u64 v[44:45], v[94:95], 1, v[96:97]
	global_store_dwordx2 v[44:45], v[42:43], off offset:264
;     template <int QVV> __device__ __forceinline__ void run(f32x4 (&acc)[2][2][4][2], const Unit& u, int wr, int wc, int fr, int fq) const {
;     ...
;                         const f32x4 w0 = *(const f32x4*)(cwp + 4 * n), w1 = *(const f32x4*)(cwp + 1024 + 4 * n), w2 = *(const f32x4*)(cwp + 2048 + 4 * n), w3 = *(const f32x4*)(cwp + 3072 + 4 * n), bb = *(const f32x4*)(cbp + 4 * n);
;                         f32x4 X[4];
; #pragma unroll
;                         for (int m = 0; m < 4; ++m) X[m] = acc[ai][bj][m][n] * rs[ai][m] + sh[n];
;                         if (fr <= 2) *(u32x2*)(tb + lo + (unsigned)(ai * HALF) * rs_ + bj * HALF * 2 + n * 8) = (u32x2){pk2(X[0][0], X[0][1]), pk2(X[0][2], X[0][3])};
;                         if (fr >= 13) *(u32x2*)(tb + lo + (unsigned)(ai * HALF + 48) * rs_ + bj * HALF * 2 + n * 8) = (u32x2){pk2(X[3][0], X[3][1]), pk2(X[3][2], X[3][3])};
; #pragma unroll
;                         for (int m = 0; m < 4; ++m) {
;                             const int mp = m > 0 ? m - 1 : 0, mn = m < 3 ? m + 1 : 3;
;                             f32x4 o;
; #pragma unroll
;                             for (int i = 0; i < 4; ++i) {
;                                 const float xif = X[m][i], xpf = X[mp][i], xnf = X[mn][i];
;                                 const int xi = __float_as_int(xif), xp = __float_as_int(xpf), xn = __float_as_int(xnf);
;                                 const float p1 = __builtin_bit_cast(float, __builtin_amdgcn_update_dpp(__builtin_amdgcn_update_dpp(0, xp, 0x121, 0xf, 0xf, false), xi, 0x111, 0xf, 0xf, false));
;                                 const float p2 = __builtin_bit_cast(float, __builtin_amdgcn_update_dpp(__builtin_amdgcn_update_dpp(0, xp, 0x122, 0xf, 0xf, false), xi, 0x112, 0xf, 0xf, false));
;                                 const float n1 = __builtin_bit_cast(float, __builtin_amdgcn_update_dpp(__builtin_amdgcn_update_dpp(0, xn, 0x12f, 0xf, 0xf, false), xi, 0x101, 0xf, 0xf, false));
;                                 o[i] = bb[i] + w0[i] * p2 + w1[i] * p1 + w2[i] * X[m][i] + w3[i] * n1; }
;                             const int r = r0 + wr * 64 + fr + ai * HALF + m * 16;
;                             const bool edge = (m == 0 && fr < 2) || (m == 3 && fr == 15);
;                             if (!edge) *(u32x2*)(XA + (size_t)r * 1024 + c0 + bj * HALF + 4 * n) = (u32x2){pk2(o[0], o[1]), pk2(o[2], o[3])}; }
.LBB0_596:
	s_andn2_saveexec_b64 s[30:31], s[30:31]
	s_or_b64 exec, exec, s[30:31]
	v_mov_b32_e32 v42, v104
	v_mov_b32_e32 v43, v104
	v_pk_fma_f32 v[36:37], v[4:5], v[42:43], v[36:37]
	v_pk_fma_f32 v[34:35], v[2:3], v[104:105], v[34:35]
	v_mov_b32_dpp v4, v14 row_ror:2 row_mask:0xf bank_mask:0xf
	v_mov_b32_dpp v5, v15 row_ror:2 row_mask:0xf bank_mask:0xf
	v_mov_b32_dpp v2, v14 row_ror:1 row_mask:0xf bank_mask:0xf
	v_mov_b32_dpp v4, v10 row_shr:2 row_mask:0xf bank_mask:0xf
	v_mov_b32_dpp v3, v15 row_ror:1 row_mask:0xf bank_mask:0xf
	v_mov_b32_dpp v5, v11 row_shr:2 row_mask:0xf bank_mask:0xf
	v_mov_b32_dpp v44, v16 row_ror:2 row_mask:0xf bank_mask:0xf
	v_mov_b32_dpp v45, v17 row_ror:2 row_mask:0xf bank_mask:0xf
	v_mov_b32_dpp v2, v10 row_shr:1 row_mask:0xf bank_mask:0xf
	v_mov_b32_dpp v3, v11 row_shr:1 row_mask:0xf bank_mask:0xf
	v_mov_b32_dpp v42, v16 row_ror:1 row_mask:0xf bank_mask:0xf
	v_mov_b32_dpp v44, v12 row_shr:2 row_mask:0xf bank_mask:0xf
	v_mov_b32_dpp v43, v17 row_ror:1 row_mask:0xf bank_mask:0xf
	v_mov_b32_dpp v45, v13 row_shr:2 row_mask:0xf bank_mask:0xf
	s_waitcnt vmcnt(0)
	v_pk_fma_f32 v[4:5], v[18:19], v[4:5], v[38:39]
	v_mov_b32_dpp v42, v12 row_shr:1 row_mask:0xf bank_mask:0xf
	v_mov_b32_dpp v43, v13 row_shr:1 row_mask:0xf bank_mask:0xf
	v_pk_fma_f32 v[2:3], v[22:23], v[2:3], v[4:5]
	v_pk_fma_f32 v[4:5], v[20:21], v[44:45], v[40:41]
	v_mov_b32_dpp v14, v34 row_ror:15 row_mask:0xf bank_mask:0xf
	v_mov_b32_dpp v15, v35 row_ror:15 row_mask:0xf bank_mask:0xf
	v_mov_b32_dpp v16, v36 row_ror:15 row_mask:0xf bank_mask:0xf
	v_mov_b32_dpp v17, v37 row_ror:15 row_mask:0xf bank_mask:0xf
	v_pk_fma_f32 v[4:5], v[24:25], v[42:43], v[4:5]
	v_mov_b32_dpp v14, v10 row_shl:1 row_mask:0xf bank_mask:0xf
	v_mov_b32_dpp v15, v11 row_shl:1 row_mask:0xf bank_mask:0xf
	v_mov_b32_dpp v16, v12 row_shl:1 row_mask:0xf bank_mask:0xf
	v_mov_b32_dpp v17, v13 row_shl:1 row_mask:0xf bank_mask:0xf
	v_pk_fma_f32 v[2:3], v[10:11], v[26:27], v[2:3]
	v_pk_fma_f32 v[4:5], v[12:13], v[28:29], v[4:5]
	v_pk_fma_f32 v[2:3], v[30:31], v[14:15], v[2:3]
	v_pk_fma_f32 v[4:5], v[32:33], v[16:17], v[4:5]
	v_cvt_pk_bf16_f32 v2, v2, v3
	v_cvt_pk_bf16_f32 v3, v4, v5
	v_mov_b32_dpp v16, v10 row_ror:2 row_mask:0xf bank_mask:0xf
	v_mov_b32_dpp v17, v11 row_ror:2 row_mask:0xf bank_mask:0xf
	global_store_dwordx2 v[92:93], v[2:3], off offset:264
	v_mov_b32_dpp v14, v10 row_ror:1 row_mask:0xf bank_mask:0xf
	v_mov_b32_dpp v16, v34 row_shr:2 row_mask:0xf bank_mask:0xf
	v_mov_b32_dpp v15, v11 row_ror:1 row_mask:0xf bank_mask:0xf
	v_mov_b32_dpp v17, v35 row_shr:2 row_mask:0xf bank_mask:0xf
	v_mov_b32_dpp v14, v34 row_shr:1 row_mask:0xf bank_mask:0xf
	v_mov_b32_dpp v2, v6 row_ror:15 row_mask:0xf bank_mask:0xf
	v_mov_b32_dpp v15, v35 row_shr:1 row_mask:0xf bank_mask:0xf
	v_mov_b32_dpp v3, v7 row_ror:15 row_mask:0xf bank_mask:0xf
	v_pk_fma_f32 v[16:17], v[18:19], v[16:17], v[38:39]
	v_mov_b32_e32 v10, v2
	v_mov_b32_e32 v11, v3
	v_mov_b32_dpp v44, v12 row_ror:2 row_mask:0xf bank_mask:0xf
	v_mov_b32_dpp v45, v13 row_ror:2 row_mask:0xf bank_mask:0xf
	v_pk_fma_f32 v[14:15], v[22:23], v[14:15], v[16:17]
	v_mov_b32_dpp v10, v34 row_shl:1 row_mask:0xf bank_mask:0xf
	v_mov_b32_dpp v11, v35 row_shl:1 row_mask:0xf bank_mask:0xf
	v_mov_b32_dpp v42, v12 row_ror:1 row_mask:0xf bank_mask:0xf
	v_mov_b32_dpp v44, v36 row_shr:2 row_mask:0xf bank_mask:0xf
	v_mov_b32_dpp v43, v13 row_ror:1 row_mask:0xf bank_mask:0xf
	v_mov_b32_dpp v45, v37 row_shr:2 row_mask:0xf bank_mask:0xf
	v_pk_fma_f32 v[14:15], v[34:35], v[26:27], v[14:15]
	v_mov_b32_dpp v42, v36 row_shr:1 row_mask:0xf bank_mask:0xf
	v_mov_b32_dpp v4, v8 row_ror:15 row_mask:0xf bank_mask:0xf
	v_mov_b32_dpp v43, v37 row_shr:1 row_mask:0xf bank_mask:0xf
	v_mov_b32_dpp v5, v9 row_ror:15 row_mask:0xf bank_mask:0xf
	v_pk_fma_f32 v[10:11], v[30:31], v[10:11], v[14:15]
	v_pk_fma_f32 v[14:15], v[20:21], v[44:45], v[40:41]
	v_mov_b32_e32 v12, v4
	v_mov_b32_e32 v13, v5
	v_pk_fma_f32 v[14:15], v[24:25], v[42:43], v[14:15]
	v_mov_b32_dpp v12, v36 row_shl:1 row_mask:0xf bank_mask:0xf
	v_mov_b32_dpp v13, v37 row_shl:1 row_mask:0xf bank_mask:0xf
	v_pk_fma_f32 v[14:15], v[36:37], v[28:29], v[14:15]
	v_cvt_pk_bf16_f32 v10, v10, v11
	v_pk_fma_f32 v[12:13], v[32:33], v[12:13], v[14:15]
	v_cvt_pk_bf16_f32 v11, v12, v13
	global_store_dwordx2 v[116:117], v[10:11], off offset:264
	v_mov_b32_dpp v10, v34 row_ror:1 row_mask:0xf bank_mask:0xf
	v_mov_b32_dpp v12, v34 row_ror:2 row_mask:0xf bank_mask:0xf
	v_mov_b32_dpp v11, v35 row_ror:1 row_mask:0xf bank_mask:0xf
	v_mov_b32_dpp v13, v35 row_ror:2 row_mask:0xf bank_mask:0xf
	v_mov_b32_dpp v14, v36 row_ror:1 row_mask:0xf bank_mask:0xf
	v_mov_b32_dpp v16, v36 row_ror:2 row_mask:0xf bank_mask:0xf
	v_mov_b32_dpp v15, v37 row_ror:1 row_mask:0xf bank_mask:0xf
	v_mov_b32_dpp v17, v37 row_ror:2 row_mask:0xf bank_mask:0xf
	v_mov_b32_dpp v10, v6 row_shr:1 row_mask:0xf bank_mask:0xf
	v_mov_b32_dpp v12, v6 row_shr:2 row_mask:0xf bank_mask:0xf
	v_mov_b32_dpp v2, v6 row_shl:1 row_mask:0xf bank_mask:0xf
	v_mov_b32_dpp v11, v7 row_shr:1 row_mask:0xf bank_mask:0xf
	v_mov_b32_dpp v13, v7 row_shr:2 row_mask:0xf bank_mask:0xf
	v_mov_b32_dpp v3, v7 row_shl:1 row_mask:0xf bank_mask:0xf
	v_mov_b32_dpp v14, v8 row_shr:1 row_mask:0xf bank_mask:0xf
	v_mov_b32_dpp v16, v8 row_shr:2 row_mask:0xf bank_mask:0xf
	v_mov_b32_dpp v4, v8 row_shl:1 row_mask:0xf bank_mask:0xf
	v_mov_b32_dpp v15, v9 row_shr:1 row_mask:0xf bank_mask:0xf
	v_mov_b32_dpp v17, v9 row_shr:2 row_mask:0xf bank_mask:0xf
	v_mov_b32_dpp v5, v9 row_shl:1 row_mask:0xf bank_mask:0xf
	s_and_saveexec_b64 s[30:31], s[38:39]
	s_cbranch_execz .LBB0_598
	v_pk_fma_f32 v[12:13], v[18:19], v[12:13], v[38:39]
	v_ashrrev_i32_e32 v91, 31, v90
	v_pk_fma_f32 v[10:11], v[22:23], v[10:11], v[12:13]
	s_nop 0
	v_pk_fma_f32 v[6:7], v[6:7], v[26:27], v[10:11]
	s_nop 0
	v_pk_fma_f32 v[2:3], v[30:31], v[2:3], v[6:7]
	v_pk_fma_f32 v[6:7], v[20:21], v[16:17], v[40:41]
	v_cvt_pk_bf16_f32 v2, v2, v3
	v_pk_fma_f32 v[6:7], v[24:25], v[14:15], v[6:7]
	s_nop 0
	v_pk_fma_f32 v[6:7], v[8:9], v[28:29], v[6:7]
	s_nop 0
	v_pk_fma_f32 v[4:5], v[32:33], v[4:5], v[6:7]
	s_nop 0
	v_cvt_pk_bf16_f32 v3, v4, v5
	v_lshlrev_b64 v[4:5], 11, v[90:91]
	v_lshl_add_u64 v[4:5], s[34:35], 0, v[4:5]
	v_lshl_add_u64 v[4:5], v[94:95], 1, v[4:5]
	global_store_dwordx2 v[4:5], v[2:3], off offset:264

; __device__ __forceinline__ void lane_scan8(const u32x4 p0, const u32x4 p1, int d, float (&hl)[8], float (&pl)[8]) {
;     const float lv[8] = {bflo(p0.x), bflo(p0.y), bflo(p0.z), bflo(p0.w), bflo(p1.x), bflo(p1.y), bflo(p1.z), bflo(p1.w)};
;     const float uv[8] = {bfhi(p0.x), bfhi(p0.y), bfhi(p0.z), bfhi(p0.w), bfhi(p1.x), bfhi(p1.y), bfhi(p1.z), bfhi(p1.w)};
;     float H = 0.f, P = 1.f;
;     if (d == 0) {
; #pragma unroll
;         for (int k = 0; k < 8; ++k) { const float av = __builtin_amdgcn_exp2f(lv[k]); H = av * H + uv[k]; P *= av; hl[k] = H; pl[k] = P; }
;     } else {
; #pragma unroll
;         for (int k = 7; k >= 0; --k) { const float av = __builtin_amdgcn_exp2f(lv[k]); H = av * H + uv[k]; P *= av; hl[k] = H; pl[k] = P; }
;     }
; __device__ __forceinline__ void scan_final(const Args& a, int gw, int ngw, int lane, int layer) {
;     ...
;             u32x4 lw[2][4], uw[2][4]; u32x2 rgw[8];
; #pragma unroll
;             for (int d = 0; d < 2; ++d)
; #pragma unroll
;                 for (int e = 0; e < 4; ++e) { const size_t off = ((size_t)d * 1024 + c4 + e) * MT + row0; lw[d][e] = *(const u32x4*)(LU + off); uw[d][e] = *(const u32x4*)(LU + off + 4); }
; #pragma unroll
;             for (int k = 0; k < 8; ++k) rgw[k] = *(const u32x2*)(ZT + zt(row0 + k, 1024 + c4));
;             float acc[8][4];
; #pragma unroll
;             for (int e = 0; e < 4; ++e) {
; #pragma unroll
;                 for (int d = 0; d < 2; ++d) {
;                     float hl[8], pl[8]; lane_scan8(lw[d][e], uw[d][e], d, hl, pl);
;                     float Pi = d == 0 ? pl[7] : pl[0], Hi = d == 0 ? hl[7] : hl[0];
; #pragma unroll
;                     for (int sft = 1; sft < 16; sft <<= 1) {
;                         const float Pp = d == 0 ? __shfl_up(Pi, sft, 16) : __shfl_down(Pi, sft, 16), Hp = d == 0 ? __shfl_up(Hi, sft, 16) : __shfl_down(Hi, sft, 16);
;                         const bool has = d == 0 ? (j >= sft) : (j + sft <= 15);
;                         if (has) { Hi = Pi * Hp + Hi; Pi = Pi * Pp; }
;                     }
;                     float Pe = d == 0 ? __shfl_up(Pi, 1, 16) : __shfl_down(Pi, 1, 16), He = d == 0 ? __shfl_up(Hi, 1, 16) : __shfl_down(Hi, 1, 16);
;                     if (d == 0 ? (j == 0) : (j == 15)) { Pe = 1.f; He = 0.f; }
;                     const float c0 = __shfl(cv, eh * 4 + e + 8 * d, 16);
.LBB0_1189:
	s_lshl_b32 s1, s52, 2
	v_add_u32_e32 v106, s1, v178
	v_or_b32_e32 v2, 1, v106
	v_mad_u64_u32 v[2:3], s[2:3], v2, s4, v[70:71]
	global_load_dwordx4 v[14:17], v[2:3], off offset:16
	global_load_dwordx4 v[30:33], v[2:3], off
	v_or_b32_e32 v2, 2, v106
	v_mad_u64_u32 v[6:7], s[2:3], v2, s4, v[70:71]
	global_load_dwordx4 v[2:5], v[6:7], off offset:16
	global_load_dwordx4 v[18:21], v[6:7], off
	v_or_b32_e32 v6, 3, v106
	v_mad_u64_u32 v[10:11], s[2:3], v6, s4, v[70:71]
	v_add_u32_e32 v12, 0x400, v106
	global_load_dwordx4 v[6:9], v[10:11], off offset:16
	global_load_dwordx4 v[22:25], v[10:11], off
	v_mad_u64_u32 v[10:11], s[2:3], v12, s4, v[70:71]
	global_load_dwordx4 v[58:61], v[10:11], off offset:16
	global_load_dwordx4 v[50:53], v[10:11], off
	v_add_u32_e32 v10, 0x401, v106
	v_mad_u64_u32 v[10:11], s[2:3], v10, s4, v[70:71]
	global_load_dwordx4 v[62:65], v[10:11], off offset:16
	global_load_dwordx4 v[54:57], v[10:11], off
	v_add_u32_e32 v10, 0x402, v106
	v_mad_u64_u32 v[10:11], s[2:3], v10, s4, v[70:71]
	global_load_dwordx4 v[42:45], v[10:11], off offset:16
	global_load_dwordx4 v[34:37], v[10:11], off
	v_add_u32_e32 v10, 0x403, v106
	v_mad_u64_u32 v[10:11], s[2:3], v10, s4, v[70:71]
	global_load_dwordx4 v[46:49], v[10:11], off offset:16
	global_load_dwordx4 v[38:41], v[10:11], off
	v_lshrrev_b32_e32 v10, 8, v12
	v_mul_u32_u24_e32 v174, 0x840000, v10
	v_and_b32_e32 v12, 0xfc, v106
	v_lshl_add_u64 v[10:11], v[174:175], 1, s[56:57]
	v_lshlrev_b32_e32 v174, 1, v12
	v_lshl_add_u64 v[10:11], v[10:11], 0, v[174:175]
	v_lshl_add_u64 v[12:13], v[10:11], 0, v[72:73]
	global_load_dwordx2 v[182:183], v[12:13], off
	v_lshl_add_u64 v[12:13], v[10:11], 0, v[74:75]
	global_load_dwordx2 v[152:153], v[12:13], off
	v_lshl_add_u64 v[12:13], v[10:11], 0, v[76:77]
	global_load_dwordx2 v[142:143], v[12:13], off
	v_lshl_add_u64 v[12:13], v[10:11], 0, v[78:79]
	global_load_dwordx2 v[136:137], v[12:13], off
	v_lshl_add_u64 v[12:13], v[10:11], 0, v[80:81]
	global_load_dwordx2 v[132:133], v[12:13], off
	v_lshl_add_u64 v[12:13], v[10:11], 0, v[82:83]
	global_load_dwordx2 v[128:129], v[12:13], off
	v_lshl_add_u64 v[12:13], v[10:11], 0, v[84:85]
	v_lshl_add_u64 v[10:11], v[10:11], 0, v[86:87]
	s_waitcnt vmcnt(22)
	v_mad_u64_u32 v[26:27], s[2:3], v106, s4, v[70:71]
	global_load_dwordx2 v[120:121], v[12:13], off
	global_load_dwordx2 v[104:105], v[10:11], off
	s_nop 0
	global_load_dwordx4 v[10:13], v[26:27], off offset:16
	s_nop 0
	global_load_dwordx4 v[26:29], v[26:27], off
	v_lshlrev_b32_e32 v174, 1, v106
	s_cmp_ge_u32 s52, s53
	s_mov_b32 s52, 1
	s_waitcnt vmcnt(22)
	v_and_b32_e32 v149, 0xffff0000, v30
	s_waitcnt vmcnt(17)
	v_and_b32_e32 v150, 0xffff0000, v61
	s_waitcnt vmcnt(16)
	v_and_b32_e32 v190, 0xffff0000, v53
	v_and_b32_e32 v180, 0xffff0000, v59
	s_waitcnt vmcnt(15)
	v_and_b32_e32 v151, 0xffff0000, v65
	v_and_b32_e32 v181, 0xffff0000, v63
	s_waitcnt vmcnt(14)
	v_and_b32_e32 v191, 0xffff0000, v57
	s_waitcnt vmcnt(12)
	v_and_b32_e32 v220, 0xffff0000, v37
	s_waitcnt vmcnt(10)
	v_and_b32_e32 v221, 0xffff0000, v41
	s_waitcnt vmcnt(0)
	v_lshlrev_b32_e32 v107, 16, v26
	v_exp_f32_e32 v110, v107
	v_lshlrev_b32_e32 v107, 16, v27
	v_exp_f32_e32 v156, v107
	v_lshlrev_b32_e32 v107, 16, v28
	v_exp_f32_e32 v146, v107
	v_lshlrev_b32_e32 v107, 16, v29
	v_exp_f32_e32 v140, v107
	v_lshlrev_b32_e32 v107, 16, v10
	v_exp_f32_e32 v134, v107
	v_lshlrev_b32_e32 v107, 16, v11
	v_exp_f32_e32 v130, v107
	v_lshlrev_b32_e32 v107, 16, v12
	v_exp_f32_e32 v122, v107
	v_lshlrev_b32_e32 v107, 16, v13
	v_exp_f32_e32 v116, v107
	v_add_lshl_u32 v107, s1, v225, 2
	ds_bpermute_b32 v124, v107, v69
	v_lshlrev_b32_e32 v107, 16, v50
	v_exp_f32_e32 v160, v107
	v_lshlrev_b32_e32 v107, 16, v51
	v_exp_f32_e32 v162, v107
	v_lshlrev_b32_e32 v107, 16, v52
	v_exp_f32_e32 v170, v107
	v_lshlrev_b32_e32 v107, 16, v53
	v_add_lshl_u32 v53, s1, v242, 2
	ds_bpermute_b32 v192, v53, v69
	v_lshlrev_b32_e32 v53, 16, v30
	v_exp_f32_e32 v111, v53
	v_lshlrev_b32_e32 v53, 16, v31
	v_exp_f32_e32 v157, v53
	v_lshlrev_b32_e32 v53, 16, v32
	v_exp_f32_e32 v147, v53
	v_lshlrev_b32_e32 v53, 16, v33
	v_exp_f32_e32 v141, v53
	v_lshlrev_b32_e32 v53, 16, v14
	v_exp_f32_e32 v135, v53
	v_lshlrev_b32_e32 v53, 16, v15
	v_exp_f32_e32 v131, v53
	v_lshlrev_b32_e32 v53, 16, v16
	v_exp_f32_e32 v123, v53
	v_lshlrev_b32_e32 v53, 16, v17
	v_exp_f32_e32 v117, v53
	v_add_lshl_u32 v53, s1, v239, 2
	ds_bpermute_b32 v125, v53, v69
	v_lshlrev_b32_e32 v53, 16, v54
	v_exp_f32_e32 v161, v53
	v_lshlrev_b32_e32 v53, 16, v55
	v_exp_f32_e32 v163, v53
	v_lshlrev_b32_e32 v53, 16, v56
	v_exp_f32_e32 v171, v53
	v_lshlrev_b32_e32 v53, 16, v57
	v_exp_f32_e32 v173, v53
	v_lshlrev_b32_e32 v53, 16, v62
	v_exp_f32_e32 v187, v53
	v_lshlrev_b32_e32 v53, 16, v63
	v_exp_f32_e32 v167, v53
	v_lshlrev_b32_e32 v53, 16, v65
	v_exp_f32_e32 v127, v53
	v_lshlrev_b32_e32 v53, 16, v64
	v_exp_f32_e32 v165, v53
	v_add_lshl_u32 v53, s1, v243, 2
	ds_bpermute_b32 v193, v53, v69
	v_lshlrev_b32_e32 v53, 16, v18
	v_exp_f32_e32 v108, v53
	v_lshlrev_b32_e32 v53, 16, v19
	v_exp_f32_e32 v188, v53
	v_lshlrev_b32_e32 v53, 16, v20
	v_exp_f32_e32 v168, v53
	v_lshlrev_b32_e32 v53, 16, v21
	v_exp_f32_e32 v158, v53
	v_lshlrev_b32_e32 v53, 16, v2
	v_exp_f32_e32 v154, v53
	v_lshlrev_b32_e32 v53, 16, v3
	v_exp_f32_e32 v144, v53
	v_lshlrev_b32_e32 v53, 16, v4
	v_exp_f32_e32 v138, v53
	v_lshlrev_b32_e32 v53, 16, v5
	v_exp_f32_e32 v112, v53
	v_add_lshl_u32 v53, s1, v240, 2
	v_exp_f32_e32 v172, v107
	v_lshlrev_b32_e32 v107, 16, v58
	ds_bpermute_b32 v114, v53, v69
	v_lshlrev_b32_e32 v53, 16, v34
	v_exp_f32_e32 v186, v107
	v_lshlrev_b32_e32 v107, 16, v59
	v_exp_f32_e32 v212, v53
	v_lshlrev_b32_e32 v53, 16, v35
; __device__ __forceinline__ float bflo(unsigned w) { return __uint_as_float(w << 16); }
; __device__ __forceinline__ float bfhi(unsigned w) { return __uint_as_float(w & 0xffff0000u); }
; __device__ __forceinline__ void lane_scan8(const u32x4 p0, const u32x4 p1, int d, float (&hl)[8], float (&pl)[8]) {
;     const float lv[8] = {bflo(p0.x), bflo(p0.y), bflo(p0.z), bflo(p0.w), bflo(p1.x), bflo(p1.y), bflo(p1.z), bflo(p1.w)};
;     const float uv[8] = {bfhi(p0.x), bfhi(p0.y), bfhi(p0.z), bfhi(p0.w), bfhi(p1.x), bfhi(p1.y), bfhi(p1.z), bfhi(p1.w)};
;     float H = 0.f, P = 1.f;
;     if (d == 0) {
; #pragma unroll
;         for (int k = 0; k < 8; ++k) { const float av = __builtin_amdgcn_exp2f(lv[k]); H = av * H + uv[k]; P *= av; hl[k] = H; pl[k] = P; }
;     } else {
; #pragma unroll
;         for (int k = 7; k >= 0; --k) { const float av = __builtin_amdgcn_exp2f(lv[k]); H = av * H + uv[k]; P *= av; hl[k] = H; pl[k] = P; }
;     }
; __device__ __forceinline__ void scan_final(const Args& a, int gw, int ngw, int lane, int layer) {
;     ...
;                     float hl[8], pl[8]; lane_scan8(lw[d][e], uw[d][e], d, hl, pl);
;                     float Pi = d == 0 ? pl[7] : pl[0], Hi = d == 0 ? hl[7] : hl[0];
; #pragma unroll
;                     for (int sft = 1; sft < 16; sft <<= 1) {
;                         const float Pp = d == 0 ? __shfl_up(Pi, sft, 16) : __shfl_down(Pi, sft, 16), Hp = d == 0 ? __shfl_up(Hi, sft, 16) : __shfl_down(Hi, sft, 16);
;                         const bool has = d == 0 ? (j >= sft) : (j + sft <= 15);
;                         if (has) { Hi = Pi * Hp + Hi; Pi = Pi * Pp; }
;                     }
;                     float Pe = d == 0 ? __shfl_up(Pi, 1, 16) : __shfl_down(Pi, 1, 16), He = d == 0 ? __shfl_up(Hi, 1, 16) : __shfl_down(Hi, 1, 16);
;                     if (d == 0 ? (j == 0) : (j == 15)) { Pe = 1.f; He = 0.f; }
;                     const float c0 = __shfl(cv, eh * 4 + e + 8 * d, 16);
	v_exp_f32_e32 v166, v107
	v_lshlrev_b32_e32 v107, 16, v61
	v_exp_f32_e32 v214, v53
	v_lshlrev_b32_e32 v53, 16, v36
	v_exp_f32_e32 v126, v107
	v_lshlrev_b32_e32 v107, 16, v60
	v_exp_f32_e32 v216, v53
	v_lshlrev_b32_e32 v53, 16, v37
	v_add_lshl_u32 v37, s1, v244, 2
	v_exp_f32_e32 v164, v107
	ds_bpermute_b32 v222, v37, v69
	v_lshlrev_b32_e32 v37, 16, v22
	v_exp_f32_e32 v109, v37
	v_lshlrev_b32_e32 v37, 16, v23
	v_exp_f32_e32 v189, v37
	v_lshlrev_b32_e32 v37, 16, v24
	v_exp_f32_e32 v210, v53
	v_lshlrev_b32_e32 v53, 16, v42
	v_exp_f32_e32 v169, v37
	v_lshlrev_b32_e32 v37, 16, v25
	v_pk_fma_f32 v[150:151], v[126:127], 0, v[150:151] op_sel_hi:[1,0,1]
	v_and_b32_e32 v61, 0xffff0000, v64
	v_and_b32_e32 v60, 0xffff0000, v60
	v_exp_f32_e32 v196, v53
	v_lshlrev_b32_e32 v53, 16, v43
	v_exp_f32_e32 v159, v37
	v_lshlrev_b32_e32 v37, 16, v6
	v_pk_fma_f32 v[60:61], v[164:165], v[150:151], v[60:61]
	v_and_b32_e32 v59, 0xffff0000, v62
	v_pk_mul_f32 v[62:63], v[126:127], v[164:165]
	v_exp_f32_e32 v218, v53
	v_lshlrev_b32_e32 v53, 16, v45
	v_exp_f32_e32 v155, v37
	v_lshlrev_b32_e32 v37, 16, v7
	v_and_b32_e32 v58, 0xffff0000, v58
	v_pk_mul_f32 v[164:165], v[166:167], v[62:63]
	v_pk_fma_f32 v[166:167], v[166:167], v[60:61], v[180:181]
	v_exp_f32_e32 v118, v53
	v_lshlrev_b32_e32 v53, 16, v44
	v_exp_f32_e32 v145, v37
	v_lshlrev_b32_e32 v37, 16, v8
	v_pk_mul_f32 v[184:185], v[186:187], v[164:165]
	v_pk_fma_f32 v[186:187], v[186:187], v[166:167], v[58:59]
	v_exp_f32_e32 v194, v53
	v_exp_f32_e32 v139, v37
	v_lshlrev_b32_e32 v37, 16, v9
	v_pk_mul_f32 v[198:199], v[172:173], v[184:185]
	v_pk_fma_f32 v[200:201], v[172:173], v[186:187], v[190:191]
	v_and_b32_e32 v53, 0xffff0000, v56
	v_and_b32_e32 v52, 0xffff0000, v52
	v_exp_f32_e32 v113, v37
	v_add_lshl_u32 v37, s1, v241, 2
	v_pk_mul_f32 v[64:65], v[170:171], v[198:199]
	v_pk_fma_f32 v[202:203], v[170:171], v[200:201], v[52:53]
	v_and_b32_e32 v53, 0xffff0000, v55
	v_and_b32_e32 v52, 0xffff0000, v51
	ds_bpermute_b32 v115, v37, v69
	v_lshlrev_b32_e32 v37, 16, v38
	v_pk_mul_f32 v[204:205], v[162:163], v[64:65]
	v_pk_fma_f32 v[206:207], v[162:163], v[202:203], v[52:53]
	v_and_b32_e32 v51, 0xffff0000, v54
	v_and_b32_e32 v50, 0xffff0000, v50
	v_exp_f32_e32 v213, v37
	v_lshlrev_b32_e32 v37, 16, v39
	v_pk_mul_f32 v[208:209], v[160:161], v[204:205]
	v_pk_fma_f32 v[50:51], v[160:161], v[206:207], v[50:51]
	v_exp_f32_e32 v215, v37
	v_lshlrev_b32_e32 v37, 16, v40
	v_and_b32_e32 v148, 0xffff0000, v26
	s_nop 1
	v_mov_b32_dpp v26, v208 row_shl:1 row_mask:0xf bank_mask:0xf bound_ctrl:1
	v_mov_b32_dpp v30, v50 row_shl:1 row_mask:0xf bank_mask:0xf bound_ctrl:1
	v_exp_f32_e32 v217, v37
	v_lshlrev_b32_e32 v37, 16, v41
	v_exp_f32_e32 v211, v37
	v_lshlrev_b32_e32 v37, 16, v46
	v_exp_f32_e32 v197, v37
	v_lshlrev_b32_e32 v37, 16, v47
	v_exp_f32_e32 v219, v37
	v_lshlrev_b32_e32 v37, 16, v49
	v_exp_f32_e32 v119, v37
	v_lshlrev_b32_e32 v37, 16, v48
	s_waitcnt lgkmcnt(0)
	v_fma_f32 v30, v208, v30, v50
	v_mul_f32_e32 v26, v208, v26
	v_exp_f32_e32 v195, v37
	v_add_lshl_u32 v37, s1, v237, 2
	v_cndmask_b32_e32 v30, v30, v50, vcc
	v_cndmask_b32_e32 v26, v26, v208, vcc
	ds_bpermute_b32 v223, v37, v69
	s_nop 1
	v_mov_b32_dpp v37, v26 row_shl:2 row_mask:0xf bank_mask:0xf bound_ctrl:1
	v_mov_b32_dpp v41, v30 row_shl:2 row_mask:0xf bank_mask:0xf bound_ctrl:1
	v_and_b32_e32 v44, 0xffff0000, v44
	v_pk_mul_f32 v[162:163], v[118:119], v[194:195]
	v_and_b32_e32 v36, 0xffff0000, v36
	s_waitcnt lgkmcnt(0)
	v_mul_f32_e32 v37, v26, v37
	v_fma_f32 v41, v26, v41, v30
	v_cndmask_b32_e64 v30, v30, v41, s[46:47]
	v_cndmask_b32_e64 v26, v26, v37, s[46:47]
	s_nop 1
	v_mov_b32_dpp v37, v26 row_shl:4 row_mask:0xf bank_mask:0xf bound_ctrl:1
	v_mov_b32_dpp v41, v30 row_shl:4 row_mask:0xf bank_mask:0xf bound_ctrl:1
	v_pk_mul_f32 v[170:171], v[218:219], v[162:163]
	v_and_b32_e32 v34, 0xffff0000, v34
	v_pk_fma_f32 v[148:149], v[110:111], 0, v[148:149] op_sel_hi:[1,0,1]
	v_mul_f32_e32 v37, v26, v37
	v_fma_f32 v41, v26, v41, v30
	v_cndmask_b32_e64 v30, v30, v41, s[48:49]
	v_cndmask_b32_e64 v26, v26, v37, s[48:49]
	s_nop 1
	v_mov_b32_dpp v37, v26 row_shl:8 row_mask:0xf bank_mask:0xf bound_ctrl:1
	v_mov_b32_dpp v41, v30 row_shl:8 row_mask:0xf bank_mask:0xf bound_ctrl:1
	v_and_b32_e32 v31, 0xffff0000, v31
	v_and_b32_e32 v33, 0xffff0000, v33
	v_and_b32_e32 v15, 0xffff0000, v15
	v_mul_f32_e32 v37, v26, v37
	v_fma_f32 v41, v26, v41, v30
	v_cndmask_b32_e64 v30, v30, v41, s[50:51]
	v_cndmask_b32_e64 v26, v26, v37, s[50:51]
	s_nop 1
	v_mov_b32_dpp v37, v209 row_shl:1 row_mask:0xf bank_mask:0xf bound_ctrl:1
	v_mov_b32_dpp v41, v51 row_shl:1 row_mask:0xf bank_mask:0xf bound_ctrl:1
	v_mov_b32_dpp v26, v26 row_shl:1 row_mask:0xf bank_mask:0xf
	v_mov_b32_dpp v30, v30 row_shl:1 row_mask:0xf bank_mask:0xf
	v_and_b32_e32 v17, 0xffff0000, v17
	v_mul_f32_e32 v37, v209, v37
	v_fma_f32 v41, v209, v41, v51
	v_cndmask_b32_e32 v41, v41, v51, vcc
	v_cndmask_b32_e32 v37, v37, v209, vcc
	s_nop 1
	v_mov_b32_dpp v52, v37 row_shl:2 row_mask:0xf bank_mask:0xf bound_ctrl:1
	v_mov_b32_dpp v53, v41 row_shl:2 row_mask:0xf bank_mask:0xf bound_ctrl:1
	v_cndmask_b32_e64 v54, v30, 0, vcc
	v_lshl_add_u64 v[106:107], s[62:63], 0, v[174:175]
	v_mul_f32_e32 v52, v37, v52
	v_fma_f32 v53, v37, v53, v41
	v_cndmask_b32_e64 v41, v41, v53, s[46:47]
	v_cndmask_b32_e64 v37, v37, v52, s[46:47]
	s_nop 1
	v_mov_b32_dpp v52, v37 row_shl:4 row_mask:0xf bank_mask:0xf bound_ctrl:1
	v_mov_b32_dpp v53, v41 row_shl:4 row_mask:0xf bank_mask:0xf bound_ctrl:1
	v_mul_f32_e32 v52, v37, v52
	v_fma_f32 v53, v37, v53, v41
	v_cndmask_b32_e64 v41, v41, v53, s[48:49]
	v_cndmask_b32_e64 v37, v37, v52, s[48:49]
	s_nop 1
; __device__ __forceinline__ void scan_final(const Args& a, int gw, int ngw, int lane, int layer) {
;     ...
;                     for (int sft = 1; sft < 16; sft <<= 1) {
;                         const float Pp = d == 0 ? __shfl_up(Pi, sft, 16) : __shfl_down(Pi, sft, 16), Hp = d == 0 ? __shfl_up(Hi, sft, 16) : __shfl_down(Hi, sft, 16);
;                         const bool has = d == 0 ? (j >= sft) : (j + sft <= 15);
;                         if (has) { Hi = Pi * Hp + Hi; Pi = Pi * Pp; }
;                     }
;                     float Pe = d == 0 ? __shfl_up(Pi, 1, 16) : __shfl_down(Pi, 1, 16), He = d == 0 ? __shfl_up(Hi, 1, 16) : __shfl_down(Hi, 1, 16);
;                     if (d == 0 ? (j == 0) : (j == 15)) { Pe = 1.f; He = 0.f; }
;                     const float c0 = __shfl(cv, eh * 4 + e + 8 * d, 16);
;                     const float sj = Pe * c0 + He;
	v_mov_b32_dpp v52, v37 row_shl:8 row_mask:0xf bank_mask:0xf bound_ctrl:1
	v_mov_b32_dpp v53, v41 row_shl:8 row_mask:0xf bank_mask:0xf bound_ctrl:1
	v_mul_f32_e32 v52, v37, v52
	v_fma_f32 v53, v37, v53, v41
	v_cndmask_b32_e64 v41, v41, v53, s[50:51]
	v_cndmask_b32_e64 v37, v37, v52, s[50:51]
	s_nop 1
	v_mov_b32_dpp v37, v37 row_shl:1 row_mask:0xf bank_mask:0xf
	v_mov_b32_dpp v41, v41 row_shl:1 row_mask:0xf bank_mask:0xf
	v_cndmask_b32_e64 v52, v26, 1.0, vcc
	v_cndmask_b32_e64 v53, v37, 1.0, vcc
	v_cndmask_b32_e64 v55, v41, 0, vcc
	v_pk_fma_f32 v[58:59], v[52:53], v[192:193], v[54:55]
	v_and_b32_e32 v37, 0xffff0000, v40
	v_pk_fma_f32 v[54:55], v[208:209], v[58:59], v[50:51]
	v_lshlrev_b32_e32 v50, 16, v182
	v_mul_f32_e32 v26, 0x3d372713, v50
	v_mul_f32_e32 v26, v26, v50
	v_mov_b32_e32 v30, v50
	v_fmac_f32_e32 v30, v26, v30
	v_mul_f32_e32 v26, 0x3f4c422a, v30
	v_add_f32_e32 v26, v26, v26
	v_mul_f32_e32 v26, 0x3fb8aa3b, v26
	v_exp_f32_e32 v26, v26
	v_and_b32_e32 v51, 0xffff0000, v182
	v_mov_b32_e32 v30, v51
	v_add_f32_e32 v26, 1.0, v26
	v_rcp_f32_e32 v52, v26
	v_mul_f32_e32 v26, 0x3d372713, v51
	v_mul_f32_e32 v26, v26, v51
	v_fmac_f32_e32 v30, v26, v30
	v_mul_f32_e32 v26, 0x3f4c422a, v30
	v_add_f32_e32 v26, v26, v26
	v_mul_f32_e32 v26, 0x3fb8aa3b, v26
	v_exp_f32_e32 v26, v26
	v_pk_mul_f32 v[50:51], v[50:51], 0.5 op_sel_hi:[1,0]
	v_add_f32_e32 v26, 1.0, v26
	v_rcp_f32_e32 v53, v26
	s_nop 0
	v_pk_fma_f32 v[52:53], v[52:53], 2.0, 1.0 op_sel_hi:[1,0,0] neg_lo:[1,0,0] neg_hi:[1,0,0]
	s_nop 0
	v_pk_add_f32 v[52:53], v[52:53], 1.0 op_sel_hi:[1,0]
	s_nop 0
	v_pk_mul_f32 v[56:57], v[50:51], v[52:53]
	v_and_b32_e32 v53, 0xffff0000, v49
	v_and_b32_e32 v52, 0xffff0000, v45
	v_pk_fma_f32 v[52:53], v[118:119], 0, v[52:53] op_sel_hi:[1,0,1]
	v_and_b32_e32 v45, 0xffff0000, v48
	v_pk_fma_f32 v[160:161], v[194:195], v[52:53], v[44:45]
	v_and_b32_e32 v49, 0xffff0000, v47
	v_and_b32_e32 v48, 0xffff0000, v43
	v_and_b32_e32 v47, 0xffff0000, v46
	v_and_b32_e32 v46, 0xffff0000, v42
	v_pk_fma_f32 v[172:173], v[218:219], v[160:161], v[48:49]
	v_pk_mul_f32 v[194:195], v[196:197], v[170:171]
	v_pk_fma_f32 v[196:197], v[196:197], v[172:173], v[46:47]
	v_pk_mul_f32 v[208:209], v[210:211], v[194:195]
	v_pk_fma_f32 v[210:211], v[210:211], v[196:197], v[220:221]
	v_pk_mul_f32 v[44:45], v[216:217], v[208:209]
	v_pk_fma_f32 v[46:47], v[216:217], v[210:211], v[36:37]
	v_and_b32_e32 v37, 0xffff0000, v39
	v_and_b32_e32 v36, 0xffff0000, v35
	v_pk_mul_f32 v[42:43], v[214:215], v[44:45]
	v_pk_fma_f32 v[48:49], v[214:215], v[46:47], v[36:37]
	v_and_b32_e32 v35, 0xffff0000, v38
	v_pk_mul_f32 v[180:181], v[212:213], v[42:43]
	v_pk_fma_f32 v[34:35], v[212:213], v[48:49], v[34:35]
	v_and_b32_e32 v51, 0xffff0000, v22
	v_and_b32_e32 v50, 0xffff0000, v18
	s_nop 1
	v_mov_b32_dpp v18, v180 row_shl:1 row_mask:0xf bank_mask:0xf bound_ctrl:1
	v_mov_b32_dpp v22, v34 row_shl:1 row_mask:0xf bank_mask:0xf bound_ctrl:1
	v_pk_fma_f32 v[50:51], v[108:109], 0, v[50:51] op_sel_hi:[1,0,1]
	v_mul_f32_e32 v18, v180, v18
	v_fma_f32 v22, v180, v22, v34
	v_cndmask_b32_e32 v22, v22, v34, vcc
	v_cndmask_b32_e32 v18, v18, v180, vcc
	s_nop 1
	v_mov_b32_dpp v26, v18 row_shl:2 row_mask:0xf bank_mask:0xf bound_ctrl:1
	v_mov_b32_dpp v30, v22 row_shl:2 row_mask:0xf bank_mask:0xf bound_ctrl:1
	v_mul_f32_e32 v26, v18, v26
	v_fma_f32 v30, v18, v30, v22
	v_cndmask_b32_e64 v22, v22, v30, s[46:47]
	v_cndmask_b32_e64 v18, v18, v26, s[46:47]
	s_nop 1
	v_mov_b32_dpp v26, v18 row_shl:4 row_mask:0xf bank_mask:0xf bound_ctrl:1
	v_mov_b32_dpp v30, v22 row_shl:4 row_mask:0xf bank_mask:0xf bound_ctrl:1
	v_mul_f32_e32 v26, v18, v26
	v_fma_f32 v30, v18, v30, v22
	v_cndmask_b32_e64 v22, v22, v30, s[48:49]
	v_cndmask_b32_e64 v18, v18, v26, s[48:49]
	s_nop 1
	v_mov_b32_dpp v26, v18 row_shl:8 row_mask:0xf bank_mask:0xf bound_ctrl:1
	v_mov_b32_dpp v30, v22 row_shl:8 row_mask:0xf bank_mask:0xf bound_ctrl:1
	v_mul_f32_e32 v26, v18, v26
	v_fma_f32 v30, v18, v30, v22
	v_cndmask_b32_e64 v22, v22, v30, s[50:51]
	v_cndmask_b32_e64 v18, v18, v26, s[50:51]
	s_nop 1
	v_mov_b32_dpp v26, v181 row_shl:1 row_mask:0xf bank_mask:0xf bound_ctrl:1
	v_mov_b32_dpp v30, v35 row_shl:1 row_mask:0xf bank_mask:0xf bound_ctrl:1
	v_mov_b32_dpp v18, v18 row_shl:1 row_mask:0xf bank_mask:0xf
	v_mov_b32_dpp v22, v22 row_shl:1 row_mask:0xf bank_mask:0xf
	v_mul_f32_e32 v26, v181, v26
	v_fma_f32 v30, v181, v30, v35
	v_cndmask_b32_e32 v30, v30, v35, vcc
	v_cndmask_b32_e32 v26, v26, v181, vcc
	s_nop 1
	v_mov_b32_dpp v36, v26 row_shl:2 row_mask:0xf bank_mask:0xf bound_ctrl:1
	v_mov_b32_dpp v37, v30 row_shl:2 row_mask:0xf bank_mask:0xf bound_ctrl:1
	v_cndmask_b32_e64 v38, v22, 0, vcc
	v_mul_f32_e32 v36, v26, v36
	v_fma_f32 v37, v26, v37, v30
	v_cndmask_b32_e64 v30, v30, v37, s[46:47]
	v_cndmask_b32_e64 v26, v26, v36, s[46:47]
	s_nop 1
	v_mov_b32_dpp v36, v26 row_shl:4 row_mask:0xf bank_mask:0xf bound_ctrl:1
	v_mov_b32_dpp v37, v30 row_shl:4 row_mask:0xf bank_mask:0xf bound_ctrl:1
	v_mul_f32_e32 v36, v26, v36
	v_fma_f32 v37, v26, v37, v30
	v_cndmask_b32_e64 v30, v30, v37, s[48:49]
	v_cndmask_b32_e64 v26, v26, v36, s[48:49]
	s_nop 1
	v_mov_b32_dpp v36, v26 row_shl:8 row_mask:0xf bank_mask:0xf bound_ctrl:1
	v_mov_b32_dpp v37, v30 row_shl:8 row_mask:0xf bank_mask:0xf bound_ctrl:1
	v_mul_f32_e32 v36, v26, v36
	v_fma_f32 v37, v26, v37, v30
	v_cndmask_b32_e64 v30, v30, v37, s[50:51]
	v_cndmask_b32_e64 v26, v26, v36, s[50:51]
	s_nop 1
	v_mov_b32_dpp v26, v26 row_shl:1 row_mask:0xf bank_mask:0xf
	v_mov_b32_dpp v30, v30 row_shl:1 row_mask:0xf bank_mask:0xf
	v_cndmask_b32_e64 v36, v18, 1.0, vcc
	v_cndmask_b32_e64 v37, v26, 1.0, vcc
	v_cndmask_b32_e64 v39, v30, 0, vcc
; __device__ __forceinline__ float bflo(unsigned w) { return __uint_as_float(w << 16); }
; __device__ __forceinline__ float bfhi(unsigned w) { return __uint_as_float(w & 0xffff0000u); }
; __device__ __forceinline__ float gelu_tanh(float x) { const float y = 0.7978845608028654f * (x + 0.044715f * x * x * x); const float e = __expf(2.0f * y); const float th = 1.0f - 2.0f * __builtin_amdgcn_rcpf(e + 1.0f); return 0.5f * x * (1.0f + th); }
; __device__ __forceinline__ void scan_final(const Args& a, int gw, int ngw, int lane, int layer) {
;     ...
;                     const float sj = Pe * c0 + He;
; #pragma unroll
;                     for (int k = 0; k < 8; ++k) { const float hv = hl[k] + pl[k] * sj; if (d == 0) acc[k][e] = hv; else acc[k][e] += hv; }
;                 }
;             }
; #pragma unroll
;             for (int k = 0; k < 8; ++k) { const float r0 = bflo(rgw[k].x), r1 = bfhi(rgw[k].x), r2 = bflo(rgw[k].y), r3 = bfhi(rgw[k].y);
;                 u32x2 w; w.x = pk2(acc[k][0] * gelu_tanh(r0), acc[k][1] * gelu_tanh(r1)); w.y = pk2(acc[k][2] * gelu_tanh(r2), acc[k][3] * gelu_tanh(r3));
	v_pk_fma_f32 v[40:41], v[36:37], v[222:223], v[38:39]
	v_lshlrev_b32_e32 v36, 16, v183
	v_mul_f32_e32 v18, 0x3d372713, v36
	v_mul_f32_e32 v18, v18, v36
	v_mov_b32_e32 v22, v36
	v_fmac_f32_e32 v22, v18, v22
	v_mul_f32_e32 v18, 0x3f4c422a, v22
	v_add_f32_e32 v18, v18, v18
	v_mul_f32_e32 v18, 0x3fb8aa3b, v18
	v_exp_f32_e32 v18, v18
	v_and_b32_e32 v37, 0xffff0000, v183
	v_mov_b32_e32 v22, v37
	v_lshlrev_b32_e32 v26, 16, v152
	v_add_f32_e32 v18, 1.0, v18
	v_rcp_f32_e32 v38, v18
	v_mul_f32_e32 v18, 0x3d372713, v37
	v_mul_f32_e32 v18, v18, v37
	v_fmac_f32_e32 v22, v18, v22
	v_mul_f32_e32 v18, 0x3f4c422a, v22
	v_add_f32_e32 v18, v18, v18
	v_mul_f32_e32 v18, 0x3fb8aa3b, v18
	v_exp_f32_e32 v18, v18
	v_mov_b32_e32 v22, v26
	v_and_b32_e32 v30, 0xffff0000, v27
	v_and_b32_e32 v27, 0xffff0000, v152
	v_add_f32_e32 v18, 1.0, v18
	v_rcp_f32_e32 v39, v18
	v_mul_f32_e32 v18, 0x3d372713, v26
	v_mul_f32_e32 v18, v18, v26
	v_fmac_f32_e32 v22, v18, v22
	v_mul_f32_e32 v18, 0x3f4c422a, v22
	v_add_f32_e32 v18, v18, v18
	v_mul_f32_e32 v18, 0x3fb8aa3b, v18
	v_exp_f32_e32 v18, v18
	v_pk_fma_f32 v[190:191], v[156:157], v[148:149], v[30:31]
	v_mov_b32_e32 v22, v27
	v_pk_mul_f32 v[182:183], v[110:111], v[156:157]
	v_add_f32_e32 v18, 1.0, v18
	v_rcp_f32_e32 v30, v18
	v_mul_f32_e32 v18, 0x3d372713, v27
	v_mul_f32_e32 v18, v18, v27
	v_fmac_f32_e32 v22, v18, v22
	v_mul_f32_e32 v18, 0x3f4c422a, v22
	v_add_f32_e32 v18, v18, v18
	v_mul_f32_e32 v18, 0x3fb8aa3b, v18
	v_exp_f32_e32 v18, v18
	v_pk_mul_f32 v[26:27], v[26:27], 0.5 op_sel_hi:[1,0]
	v_pk_fma_f32 v[156:157], v[204:205], v[58:59], v[206:207]
	v_pk_fma_f32 v[44:45], v[44:45], v[40:41], v[46:47]
	v_add_f32_e32 v18, 1.0, v18
	v_rcp_f32_e32 v31, v18
	v_pk_fma_f32 v[34:35], v[180:181], v[40:41], v[34:35]
	v_pk_fma_f32 v[38:39], v[38:39], 2.0, 1.0 op_sel_hi:[1,0,0] neg_lo:[1,0,0] neg_hi:[1,0,0]
	v_pk_mul_f32 v[36:37], v[36:37], 0.5 op_sel_hi:[1,0]
	v_pk_fma_f32 v[30:31], v[30:31], 2.0, 1.0 op_sel_hi:[1,0,0] neg_lo:[1,0,0] neg_hi:[1,0,0]
	v_pk_add_f32 v[38:39], v[38:39], 1.0 op_sel_hi:[1,0]
	v_pk_add_f32 v[30:31], v[30:31], 1.0 op_sel_hi:[1,0]
	v_pk_mul_f32 v[38:39], v[36:37], v[38:39]
	v_pk_mul_f32 v[192:193], v[26:27], v[30:31]
	v_lshlrev_b32_e32 v30, 16, v153
	v_and_b32_e32 v26, 0xffff0000, v19
	v_pk_fma_f32 v[18:19], v[42:43], v[40:41], v[48:49]
	v_mul_f32_e32 v42, 0x3d372713, v30
	v_mul_f32_e32 v42, v42, v30
	v_mov_b32_e32 v43, v30
	v_and_b32_e32 v31, 0xffff0000, v153
	v_fmac_f32_e32 v43, v42, v43
	v_mul_f32_e32 v42, 0x3f4c422a, v43
	v_mul_f32_e32 v43, 0x3d372713, v31
	v_mul_f32_e32 v43, v43, v31
	v_mov_b32_e32 v48, v31
	v_fmac_f32_e32 v48, v43, v48
	v_mul_f32_e32 v43, 0x3f4c422a, v48
	v_and_b32_e32 v49, 0xffff0000, v32
	v_and_b32_e32 v48, 0xffff0000, v28
	v_pk_fma_f32 v[204:205], v[146:147], v[190:191], v[48:49]
	v_lshlrev_b32_e32 v48, 16, v142
	v_mul_f32_e32 v28, 0x3d372713, v48
	v_mul_f32_e32 v28, v28, v48
	v_mov_b32_e32 v32, v48
	v_fmac_f32_e32 v32, v28, v32
	v_mul_f32_e32 v28, 0x3f4c422a, v32
	v_add_f32_e32 v28, v28, v28
	v_mul_f32_e32 v28, 0x3fb8aa3b, v28
	v_exp_f32_e32 v28, v28
	v_and_b32_e32 v27, 0xffff0000, v23
	v_and_b32_e32 v49, 0xffff0000, v142
	v_pk_mul_f32 v[22:23], v[108:109], v[188:189]
	v_add_f32_e32 v28, 1.0, v28
	v_pk_fma_f32 v[26:27], v[188:189], v[50:51], v[26:27]
	v_pk_fma_f32 v[188:189], v[64:65], v[58:59], v[202:203]
	v_rcp_f32_e32 v64, v28
	v_mul_f32_e32 v28, 0x3d372713, v49
	v_mul_f32_e32 v28, v28, v49
	v_mov_b32_e32 v32, v49
	v_fmac_f32_e32 v32, v28, v32
	v_mul_f32_e32 v28, 0x3f4c422a, v32
	v_add_f32_e32 v28, v28, v28
	v_mul_f32_e32 v28, 0x3fb8aa3b, v28
	v_exp_f32_e32 v28, v28
	v_pk_mul_f32 v[48:49], v[48:49], 0.5 op_sel_hi:[1,0]
	v_and_b32_e32 v32, 0xffff0000, v29
	v_and_b32_e32 v29, 0xffff0000, v136
	v_add_f32_e32 v28, 1.0, v28
	v_rcp_f32_e32 v65, v28
	v_lshlrev_b32_e32 v28, 16, v136
	v_pk_mul_f32 v[46:47], v[168:169], v[22:23]
	v_pk_mul_f32 v[202:203], v[146:147], v[182:183]
	v_pk_fma_f32 v[64:65], v[64:65], 2.0, 1.0 op_sel_hi:[1,0,0] neg_lo:[1,0,0] neg_hi:[1,0,0]
	v_and_b32_e32 v146, 0xffff0000, v2
	v_pk_add_f32 v[64:65], v[64:65], 1.0 op_sel_hi:[1,0]
	v_and_b32_e32 v147, 0xffff0000, v6
	v_pk_mul_f32 v[206:207], v[48:49], v[64:65]
	v_lshlrev_b32_e32 v64, 16, v143
	v_and_b32_e32 v48, 0xffff0000, v20
	v_mul_f32_e32 v20, 0x3d372713, v64
	v_and_b32_e32 v49, 0xffff0000, v24
	v_mul_f32_e32 v20, v20, v64
	v_mov_b32_e32 v24, v64
	v_fmac_f32_e32 v24, v20, v24
	v_mul_f32_e32 v20, 0x3f4c422a, v24
	v_add_f32_e32 v20, v20, v20
	v_mul_f32_e32 v20, 0x3fb8aa3b, v20
	v_exp_f32_e32 v20, v20
	v_and_b32_e32 v65, 0xffff0000, v143
	v_mov_b32_e32 v24, v65
	v_pk_fma_f32 v[48:49], v[168:169], v[26:27], v[48:49]
	v_add_f32_e32 v20, 1.0, v20
	v_rcp_f32_e32 v142, v20
	v_mul_f32_e32 v20, 0x3d372713, v65
	v_mul_f32_e32 v20, v20, v65
	v_fmac_f32_e32 v24, v20, v24
	v_mul_f32_e32 v20, 0x3f4c422a, v24
	v_add_f32_e32 v20, v20, v20
	v_mul_f32_e32 v20, 0x3fb8aa3b, v20
	v_exp_f32_e32 v20, v20
	v_mov_b32_e32 v24, v28
	v_pk_fma_f32 v[168:169], v[198:199], v[58:59], v[200:201]
	v_pk_fma_f32 v[200:201], v[140:141], v[204:205], v[32:33]
	v_add_f32_e32 v20, 1.0, v20
	v_rcp_f32_e32 v143, v20
	v_mul_f32_e32 v20, 0x3d372713, v28
	v_mul_f32_e32 v20, v20, v28
	v_fmac_f32_e32 v24, v20, v24
	v_mul_f32_e32 v20, 0x3f4c422a, v24
	v_add_f32_e32 v20, v20, v20
	v_mul_f32_e32 v20, 0x3fb8aa3b, v20
	v_exp_f32_e32 v20, v20
	v_mov_b32_e32 v24, v29
	v_pk_mul_f32 v[198:199], v[140:141], v[202:203]
	v_and_b32_e32 v141, 0xffff0000, v14
	v_add_f32_e32 v20, 1.0, v20
	v_rcp_f32_e32 v32, v20
	v_mul_f32_e32 v20, 0x3d372713, v29
	v_mul_f32_e32 v20, v20, v29
	v_fmac_f32_e32 v24, v20, v24
	v_mul_f32_e32 v20, 0x3f4c422a, v24
	v_add_f32_e32 v20, v20, v20
; __device__ __forceinline__ float bflo(unsigned w) { return __uint_as_float(w << 16); }
; __device__ __forceinline__ float bfhi(unsigned w) { return __uint_as_float(w & 0xffff0000u); }
; __device__ __forceinline__ float gelu_tanh(float x) { const float y = 0.7978845608028654f * (x + 0.044715f * x * x * x); const float e = __expf(2.0f * y); const float th = 1.0f - 2.0f * __builtin_amdgcn_rcpf(e + 1.0f); return 0.5f * x * (1.0f + th); }
; __device__ __forceinline__ void lane_scan8(const u32x4 p0, const u32x4 p1, int d, float (&hl)[8], float (&pl)[8]) {
;     ...
;     if (d == 0) {
; #pragma unroll
;         for (int k = 0; k < 8; ++k) { const float av = __builtin_amdgcn_exp2f(lv[k]); H = av * H + uv[k]; P *= av; hl[k] = H; pl[k] = P; }
;     } else {
; #pragma unroll
;         for (int k = 7; k >= 0; --k) { const float av = __builtin_amdgcn_exp2f(lv[k]); H = av * H + uv[k]; P *= av; hl[k] = H; pl[k] = P; }
;     }
; __device__ __forceinline__ void scan_final(const Args& a, int gw, int ngw, int lane, int layer) {
;     ...
;             for (int k = 0; k < 8; ++k) { const float r0 = bflo(rgw[k].x), r1 = bfhi(rgw[k].x), r2 = bflo(rgw[k].y), r3 = bfhi(rgw[k].y);
;                 u32x2 w; w.x = pk2(acc[k][0] * gelu_tanh(r0), acc[k][1] * gelu_tanh(r1)); w.y = pk2(acc[k][2] * gelu_tanh(r2), acc[k][3] * gelu_tanh(r3));
	v_mul_f32_e32 v20, 0x3fb8aa3b, v20
	v_exp_f32_e32 v20, v20
	v_pk_mul_f32 v[28:29], v[28:29], 0.5 op_sel_hi:[1,0]
	v_add_f32_e32 v42, v42, v42
	v_add_f32_e32 v43, v43, v43
	v_add_f32_e32 v20, 1.0, v20
	v_rcp_f32_e32 v33, v20
	v_mul_f32_e32 v42, 0x3fb8aa3b, v42
	v_mul_f32_e32 v43, 0x3fb8aa3b, v43
	v_exp_f32_e32 v42, v42
	v_pk_fma_f32 v[32:33], v[32:33], 2.0, 1.0 op_sel_hi:[1,0,0] neg_lo:[1,0,0] neg_hi:[1,0,0]
	v_exp_f32_e32 v43, v43
	v_pk_add_f32 v[32:33], v[32:33], 1.0 op_sel_hi:[1,0]
	v_add_f32_e32 v42, 1.0, v42
	v_pk_mul_f32 v[212:213], v[28:29], v[32:33]
	v_lshlrev_b32_e32 v32, 16, v137
	v_mul_f32_e32 v136, 0x3d372713, v32
	v_and_b32_e32 v33, 0xffff0000, v137
	v_mul_f32_e32 v136, v136, v32
	v_mov_b32_e32 v137, v32
	v_fmac_f32_e32 v137, v136, v137
	v_mul_f32_e32 v136, 0x3f4c422a, v137
	v_mul_f32_e32 v137, 0x3d372713, v33
	v_mul_f32_e32 v137, v137, v33
	v_mov_b32_e32 v140, v33
	v_fmac_f32_e32 v140, v137, v140
	v_and_b32_e32 v29, 0xffff0000, v25
	v_and_b32_e32 v28, 0xffff0000, v21
	v_mul_f32_e32 v137, 0x3f4c422a, v140
	v_and_b32_e32 v140, 0xffff0000, v10
	v_pk_mul_f32 v[24:25], v[158:159], v[46:47]
	v_pk_fma_f32 v[28:29], v[158:159], v[48:49], v[28:29]
	v_pk_fma_f32 v[158:159], v[184:185], v[58:59], v[186:187]
	v_pk_mul_f32 v[184:185], v[134:135], v[198:199]
	v_pk_fma_f32 v[186:187], v[134:135], v[200:201], v[140:141]
	v_lshlrev_b32_e32 v134, 16, v132
	v_and_b32_e32 v135, 0xffff0000, v132
	v_mul_f32_e32 v10, 0x3d372713, v134
	v_lshlrev_b32_e32 v132, 16, v133
	v_mul_f32_e32 v10, v10, v134
	v_mov_b32_e32 v14, v134
	v_mul_f32_e32 v2, 0x3d372713, v132
	v_fmac_f32_e32 v14, v10, v14
	v_mul_f32_e32 v2, v2, v132
	v_mov_b32_e32 v6, v132
	v_mul_f32_e32 v10, 0x3f4c422a, v14
	v_fmac_f32_e32 v6, v2, v6
	v_add_f32_e32 v10, v10, v10
	v_mul_f32_e32 v2, 0x3f4c422a, v6
	v_mul_f32_e32 v10, 0x3fb8aa3b, v10
	v_add_f32_e32 v2, v2, v2
	v_exp_f32_e32 v10, v10
	v_mul_f32_e32 v2, 0x3fb8aa3b, v2
	v_exp_f32_e32 v2, v2
	v_and_b32_e32 v133, 0xffff0000, v133
	v_add_f32_e32 v10, 1.0, v10
	v_rcp_f32_e32 v140, v10
	v_mul_f32_e32 v10, 0x3d372713, v135
	v_add_f32_e32 v2, 1.0, v2
	v_mul_f32_e32 v10, v10, v135
	v_mov_b32_e32 v14, v135
	v_rcp_f32_e32 v152, v2
	v_mul_f32_e32 v2, 0x3d372713, v133
	v_fmac_f32_e32 v14, v10, v14
	v_mul_f32_e32 v2, v2, v133
	v_mov_b32_e32 v6, v133
	v_mul_f32_e32 v10, 0x3f4c422a, v14
	v_fmac_f32_e32 v6, v2, v6
	v_add_f32_e32 v10, v10, v10
	v_mul_f32_e32 v2, 0x3f4c422a, v6
	v_mul_f32_e32 v10, 0x3fb8aa3b, v10
	v_add_f32_e32 v2, v2, v2
	v_exp_f32_e32 v10, v10
	v_mul_f32_e32 v2, 0x3fb8aa3b, v2
	v_exp_f32_e32 v2, v2
	v_pk_mul_f32 v[134:135], v[134:135], 0.5 op_sel_hi:[1,0]
	v_add_f32_e32 v10, 1.0, v10
	v_rcp_f32_e32 v141, v10
	v_add_f32_e32 v2, 1.0, v2
	v_lshlrev_b32_e32 v10, 16, v128
	v_rcp_f32_e32 v153, v2
	v_mul_f32_e32 v2, 0x3d372713, v10
	v_mul_f32_e32 v2, v2, v10
	v_mov_b32_e32 v6, v10
	v_fmac_f32_e32 v6, v2, v6
	v_mul_f32_e32 v2, 0x3f4c422a, v6
	v_add_f32_e32 v2, v2, v2
	v_mul_f32_e32 v2, 0x3fb8aa3b, v2
	v_exp_f32_e32 v2, v2
	v_pk_fma_f32 v[140:141], v[140:141], 2.0, 1.0 op_sel_hi:[1,0,0] neg_lo:[1,0,0] neg_hi:[1,0,0]
	v_and_b32_e32 v14, 0xffff0000, v11
	v_pk_add_f32 v[140:141], v[140:141], 1.0 op_sel_hi:[1,0]
	v_and_b32_e32 v11, 0xffff0000, v128
	v_add_f32_e32 v2, 1.0, v2
	v_pk_fma_f32 v[20:21], v[208:209], v[40:41], v[210:211]
	v_pk_mul_f32 v[208:209], v[134:135], v[140:141]
	v_pk_mul_f32 v[140:141], v[154:155], v[24:25]
	v_pk_fma_f32 v[146:147], v[154:155], v[28:29], v[146:147]
	v_pk_fma_f32 v[154:155], v[164:165], v[58:59], v[166:167]
	v_pk_fma_f32 v[166:167], v[130:131], v[186:187], v[14:15]
	v_rcp_f32_e32 v14, v2
	v_mul_f32_e32 v2, 0x3d372713, v11
	v_mul_f32_e32 v2, v2, v11
	v_mov_b32_e32 v6, v11
	v_fmac_f32_e32 v6, v2, v6
	v_mul_f32_e32 v2, 0x3f4c422a, v6
	v_add_f32_e32 v2, v2, v2
	v_mul_f32_e32 v2, 0x3fb8aa3b, v2
	v_exp_f32_e32 v2, v2
	v_pk_mul_f32 v[10:11], v[10:11], 0.5 op_sel_hi:[1,0]
	v_pk_fma_f32 v[134:135], v[194:195], v[40:41], v[196:197]
	v_pk_mul_f32 v[164:165], v[130:131], v[184:185]
	v_add_f32_e32 v2, 1.0, v2
	v_rcp_f32_e32 v15, v2
	v_lshlrev_b32_e32 v2, 16, v129
	v_add_f32_e32 v136, v136, v136
	v_add_f32_e32 v137, v137, v137
	v_pk_fma_f32 v[14:15], v[14:15], 2.0, 1.0 op_sel_hi:[1,0,0] neg_lo:[1,0,0] neg_hi:[1,0,0]
	v_mul_f32_e32 v136, 0x3fb8aa3b, v136
	v_pk_add_f32 v[14:15], v[14:15], 1.0 op_sel_hi:[1,0]
	v_mul_f32_e32 v137, 0x3fb8aa3b, v137
	v_pk_mul_f32 v[194:195], v[10:11], v[14:15]
	v_and_b32_e32 v15, 0xffff0000, v7
	v_and_b32_e32 v14, 0xffff0000, v3
	v_pk_fma_f32 v[130:131], v[144:145], v[146:147], v[14:15]
	v_mul_f32_e32 v14, 0x3d372713, v2
	v_mul_f32_e32 v14, v14, v2
	v_mov_b32_e32 v15, v2
	v_and_b32_e32 v3, 0xffff0000, v129
	v_fmac_f32_e32 v15, v14, v15
	v_mul_f32_e32 v14, 0x3f4c422a, v15
	v_mul_f32_e32 v15, 0x3d372713, v3
	v_mul_f32_e32 v15, v15, v3
	v_mov_b32_e32 v128, v3
	v_fmac_f32_e32 v128, v15, v128
	v_mul_f32_e32 v15, 0x3f4c422a, v128
	v_add_f32_e32 v14, v14, v14
	v_add_f32_e32 v15, v15, v15
	v_mul_f32_e32 v14, 0x3fb8aa3b, v14
	v_mul_f32_e32 v15, 0x3fb8aa3b, v15
	v_exp_f32_e32 v14, v14
	v_exp_f32_e32 v15, v15
	v_pk_mul_f32 v[2:3], v[2:3], 0.5 op_sel_hi:[1,0]
	v_pk_mul_f32 v[10:11], v[144:145], v[140:141]
	v_add_f32_e32 v14, 1.0, v14
	v_add_f32_e32 v15, 1.0, v15
	v_rcp_f32_e32 v14, v14
	v_rcp_f32_e32 v15, v15
	v_and_b32_e32 v144, 0xffff0000, v12
	v_and_b32_e32 v145, 0xffff0000, v16
	v_pk_fma_f32 v[6:7], v[170:171], v[40:41], v[172:173]
	v_pk_fma_f32 v[14:15], v[14:15], 2.0, 1.0 op_sel_hi:[1,0,0] neg_lo:[1,0,0] neg_hi:[1,0,0]
	v_pk_mul_f32 v[170:171], v[122:123], v[164:165]
	v_pk_add_f32 v[14:15], v[14:15], 1.0 op_sel_hi:[1,0]
	v_pk_fma_f32 v[144:145], v[122:123], v[166:167], v[144:145]
	v_pk_mul_f32 v[128:129], v[2:3], v[14:15]
; __device__ __forceinline__ void scan_final(const Args& a, int gw, int ngw, int lane, int layer) {
;     ...
;                     for (int sft = 1; sft < 16; sft <<= 1) {
;                         const float Pp = d == 0 ? __shfl_up(Pi, sft, 16) : __shfl_down(Pi, sft, 16), Hp = d == 0 ? __shfl_up(Hi, sft, 16) : __shfl_down(Hi, sft, 16);
;                         const bool has = d == 0 ? (j >= sft) : (j + sft <= 15);
;                         if (has) { Hi = Pi * Hp + Hi; Pi = Pi * Pp; }
;                     }
;                     float Pe = d == 0 ? __shfl_up(Pi, 1, 16) : __shfl_down(Pi, 1, 16), He = d == 0 ? __shfl_up(Hi, 1, 16) : __shfl_down(Hi, 1, 16);
;                     if (d == 0 ? (j == 0) : (j == 15)) { Pe = 1.f; He = 0.f; }
;                     const float c0 = __shfl(cv, eh * 4 + e + 8 * d, 16);
	v_pk_fma_f32 v[2:3], v[62:63], v[58:59], v[60:61]
	v_lshlrev_b32_e32 v60, 16, v120
	v_mul_f32_e32 v12, 0x3d372713, v60
	v_mul_f32_e32 v12, v12, v60
	v_mov_b32_e32 v16, v60
	v_fmac_f32_e32 v16, v12, v16
	v_mul_f32_e32 v12, 0x3f4c422a, v16
	v_add_f32_e32 v12, v12, v12
	v_mul_f32_e32 v12, 0x3fb8aa3b, v12
	v_exp_f32_e32 v12, v12
	v_and_b32_e32 v61, 0xffff0000, v120
	v_mov_b32_e32 v16, v61
	v_pk_mul_f32 v[122:123], v[138:139], v[10:11]
	v_add_f32_e32 v12, 1.0, v12
	v_rcp_f32_e32 v62, v12
	v_mul_f32_e32 v12, 0x3d372713, v61
	v_mul_f32_e32 v12, v12, v61
	v_fmac_f32_e32 v16, v12, v16
	v_mul_f32_e32 v12, 0x3f4c422a, v16
	v_add_f32_e32 v12, v12, v12
	v_mul_f32_e32 v12, 0x3fb8aa3b, v12
	v_exp_f32_e32 v12, v12
	v_pk_mul_f32 v[60:61], v[60:61], 0.5 op_sel_hi:[1,0]
	v_and_b32_e32 v16, 0xffff0000, v13
	v_pk_fma_f32 v[16:17], v[116:117], v[144:145], v[16:17]
	v_add_f32_e32 v12, 1.0, v12
	v_rcp_f32_e32 v63, v12
	v_pk_fma_f32 v[12:13], v[126:127], v[58:59], v[150:151]
	v_pk_mul_f32 v[58:59], v[116:117], v[170:171]
	v_exp_f32_e32 v136, v136
	v_pk_fma_f32 v[62:63], v[62:63], 2.0, 1.0 op_sel_hi:[1,0,0] neg_lo:[1,0,0] neg_hi:[1,0,0]
	v_exp_f32_e32 v137, v137
	v_pk_add_f32 v[62:63], v[62:63], 1.0 op_sel_hi:[1,0]
	v_add_f32_e32 v43, 1.0, v43
	v_pk_mul_f32 v[172:173], v[60:61], v[62:63]
	v_and_b32_e32 v63, 0xffff0000, v8
	v_and_b32_e32 v62, 0xffff0000, v4
	v_pk_fma_f32 v[138:139], v[138:139], v[130:131], v[62:63]
	v_lshlrev_b32_e32 v62, 16, v121
	v_mul_f32_e32 v4, 0x3d372713, v62
	v_mul_f32_e32 v4, v4, v62
	v_mov_b32_e32 v8, v62
	v_fmac_f32_e32 v8, v4, v8
	v_mul_f32_e32 v4, 0x3f4c422a, v8
	v_add_f32_e32 v4, v4, v4
	v_mul_f32_e32 v4, 0x3fb8aa3b, v4
	v_exp_f32_e32 v4, v4
	v_and_b32_e32 v63, 0xffff0000, v121
	v_mov_b32_e32 v8, v63
	v_pk_fma_f32 v[60:61], v[162:163], v[40:41], v[160:161]
	v_add_f32_e32 v4, 1.0, v4
	v_rcp_f32_e32 v120, v4
	v_mul_f32_e32 v4, 0x3d372713, v63
	v_mul_f32_e32 v4, v4, v63
	v_fmac_f32_e32 v8, v4, v8
	v_mul_f32_e32 v4, 0x3f4c422a, v8
	v_add_f32_e32 v4, v4, v4
	v_mul_f32_e32 v4, 0x3fb8aa3b, v4
	v_exp_f32_e32 v4, v4
	s_nop 1
	v_mov_b32_dpp v8, v16 row_shr:1 row_mask:0xf bank_mask:0xf bound_ctrl:1
	v_pk_mul_f32 v[62:63], v[62:63], 0.5 op_sel_hi:[1,0]
	v_rcp_f32_e32 v42, v42
	v_add_f32_e32 v4, 1.0, v4
	v_rcp_f32_e32 v121, v4
	s_nop 1
	v_mov_b32_dpp v4, v58 row_shr:1 row_mask:0xf bank_mask:0xf bound_ctrl:1
	v_fma_f32 v8, v58, v8, v16
	v_cndmask_b32_e64 v8, v8, v16, s[38:39]
	s_nop 1
	v_mov_b32_dpp v117, v8 row_shr:2 row_mask:0xf bank_mask:0xf bound_ctrl:1
	v_pk_fma_f32 v[120:121], v[120:121], 2.0, 1.0 op_sel_hi:[1,0,0] neg_lo:[1,0,0] neg_hi:[1,0,0]
	v_mul_f32_e32 v4, v58, v4
	v_cndmask_b32_e64 v4, v4, v58, s[38:39]
	s_nop 1
	v_mov_b32_dpp v116, v4 row_shr:2 row_mask:0xf bank_mask:0xf bound_ctrl:1
	v_fma_f32 v117, v4, v117, v8
	v_cndmask_b32_e64 v8, v8, v117, s[40:41]
	s_nop 1
	v_mov_b32_dpp v117, v8 row_shr:4 row_mask:0xf bank_mask:0xf bound_ctrl:1
	v_pk_add_f32 v[120:121], v[120:121], 1.0 op_sel_hi:[1,0]
	v_mul_f32_e32 v116, v4, v116
	v_cndmask_b32_e64 v4, v4, v116, s[40:41]
	s_nop 1
	v_mov_b32_dpp v116, v4 row_shr:4 row_mask:0xf bank_mask:0xf bound_ctrl:1
	v_fma_f32 v117, v4, v117, v8
	v_cndmask_b32_e64 v8, v8, v117, s[42:43]
	s_nop 1
	v_mov_b32_dpp v117, v8 row_shr:8 row_mask:0xf bank_mask:0xf bound_ctrl:1
	v_pk_mul_f32 v[120:121], v[62:63], v[120:121]
	v_mul_f32_e32 v116, v4, v116
	v_cndmask_b32_e64 v4, v4, v116, s[42:43]
	s_nop 1
	v_mov_b32_dpp v116, v4 row_shr:8 row_mask:0xf bank_mask:0xf bound_ctrl:1
	v_fma_f32 v117, v4, v117, v8
	v_cndmask_b32_e64 v8, v8, v117, s[44:45]
	s_nop 1
	v_mov_b32_dpp v117, v17 row_shr:1 row_mask:0xf bank_mask:0xf bound_ctrl:1
	v_mov_b32_dpp v8, v8 row_shr:1 row_mask:0xf bank_mask:0xf
	v_mul_f32_e32 v116, v4, v116
	v_cndmask_b32_e64 v4, v4, v116, s[44:45]
	s_nop 1
	v_mov_b32_dpp v116, v59 row_shr:1 row_mask:0xf bank_mask:0xf bound_ctrl:1
	v_fma_f32 v117, v59, v117, v17
	v_cndmask_b32_e64 v117, v117, v17, s[38:39]
	s_nop 1
	v_mov_b32_dpp v127, v117 row_shr:2 row_mask:0xf bank_mask:0xf bound_ctrl:1
	v_mov_b32_dpp v4, v4 row_shr:1 row_mask:0xf bank_mask:0xf
	v_mul_f32_e32 v116, v59, v116
	v_cndmask_b32_e64 v116, v116, v59, s[38:39]
	s_nop 1
	v_mov_b32_dpp v126, v116 row_shr:2 row_mask:0xf bank_mask:0xf bound_ctrl:1
	v_fma_f32 v127, v116, v127, v117
	v_cndmask_b32_e64 v117, v117, v127, s[40:41]
	s_nop 1
	v_mov_b32_dpp v127, v117 row_shr:4 row_mask:0xf bank_mask:0xf bound_ctrl:1
	v_lshl_add_u64 v[62:63], v[106:107], 0, v[100:101]
	v_mul_f32_e32 v126, v116, v126
	v_cndmask_b32_e64 v116, v116, v126, s[40:41]
	s_nop 1
	v_mov_b32_dpp v126, v116 row_shr:4 row_mask:0xf bank_mask:0xf bound_ctrl:1
	v_fma_f32 v127, v116, v127, v117
	v_cndmask_b32_e64 v117, v117, v127, s[42:43]
	s_nop 1
	v_mov_b32_dpp v127, v117 row_shr:8 row_mask:0xf bank_mask:0xf bound_ctrl:1
	v_rcp_f32_e32 v43, v43
	v_mul_f32_e32 v126, v116, v126
	v_cndmask_b32_e64 v116, v116, v126, s[42:43]
	s_nop 1
	v_mov_b32_dpp v126, v116 row_shr:8 row_mask:0xf bank_mask:0xf bound_ctrl:1
	v_fma_f32 v127, v116, v127, v117
	v_cndmask_b32_e64 v117, v117, v127, s[44:45]
	v_add_f32_e32 v136, 1.0, v136
	v_add_f32_e32 v137, 1.0, v137
	v_mul_f32_e32 v126, v116, v126
	v_cndmask_b32_e64 v116, v116, v126, s[44:45]
	s_nop 1
	v_mov_b32_dpp v116, v116 row_shr:1 row_mask:0xf bank_mask:0xf
	v_mov_b32_dpp v126, v117 row_shr:1 row_mask:0xf bank_mask:0xf bound_ctrl:1
	v_rcp_f32_e32 v136, v136
	v_rcp_f32_e32 v137, v137
	v_pk_fma_f32 v[42:43], v[42:43], 2.0, 1.0 op_sel_hi:[1,0,0] neg_lo:[1,0,0] neg_hi:[1,0,0]
	v_cndmask_b32_e64 v117, v116, 1.0, s[38:39]
	v_cndmask_b32_e64 v116, v4, 1.0, s[38:39]
	v_cndmask_b32_e64 v127, v126, 0, s[38:39]
	v_cndmask_b32_e64 v126, v8, 0, s[38:39]
; __device__ __forceinline__ float bflo(unsigned w) { return __uint_as_float(w << 16); }
; __device__ __forceinline__ float bfhi(unsigned w) { return __uint_as_float(w & 0xffff0000u); }
; __device__ __forceinline__ float gelu_tanh(float x) { const float y = 0.7978845608028654f * (x + 0.044715f * x * x * x); const float e = __expf(2.0f * y); const float th = 1.0f - 2.0f * __builtin_amdgcn_rcpf(e + 1.0f); return 0.5f * x * (1.0f + th); }
; __device__ __forceinline__ void scan_final(const Args& a, int gw, int ngw, int lane, int layer) {
;     ...
;                     for (int sft = 1; sft < 16; sft <<= 1) {
;                         const float Pp = d == 0 ? __shfl_up(Pi, sft, 16) : __shfl_down(Pi, sft, 16), Hp = d == 0 ? __shfl_up(Hi, sft, 16) : __shfl_down(Hi, sft, 16);
;                         const bool has = d == 0 ? (j >= sft) : (j + sft <= 15);
;                         if (has) { Hi = Pi * Hp + Hi; Pi = Pi * Pp; }
;                     }
;                     float Pe = d == 0 ? __shfl_up(Pi, 1, 16) : __shfl_down(Pi, 1, 16), He = d == 0 ? __shfl_up(Hi, 1, 16) : __shfl_down(Hi, 1, 16);
;                     if (d == 0 ? (j == 0) : (j == 15)) { Pe = 1.f; He = 0.f; }
;                     const float c0 = __shfl(cv, eh * 4 + e + 8 * d, 16);
;                     const float sj = Pe * c0 + He;
; #pragma unroll
;                     for (int k = 0; k < 8; ++k) { const float hv = hl[k] + pl[k] * sj; if (d == 0) acc[k][e] = hv; else acc[k][e] += hv; }
;                 }
;             }
; #pragma unroll
;             for (int k = 0; k < 8; ++k) { const float r0 = bflo(rgw[k].x), r1 = bfhi(rgw[k].x), r2 = bflo(rgw[k].y), r3 = bfhi(rgw[k].y);
;                 u32x2 w; w.x = pk2(acc[k][0] * gelu_tanh(r0), acc[k][1] * gelu_tanh(r1)); w.y = pk2(acc[k][2] * gelu_tanh(r2), acc[k][3] * gelu_tanh(r3));
	v_pk_fma_f32 v[116:117], v[116:117], v[124:125], v[126:127]
	v_pk_mul_f32 v[30:31], v[30:31], 0.5 op_sel_hi:[1,0]
	v_pk_fma_f32 v[110:111], v[110:111], v[116:117], v[148:149]
	v_pk_fma_f32 v[124:125], v[182:183], v[116:117], v[190:191]
	v_pk_fma_f32 v[144:145], v[170:171], v[116:117], v[144:145]
	v_pk_fma_f32 v[16:17], v[58:59], v[116:117], v[16:17]
	v_pk_add_f32 v[54:55], v[110:111], v[54:55]
	v_pk_fma_f32 v[126:127], v[202:203], v[116:117], v[204:205]
	v_pk_add_f32 v[58:59], v[124:125], v[156:157]
	v_pk_add_f32 v[2:3], v[144:145], v[2:3]
	v_pk_add_f32 v[144:145], v[16:17], v[12:13]
	v_pk_mul_f32 v[12:13], v[56:57], v[54:55]
	v_pk_fma_f32 v[148:149], v[198:199], v[116:117], v[200:201]
	v_pk_fma_f32 v[150:151], v[184:185], v[116:117], v[186:187]
	v_pk_fma_f32 v[160:161], v[164:165], v[116:117], v[166:167]
	v_pk_add_f32 v[116:117], v[126:127], v[188:189]
	v_cvt_pk_bf16_f32 v110, v12, v13
	v_pk_mul_f32 v[12:13], v[192:193], v[58:59]
	v_pk_add_f32 v[124:125], v[148:149], v[168:169]
	v_cvt_pk_bf16_f32 v58, v12, v13
	v_pk_mul_f32 v[12:13], v[206:207], v[116:117]
	v_pk_add_f32 v[126:127], v[150:151], v[158:159]
	v_cvt_pk_bf16_f32 v56, v12, v13
	v_pk_mul_f32 v[12:13], v[212:213], v[124:125]
	v_pk_mul_f32 v[2:3], v[172:173], v[2:3]
	v_pk_add_f32 v[148:149], v[160:161], v[154:155]
	v_cvt_pk_bf16_f32 v54, v12, v13
	v_pk_mul_f32 v[12:13], v[208:209], v[126:127]
	v_cvt_pk_bf16_f32 v8, v2, v3
	v_lshlrev_b32_e32 v2, 16, v104
	v_cvt_pk_bf16_f32 v16, v12, v13
	v_pk_mul_f32 v[12:13], v[194:195], v[148:149]
	v_mul_f32_e32 v4, 0x3d372713, v2
	v_cvt_pk_bf16_f32 v12, v12, v13
	v_mul_f32_e32 v4, v4, v2
	v_mov_b32_e32 v13, v2
	v_fmac_f32_e32 v13, v4, v13
	v_mul_f32_e32 v4, 0x3f4c422a, v13
	v_add_f32_e32 v4, v4, v4
	v_mul_f32_e32 v4, 0x3fb8aa3b, v4
	v_exp_f32_e32 v4, v4
	v_and_b32_e32 v3, 0xffff0000, v104
	v_mov_b32_e32 v13, v3
	v_pk_add_f32 v[42:43], v[42:43], 1.0 op_sel_hi:[1,0]
	v_add_f32_e32 v4, 1.0, v4
	v_rcp_f32_e32 v116, v4
	v_mul_f32_e32 v4, 0x3d372713, v3
	v_mul_f32_e32 v4, v4, v3
	v_fmac_f32_e32 v13, v4, v13
	v_mul_f32_e32 v4, 0x3f4c422a, v13
	v_add_f32_e32 v4, v4, v4
	v_mul_f32_e32 v4, 0x3fb8aa3b, v4
	v_exp_f32_e32 v4, v4
	v_pk_mul_f32 v[2:3], v[2:3], 0.5 op_sel_hi:[1,0]
	v_pk_fma_f32 v[142:143], v[142:143], 2.0, 1.0 op_sel_hi:[1,0,0] neg_lo:[1,0,0] neg_hi:[1,0,0]
	v_pk_mul_f32 v[42:43], v[30:31], v[42:43]
	v_add_f32_e32 v4, 1.0, v4
	v_rcp_f32_e32 v117, v4
	v_pk_mul_f32 v[64:65], v[64:65], 0.5 op_sel_hi:[1,0]
	v_pk_add_f32 v[142:143], v[142:143], 1.0 op_sel_hi:[1,0]
	v_pk_fma_f32 v[136:137], v[136:137], 2.0, 1.0 op_sel_hi:[1,0,0] neg_lo:[1,0,0] neg_hi:[1,0,0]
	v_pk_fma_f32 v[116:117], v[116:117], 2.0, 1.0 op_sel_hi:[1,0,0] neg_lo:[1,0,0] neg_hi:[1,0,0]
	v_pk_mul_f32 v[142:143], v[64:65], v[142:143]
	v_pk_add_f32 v[116:117], v[116:117], 1.0 op_sel_hi:[1,0]
	v_pk_mul_f32 v[32:33], v[32:33], 0.5 op_sel_hi:[1,0]
	v_pk_mul_f32 v[2:3], v[2:3], v[116:117]
	v_and_b32_e32 v117, 0xffff0000, v9
	v_and_b32_e32 v116, 0xffff0000, v5
	v_pk_mul_f32 v[2:3], v[2:3], v[144:145]
	v_pk_fma_f32 v[4:5], v[118:119], v[40:41], v[52:53]
	v_pk_mul_f32 v[40:41], v[112:113], v[122:123]
	v_pk_fma_f32 v[52:53], v[112:113], v[138:139], v[116:117]
	v_cvt_pk_bf16_f32 v2, v2, v3
	s_nop 1
	v_mov_b32_dpp v3, v40 row_shr:1 row_mask:0xf bank_mask:0xf bound_ctrl:1
	v_mov_b32_dpp v9, v52 row_shr:1 row_mask:0xf bank_mask:0xf bound_ctrl:1
	v_pk_add_f32 v[136:137], v[136:137], 1.0 op_sel_hi:[1,0]
	v_pk_fma_f32 v[152:153], v[152:153], 2.0, 1.0 op_sel_hi:[1,0,0] neg_lo:[1,0,0] neg_hi:[1,0,0]
	v_pk_mul_f32 v[136:137], v[32:33], v[136:137]
	v_mul_f32_e32 v3, v40, v3
	v_fma_f32 v9, v40, v9, v52
	v_cndmask_b32_e64 v9, v9, v52, s[38:39]
	v_cndmask_b32_e64 v3, v3, v40, s[38:39]
	s_nop 1
	v_mov_b32_dpp v13, v3 row_shr:2 row_mask:0xf bank_mask:0xf bound_ctrl:1
	v_mov_b32_dpp v17, v9 row_shr:2 row_mask:0xf bank_mask:0xf bound_ctrl:1
	v_pk_mul_f32 v[132:133], v[132:133], 0.5 op_sel_hi:[1,0]
	v_pk_add_f32 v[152:153], v[152:153], 1.0 op_sel_hi:[1,0]
	v_lshl_add_u64 v[36:37], v[106:107], 0, v[88:89]
	v_mul_f32_e32 v13, v3, v13
	v_fma_f32 v17, v3, v17, v9
	v_cndmask_b32_e64 v9, v9, v17, s[40:41]
	v_cndmask_b32_e64 v3, v3, v13, s[40:41]
	s_nop 1
	v_mov_b32_dpp v13, v3 row_shr:4 row_mask:0xf bank_mask:0xf bound_ctrl:1
	v_mov_b32_dpp v17, v9 row_shr:4 row_mask:0xf bank_mask:0xf bound_ctrl:1
	v_pk_mul_f32 v[152:153], v[132:133], v[152:153]
	v_lshl_add_u64 v[30:31], v[106:107], 0, v[90:91]
	v_lshl_add_u64 v[64:65], v[106:107], 0, v[92:93]
	v_mul_f32_e32 v13, v3, v13
	v_fma_f32 v17, v3, v17, v9
	v_cndmask_b32_e64 v9, v9, v17, s[42:43]
	v_cndmask_b32_e64 v3, v3, v13, s[42:43]
	s_nop 1
	v_mov_b32_dpp v13, v3 row_shr:8 row_mask:0xf bank_mask:0xf bound_ctrl:1
	v_mov_b32_dpp v17, v9 row_shr:8 row_mask:0xf bank_mask:0xf bound_ctrl:1
; __device__ __forceinline__ float bflo(unsigned w) { return __uint_as_float(w << 16); }
; __device__ __forceinline__ float bfhi(unsigned w) { return __uint_as_float(w & 0xffff0000u); }
; __device__ __forceinline__ float gelu_tanh(float x) { const float y = 0.7978845608028654f * (x + 0.044715f * x * x * x); const float e = __expf(2.0f * y); const float th = 1.0f - 2.0f * __builtin_amdgcn_rcpf(e + 1.0f); return 0.5f * x * (1.0f + th); }
; __device__ __forceinline__ void scan_final(const Args& a, int gw, int ngw, int lane, int layer) {
;     ...
;                     for (int sft = 1; sft < 16; sft <<= 1) {
;                         const float Pp = d == 0 ? __shfl_up(Pi, sft, 16) : __shfl_down(Pi, sft, 16), Hp = d == 0 ? __shfl_up(Hi, sft, 16) : __shfl_down(Hi, sft, 16);
;                         const bool has = d == 0 ? (j >= sft) : (j + sft <= 15);
;                         if (has) { Hi = Pi * Hp + Hi; Pi = Pi * Pp; }
;                     }
;                     float Pe = d == 0 ? __shfl_up(Pi, 1, 16) : __shfl_down(Pi, 1, 16), He = d == 0 ? __shfl_up(Hi, 1, 16) : __shfl_down(Hi, 1, 16);
;                     if (d == 0 ? (j == 0) : (j == 15)) { Pe = 1.f; He = 0.f; }
;                     const float c0 = __shfl(cv, eh * 4 + e + 8 * d, 16);
;                     const float sj = Pe * c0 + He;
; #pragma unroll
;                     for (int k = 0; k < 8; ++k) { const float hv = hl[k] + pl[k] * sj; if (d == 0) acc[k][e] = hv; else acc[k][e] += hv; }
;                 }
;             }
; #pragma unroll
;             for (int k = 0; k < 8; ++k) { const float r0 = bflo(rgw[k].x), r1 = bfhi(rgw[k].x), r2 = bflo(rgw[k].y), r3 = bfhi(rgw[k].y);
;                 u32x2 w; w.x = pk2(acc[k][0] * gelu_tanh(r0), acc[k][1] * gelu_tanh(r1)); w.y = pk2(acc[k][2] * gelu_tanh(r2), acc[k][3] * gelu_tanh(r3));
;                 *(u32x2*)(YS + (size_t)(row0 + k) * 3072 + c4) = w; }
	v_lshl_add_u64 v[32:33], v[106:107], 0, v[94:95]
	v_lshl_add_u64 v[132:133], v[106:107], 0, v[96:97]
	v_lshl_add_u64 v[14:15], v[106:107], 0, v[98:99]
	v_mul_f32_e32 v13, v3, v13
	v_fma_f32 v17, v3, v17, v9
	v_cndmask_b32_e64 v9, v9, v17, s[44:45]
	v_cndmask_b32_e64 v3, v3, v13, s[44:45]
	s_nop 1
	v_mov_b32_dpp v13, v41 row_shr:1 row_mask:0xf bank_mask:0xf bound_ctrl:1
	v_mov_b32_dpp v17, v53 row_shr:1 row_mask:0xf bank_mask:0xf bound_ctrl:1
	v_mov_b32_dpp v3, v3 row_shr:1 row_mask:0xf bank_mask:0xf
	v_mov_b32_dpp v9, v9 row_shr:1 row_mask:0xf bank_mask:0xf
	v_mul_f32_e32 v13, v41, v13
	v_fma_f32 v17, v41, v17, v53
	v_cndmask_b32_e64 v17, v17, v53, s[38:39]
	v_cndmask_b32_e64 v13, v13, v41, s[38:39]
	s_nop 1
	v_mov_b32_dpp v55, v13 row_shr:2 row_mask:0xf bank_mask:0xf bound_ctrl:1
	v_mov_b32_dpp v57, v17 row_shr:2 row_mask:0xf bank_mask:0xf bound_ctrl:1
	v_cndmask_b32_e64 v112, v3, 1.0, s[38:39]
	v_cndmask_b32_e64 v116, v9, 0, s[38:39]
	v_mul_f32_e32 v55, v13, v55
	v_fma_f32 v57, v13, v57, v17
	v_cndmask_b32_e64 v17, v17, v57, s[40:41]
	v_cndmask_b32_e64 v13, v13, v55, s[40:41]
	s_nop 1
	v_mov_b32_dpp v55, v13 row_shr:4 row_mask:0xf bank_mask:0xf bound_ctrl:1
	v_mov_b32_dpp v57, v17 row_shr:4 row_mask:0xf bank_mask:0xf bound_ctrl:1
	v_mul_f32_e32 v55, v13, v55
	v_fma_f32 v57, v13, v57, v17
	v_cndmask_b32_e64 v17, v17, v57, s[42:43]
	v_cndmask_b32_e64 v13, v13, v55, s[42:43]
	s_nop 1
	v_mov_b32_dpp v55, v13 row_shr:8 row_mask:0xf bank_mask:0xf bound_ctrl:1
	v_mov_b32_dpp v57, v17 row_shr:8 row_mask:0xf bank_mask:0xf bound_ctrl:1
	v_mul_f32_e32 v55, v13, v55
	v_fma_f32 v57, v13, v57, v17
	v_cndmask_b32_e64 v17, v17, v57, s[44:45]
	v_cndmask_b32_e64 v13, v13, v55, s[44:45]
	s_nop 1
	v_mov_b32_dpp v13, v13 row_shr:1 row_mask:0xf bank_mask:0xf
	v_mov_b32_dpp v17, v17 row_shr:1 row_mask:0xf bank_mask:0xf
	v_cndmask_b32_e64 v113, v13, 1.0, s[38:39]
	v_cndmask_b32_e64 v117, v17, 0, s[38:39]
	v_pk_fma_f32 v[112:113], v[112:113], v[114:115], v[116:117]
	s_nop 0
	v_pk_fma_f32 v[10:11], v[10:11], v[112:113], v[130:131]
	v_pk_fma_f32 v[22:23], v[22:23], v[112:113], v[26:27]
	v_pk_fma_f32 v[26:27], v[46:47], v[112:113], v[48:49]
	v_pk_fma_f32 v[46:47], v[122:123], v[112:113], v[138:139]
	v_pk_add_f32 v[6:7], v[10:11], v[6:7]
	v_pk_add_f32 v[10:11], v[46:47], v[60:61]
	v_pk_mul_f32 v[6:7], v[128:129], v[6:7]
	v_pk_add_f32 v[18:19], v[22:23], v[18:19]
	v_cvt_pk_bf16_f32 v13, v6, v7
	v_pk_mul_f32 v[6:7], v[120:121], v[10:11]
	v_pk_fma_f32 v[24:25], v[24:25], v[112:113], v[28:29]
	v_cvt_pk_bf16_f32 v9, v6, v7
	v_lshlrev_b32_e32 v6, 16, v105
	v_mul_f32_e32 v3, 0x3d372713, v6
	global_store_dwordx2 v[62:63], v[8:9], off
	v_mul_f32_e32 v3, v3, v6
	v_mov_b32_e32 v8, v6
	v_fmac_f32_e32 v8, v3, v8
	v_mul_f32_e32 v3, 0x3f4c422a, v8
	v_add_f32_e32 v3, v3, v3
	v_mul_f32_e32 v3, 0x3fb8aa3b, v3
	v_exp_f32_e32 v3, v3
	v_and_b32_e32 v7, 0xffff0000, v105
	v_mov_b32_e32 v9, v7
	v_pk_add_f32 v[22:23], v[26:27], v[44:45]
	v_add_f32_e32 v3, 1.0, v3
	v_rcp_f32_e32 v8, v3
	v_mul_f32_e32 v3, 0x3d372713, v7
	v_mul_f32_e32 v3, v3, v7
	v_fmac_f32_e32 v9, v3, v9
	v_mul_f32_e32 v3, 0x3f4c422a, v9
	v_add_f32_e32 v3, v3, v3
	v_mul_f32_e32 v3, 0x3fb8aa3b, v3
	v_exp_f32_e32 v3, v3
	v_pk_mul_f32 v[18:19], v[42:43], v[18:19]
	v_pk_fma_f32 v[50:51], v[108:109], v[112:113], v[50:51]
	v_pk_fma_f32 v[28:29], v[140:141], v[112:113], v[146:147]
	v_add_f32_e32 v3, 1.0, v3
	v_rcp_f32_e32 v9, v3
	v_pk_fma_f32 v[40:41], v[40:41], v[112:113], v[52:53]
	v_pk_add_f32 v[20:21], v[24:25], v[20:21]
	v_cvt_pk_bf16_f32 v59, v18, v19
	v_pk_fma_f32 v[8:9], v[8:9], 2.0, 1.0 op_sel_hi:[1,0,0] neg_lo:[1,0,0] neg_hi:[1,0,0]
	v_pk_mul_f32 v[18:19], v[142:143], v[22:23]
	v_pk_mul_f32 v[6:7], v[6:7], 0.5 op_sel_hi:[1,0]
	v_pk_add_f32 v[8:9], v[8:9], 1.0 op_sel_hi:[1,0]
	v_pk_add_f32 v[34:35], v[50:51], v[34:35]
	v_pk_add_f32 v[24:25], v[28:29], v[134:135]
	v_pk_add_f32 v[4:5], v[40:41], v[4:5]
	v_cvt_pk_bf16_f32 v57, v18, v19
	v_pk_mul_f32 v[18:19], v[136:137], v[20:21]
	v_pk_mul_f32 v[6:7], v[6:7], v[8:9]
	v_pk_mul_f32 v[26:27], v[38:39], v[34:35]
	v_cvt_pk_bf16_f32 v55, v18, v19
	v_pk_mul_f32 v[18:19], v[152:153], v[24:25]
	v_pk_mul_f32 v[4:5], v[6:7], v[4:5]
	v_cvt_pk_bf16_f32 v111, v26, v27
	v_cvt_pk_bf16_f32 v17, v18, v19
	v_cvt_pk_bf16_f32 v3, v4, v5
	v_lshl_add_u64 v[4:5], v[106:107], 0, v[102:103]
	global_store_dwordx2 v[36:37], v[110:111], off
	global_store_dwordx2 v[30:31], v[58:59], off
	global_store_dwordx2 v[64:65], v[56:57], off
	global_store_dwordx2 v[32:33], v[54:55], off
	global_store_dwordx2 v[132:133], v[16:17], off
	global_store_dwordx2 v[14:15], v[12:13], off
	global_store_dwordx2 v[4:5], v[2:3], off
	s_cbranch_scc0 .LBB0_1189
	s_add_i32 s66, s66, 1
	s_cmp_eq_u32 s66, s65
	s_cbranch_scc0 .LBB0_1188
